# GEMM main loops: one static s_setprio 1 for waves 0-3 before the loop, all per-MFMA-block priority flips removed (strategy: static priority raise for one wave half)
# speedup vs baseline: 1.0092x; 1.0024x over previous
; __device__ __forceinline__ int fresh_tid() { int t = (int)threadIdx.x; asm volatile("" : "+v"(t)); return t; }
; #define PG8_STAGE(bufoff, gbase, voff) do { _Pragma("unroll") for (int _i = 0; _i < 2; ++_i) \
;         __builtin_amdgcn_global_load_lds((const unsigned*)((const char*)(gbase) + (voff)[_i]), (PG8_LAS unsigned*)(lds + (bufoff) + ldsw + _i * 8192), 16, 0, 0); } while (0)
; template <class Epi, class Sched, bool ALIGN_EPI = false, bool SP2 = false>
; __device__ __forceinline__ void gemm_phase(PG8_LAS unsigned char* lds, const Gemm g, const Sched& S, const Epi& E) {
;     const int tid = fresh_tid(), wid = __builtin_amdgcn_readfirstlane(tid >> 6), lane = tid & 63, wr = wid >> 2, wc = wid & 3, fr = lane & 15, fq = lane >> 4;
;     const int K = g.K, nt = K / BK;
;     unsigned voffA[2], voffB[2];
; #pragma unroll
;     for (int i = 0; i < 2; ++i) { int R, C; stage_rc(tid * 16 + i * 8192, R, C); const int Rb = Epi::PERM ? ((R & ~31) + perm32(R & 31)) : R;
;         voffA[i] = (unsigned)(R * K + C) * 2u; voffB[i] = (unsigned)(Rb * K + C) * 2u; }
;     const size_t kstep = (size_t)(BK * 2);
;     const size_t hstep = (size_t)HALF * K * 2;
;     const size_t tstep = 2 * hstep;
;     const unsigned ldsw = (unsigned)wid * 1024u;
;     const int aoff = lds_byte(wr * 64 + fr, fq * 8), boff = lds_byte(wc * 32 + fr, fq * 8);
;     ...
;     const char* cA = (const char*)g.A + (size_t)cur.pm * tstep; const char* cB = (const char*)g.Bt + (size_t)cur.pn * tstep;
;     S.a_ready(cur);
;     if constexpr (SP2) {
;         PG8_STAGE(PG8_SB(0, 0), cB, voffB); PG8_STAGE(PG8_SB(0, 1), cB + hstep, voffB); PG8_STAGE(PG8_SA(0, 0), cA, voffA); PG8_STAGE(PG8_SA(0, 1), cA + hstep, voffA);
;         if (wr == 1) PG8_BAR;
;         PG8_WAIT_V(2); PG8_BAR;
;         PG8_STAGE(PG8_SB(1, 0), cB + kstep, voffB); PG8_STAGE(PG8_SA(1, 0), cA + kstep, voffA); PG8_STAGE(PG8_SB(1, 1), cB + hstep + kstep, voffB);
;         PG8_WAIT_V(6); PG8_BAR;
;     } else {
;         PG8_STAGE(PG8_SB(0, 0), cB, voffB); PG8_STAGE(PG8_SA(0, 0), cA, voffA); PG8_STAGE(PG8_SB(0, 1), cB + hstep, voffB); PG8_STAGE(PG8_SA(0, 1), cA + hstep, voffA);
;         if (wr == 1) PG8_BAR;
;         PG8_WAIT_V(4); PG8_BAR;
;         PG8_STAGE(PG8_SB(1, 0), cB + kstep, voffB); PG8_STAGE(PG8_SA(1, 0), cA + kstep, voffA); PG8_STAGE(PG8_SB(1, 1), cB + hstep + kstep, voffB);
;         PG8_WAIT_V(6); PG8_BAR;
.LBB0_203:
	s_mov_b64 s[8:9], s[80:81]
	s_mov_b64 s[12:13], s[80:81]
	s_mov_b64 s[4:5], s[80:81]
	v_mov_b32_e32 v8, v182
	s_cmpk_lt_i32 s33, 0xb00
	s_barrier
	s_cselect_b64 s[48:49], -1, 0
	s_cmpk_gt_i32 s33, 0xaff
	v_readfirstlane_b32 s10, v8
	s_cbranch_scc1 .LBB0_219
	v_lshlrev_b32_e32 v0, 4, v8
	v_add_u32_e32 v1, 0x2000, v0
	v_ashrrev_i32_e32 v2, 31, v1
	v_lshrrev_b32_e32 v2, 22, v2
	v_add_u32_e32 v2, v1, v2
	v_ashrrev_i32_e32 v9, 10, v2
	v_mul_i32_i24_e32 v2, 0x400, v9
	v_sub_u32_e32 v1, v1, v2
	v_lshrrev_b32_e32 v2, 4, v1
	v_bitop3_b32 v1, v2, v1, 32 bitop3:0x6c
	v_ashrrev_i32_e32 v2, 31, v1
	s_load_dwordx2 s[0:1], s[8:9], 0x110
	s_load_dwordx2 s[2:3], s[12:13], 0x110
	v_lshrrev_b32_e32 v2, 26, v2
	v_add_u32_e32 v2, v1, v2
	v_lshlrev_b32_e32 v3, 3, v9
	v_ashrrev_i32_e32 v10, 6, v2
	v_and_b32_e32 v3, -16, v3
	v_add_u32_e32 v3, v10, v3
	s_waitcnt lgkmcnt(0)
	s_add_u32 s36, s0, 0x3000000
	v_and_b32_e32 v4, 3, v10
	s_mov_b32 s0, 0x1fffe0
	v_lshrrev_b32_e32 v5, 2, v3
	v_lshlrev_b32_e32 v6, 1, v3
	v_and_b32_e32 v2, 0xc0, v2
	v_and_or_b32 v4, v3, s0, v4
	v_and_b32_e32 v5, 4, v5
	v_and_b32_e32 v6, 24, v6
	v_sub_u32_e32 v1, v1, v2
	v_mov_b32_e32 v2, 1
	v_or3_b32 v4, v4, v5, v6
	v_lshlrev_b32_e32 v5, 5, v9
	v_ashrrev_i16_sdwa v1, v2, sext(v1) dst_sel:DWORD dst_unused:UNUSED_PAD src0_sel:DWORD src1_sel:BYTE_0
	v_and_b32_e32 v5, 32, v5
	v_bfe_i32 v11, v1, 0, 16
	v_add_lshl_u32 v1, v5, v11, 1
	v_lshl_add_u32 v128, v4, 11, v1
	v_lshl_add_u32 v130, v3, 11, v1
	v_bfe_i32 v1, v8, 27, 1
	v_lshrrev_b32_e32 v1, 22, v1
	v_add_u32_e32 v1, v0, v1
	v_and_b32_e32 v1, 0xfffffc00, v1
	v_sub_u32_e32 v0, v0, v1
	v_lshrrev_b32_e32 v1, 4, v0
	v_bitop3_b32 v1, v1, v0, 32 bitop3:0x6c
	v_ashrrev_i32_e32 v0, 31, v0
	v_lshrrev_b32_e32 v0, 26, v0
	v_add_u32_e32 v0, v1, v0
	v_ashrrev_i32_e32 v12, 6, v0
	v_ashrrev_i32_e32 v0, 31, v8
	v_lshrrev_b32_e32 v0, 26, v0
	v_add_u32_e32 v0, v8, v0
	v_ashrrev_i32_e32 v13, 6, v0
	s_addc_u32 s37, s1, 0
	v_lshlrev_b32_e32 v0, 3, v13
	s_add_u32 s38, s2, 0x100000
	v_and_b32_e32 v0, -16, v0
	s_addc_u32 s39, s3, 0
	v_add_u32_e32 v0, v12, v0
	v_and_b32_e32 v3, 3, v12
	s_ashr_i32 s41, s33, 31
	v_and_or_b32 v3, v0, s0, v3
	s_lshr_b32 s0, s41, 29
	s_add_i32 s0, s33, s0
	s_ashr_i32 s14, s10, 6
	s_ashr_i32 s1, s0, 3
	s_and_b32 s0, s0, -8
	s_ashr_i32 s11, s10, 8
	s_lshl_b32 s40, s14, 10
	s_sub_i32 s0, s33, s0
	s_cmp_lt_i32 s0, 0
	s_movk_i32 s42, 0x161
	s_cselect_b32 s2, s42, 0x160
	s_mul_i32 s0, s0, s2
	s_add_i32 s0, s0, s1
	s_mul_hi_i32 s1, s0, 0x2e8ba2e9
	s_lshr_b32 s2, s1, 31
	s_ashr_i32 s1, s1, 5
	s_add_i32 s1, s1, s2
	s_lshl_b32 s2, s1, 3
	s_mulk_i32 s1, 0xb0
	s_sub_i32 s0, s0, s1
	s_sext_i32_i16 s1, s0
	s_bfe_u32 s1, s1, 0x3001c
	s_add_i32 s1, s0, s1
	s_sext_i32_i16 s3, s1
	s_and_b32 s1, s1, 0xfff8
	v_lshrrev_b32_e32 v4, 2, v0
	v_lshlrev_b32_e32 v5, 1, v0
	s_sub_i32 s0, s0, s1
	v_and_b32_e32 v4, 4, v4
	v_and_b32_e32 v5, 24, v5
	s_sext_i32_i16 s0, s0
	v_or3_b32 v3, v3, v4, v5
	v_mul_i32_i24_e32 v5, 64, v12
	s_lshr_b32 s16, s3, 3
	s_add_i32 s26, s2, s0
	v_sub_u32_e32 v1, v1, v5
	s_ashr_i32 s27, s26, 31
	s_bfe_i64 s[2:3], s[16:17], 0x100000
	v_lshlrev_b32_e32 v4, 5, v13
	v_ashrrev_i16_sdwa v1, v2, sext(v1) dst_sel:DWORD dst_unused:UNUSED_PAD src0_sel:DWORD src1_sel:BYTE_0
	s_lshl_b64 s[0:1], s[26:27], 19
	s_lshl_b64 s[2:3], s[2:3], 19
	v_and_b32_e32 v4, 32, v4
	v_bfe_i32 v14, v1, 0, 16
	s_add_u32 s30, s38, s2
	v_add_lshl_u32 v1, v4, v14, 1
	s_addc_u32 s31, s39, s3
	s_add_i32 s27, s40, 0
	v_lshl_add_u32 v132, v3, 11, v1
	s_add_i32 m0, s27, 0x10000
	v_lshl_add_u32 v134, v0, 11, v1
	v_readfirstlane_b32 vcc_lo, v8
	s_nop 3
	s_lshr_b32 vcc_lo, vcc_lo, 8
	s_cmp_eq_u32 vcc_lo, 0
	s_cbranch_scc0 .Lmy_prio_0
	s_setprio 1
.Lmy_prio_0:
	v_bfe_u32 v239, v8, 3, 3
	v_and_b32_e32 v240, 7, v8
	v_xor_b32_e32 v240, v240, v239
	v_lshlrev_b32_e32 v240, 4, v240
	v_lshrrev_b32_e32 v241, 6, v8
	v_lshl_add_u32 v242, v241, 3, v239
	v_mov_b32_e32 v243, 0x800
	v_mad_u32_u24 v134, v242, v243, v240
	v_add_u32_e32 v130, 0x20000, v134
	v_lshrrev_b32_e32 v244, 2, v241
	v_lshlrev_b32_e32 v244, 5, v244
	v_and_b32_e32 v245, 1, v241
	v_lshrrev_b32_e32 v246, 2, v239
	v_lshl_add_u32 v245, v245, 1, v246
	v_lshl_add_u32 v244, v245, 3, v244
	v_bfe_u32 v245, v241, 1, 1
	v_lshl_add_u32 v244, v245, 2, v244
	v_and_b32_e32 v245, 3, v239
	v_add_u32_e32 v244, v244, v245
	v_mad_u32_u24 v132, v244, v243, v240
	v_add_u32_e32 v128, 0x20000, v132
	global_load_lds_dwordx4 v132, s[30:31]
	s_add_i32 m0, s27, 0x12000
	s_add_u32 s2, s30, 0x40000
	global_load_lds_dwordx4 v128, s[30:31]
	s_addc_u32 s3, s31, 0
	s_add_i32 m0, s27, 0x14000
	s_load_dwordx2 s[4:5], s[4:5], 0x110
	global_load_lds_dwordx4 v132, s[2:3]
	s_add_i32 m0, s27, 0x16000
	s_add_u32 s28, s36, s0
	s_addc_u32 s29, s37, s1
	s_add_i32 s43, s27, 0x2000
	global_load_lds_dwordx4 v128, s[2:3]
	s_mov_b32 m0, s27
	s_add_u32 s0, s28, 0x40000
	global_load_lds_dwordx4 v134, s[28:29]
	s_mov_b32 m0, s43
	s_addc_u32 s1, s29, 0
	s_add_i32 s47, s27, 0x4000
	global_load_lds_dwordx4 v130, s[28:29]
	s_mov_b32 m0, s47
	s_add_i32 s50, s27, 0x6000
	global_load_lds_dwordx4 v134, s[0:1]
	s_mov_b32 m0, s50
	v_mov_b32_e32 v133, 0
	global_load_lds_dwordx4 v130, s[0:1]
	v_mov_b32_e32 v129, v133
	v_mov_b32_e32 v135, v133
	v_mov_b32_e32 v131, v133
	s_cmp_eq_u32 s11, 1
	s_mov_b32 s51, 0
	v_lshl_add_u64 v[6:7], s[30:31], 0, v[132:133]
	v_lshl_add_u64 v[4:5], s[30:31], 0, v[128:129]
	v_lshl_add_u64 v[0:1], s[28:29], 0, v[134:135]
	s_cselect_b64 s[8:9], -1, 0
	s_cmp_lg_u32 s11, 1
	v_lshl_add_u64 v[2:3], s[28:29], 0, v[130:131]
	s_cbranch_scc1 .LBB0_206
	s_barrier

; #define PG8_STAGE(bufoff, gbase, voff) do { _Pragma("unroll") for (int _i = 0; _i < 2; ++_i) \
;         __builtin_amdgcn_global_load_lds((const unsigned*)((const char*)(gbase) + (voff)[_i]), (PG8_LAS unsigned*)(lds + (bufoff) + ldsw + _i * 8192), 16, 0, 0); } while (0)
; #define PG8_LDA(dst, b, h) do { _Pragma("unroll") for (int m = 0; m < 4; ++m) _Pragma("unroll") for (int k = 0; k < 2; ++k) dst[m][k] = *(const PG8_LAS bf16x8*)(lds + PG8_SA(b, h) + aoff + m * 2048 + k * 1024); } while (0)
; #define PG8_LDB(dst, b, h) do { _Pragma("unroll") for (int n = 0; n < 2; ++n) _Pragma("unroll") for (int k = 0; k < 2; ++k) dst[n][k] = *(const PG8_LAS bf16x8*)(lds + PG8_SB(b, h) + boff + n * 2048 + k * 1024); } while (0)
; #define PG8_MMA(ai, bj, At, Bt) do { __builtin_amdgcn_s_setprio(1); _Pragma("unroll") for (int m = 0; m < 4; ++m) _Pragma("unroll") for (int n = 0; n < 2; ++n) _Pragma("unroll") for (int k = 0; k < 2; ++k) \
;         acc[ai][bj][m][n] = __builtin_amdgcn_mfma_f32_16x16x32_bf16(Bt[n][k], At[m][k], acc[ai][bj][m][n], 0, 0, 0); __builtin_amdgcn_s_setprio(0); } while (0)
; #define PG8_WAIT_V(n) asm volatile("s_waitcnt vmcnt(" #n ")" ::: "memory")
; #define PG8_WAIT_L(n) asm volatile("s_waitcnt lgkmcnt(" #n ")" ::: "memory")
; #define PG8_BAR __builtin_amdgcn_s_barrier()
; #define PG8_SCHED __builtin_amdgcn_sched_barrier(0)
; template <class Epi, class Sched, bool ALIGN_EPI = false, bool SP2 = false>
; __device__ __forceinline__ void gemm_phase(PG8_LAS unsigned char* lds, const Gemm g, const Sched& S, const Epi& E) {
;     ...
;             if constexpr (SP2) {
;             PG8_LDB(B0, 0, 0); PG8_LDB(B1, 0, 1); PG8_SCHED; PG8_LDA(At, 0, 0); PG8_STAGE(PG8_SA(1, 1), a1 + hstep, voffA);
;             PG8_WAIT_V(8); PG8_WAIT_L(0); PG8_BAR; PG8_MMA(0, 0, At, B0); PG8_MMA(0, 1, At, B1); PG8_BAR; PG8_SCHED;
;             PG8_LDA(At, 0, 1); PG8_STAGE(PG8_SB(0, 0), b2, voffB); PG8_STAGE(PG8_SB(0, 1), b2 + hstep, voffB); PG8_STAGE(PG8_SA(0, 0), a2, voffA);
;             PG8_WAIT_V(8); PG8_WAIT_L(0); PG8_BAR; PG8_MMA(1, 0, At, B0); PG8_MMA(1, 1, At, B1); PG8_BAR; PG8_SCHED;
.LBB0_212:
	ds_read_b128 v[144:147], v151
	ds_read_b128 v[154:157], v235
	ds_read_b128 v[158:161], v151 offset:2048
	ds_read_b128 v[162:165], v235 offset:2048
	ds_read_b128 v[166:169], v152
	ds_read_b128 v[170:173], v236
	ds_read_b128 v[174:177], v152 offset:2048
	ds_read_b128 v[178:181], v236 offset:2048
	s_add_u32 s0, s28, 0xfffc0080
	s_addc_u32 s1, s29, -1
	s_cmp_eq_u32 s64, 12
	s_cselect_b32 s35, s21, s1
	s_cselect_b32 s34, s60, s0
	s_cselect_b32 s31, s19, s63
	s_cselect_b32 s30, s61, s62
	v_lshl_add_u64 v[222:223], s[28:29], 0, v[136:137]
	s_add_i32 m0, s27, 0xc000
	ds_read_b128 v[190:193], v153
	ds_read_b128 v[194:197], v233
	ds_read_b128 v[198:201], v153 offset:2048
	ds_read_b128 v[202:205], v233 offset:2048
	ds_read_b128 v[206:209], v153 offset:4096
	ds_read_b128 v[210:213], v233 offset:4096
	ds_read_b128 v[214:217], v153 offset:6144
	ds_read_b128 v[218:221], v233 offset:6144
	global_load_lds_dwordx4 v[222:223], off
	v_lshl_add_u64 v[222:223], s[28:29], 0, v[138:139]
	s_add_i32 m0, s27, 0xe000
	s_nop 0
	global_load_lds_dwordx4 v[222:223], off
	s_waitcnt vmcnt(8)
	s_waitcnt lgkmcnt(0)
	s_barrier
	s_waitcnt lgkmcnt(0)
	v_mfma_f32_16x16x32_bf16 v[124:127], v[144:147], v[190:193], v[124:127]
	v_mfma_f32_16x16x32_bf16 v[120:123], v[158:161], v[190:193], v[120:123]
	v_mfma_f32_16x16x32_bf16 v[108:111], v[144:147], v[198:201], v[108:111]
	v_mfma_f32_16x16x32_bf16 v[104:107], v[158:161], v[198:201], v[104:107]
	v_mfma_f32_16x16x32_bf16 v[92:95], v[144:147], v[206:209], v[92:95]
	v_mfma_f32_16x16x32_bf16 v[88:91], v[158:161], v[206:209], v[88:91]
	v_mfma_f32_16x16x32_bf16 v[76:79], v[144:147], v[214:217], v[76:79]
	v_mfma_f32_16x16x32_bf16 v[72:75], v[158:161], v[214:217], v[72:75]
	v_mfma_f32_16x16x32_bf16 v[124:127], v[154:157], v[194:197], v[124:127]
	v_mfma_f32_16x16x32_bf16 v[120:123], v[162:165], v[194:197], v[120:123]
	v_mfma_f32_16x16x32_bf16 v[108:111], v[154:157], v[202:205], v[108:111]
	v_mfma_f32_16x16x32_bf16 v[104:107], v[162:165], v[202:205], v[104:107]
	v_mfma_f32_16x16x32_bf16 v[92:95], v[154:157], v[210:213], v[92:95]
	v_mfma_f32_16x16x32_bf16 v[88:91], v[162:165], v[210:213], v[88:91]
	v_mfma_f32_16x16x32_bf16 v[76:79], v[154:157], v[218:221], v[76:79]
	v_mfma_f32_16x16x32_bf16 v[72:75], v[162:165], v[218:221], v[72:75]
	v_mfma_f32_16x16x32_bf16 v[116:119], v[166:169], v[190:193], v[116:119]
	v_mfma_f32_16x16x32_bf16 v[112:115], v[174:177], v[190:193], v[112:115]
	v_mfma_f32_16x16x32_bf16 v[100:103], v[166:169], v[198:201], v[100:103]
	v_mfma_f32_16x16x32_bf16 v[96:99], v[174:177], v[198:201], v[96:99]
	v_mfma_f32_16x16x32_bf16 v[84:87], v[166:169], v[206:209], v[84:87]
	v_mfma_f32_16x16x32_bf16 v[80:83], v[174:177], v[206:209], v[80:83]
	v_mfma_f32_16x16x32_bf16 v[68:71], v[166:169], v[214:217], v[68:71]
	v_mfma_f32_16x16x32_bf16 v[64:67], v[174:177], v[214:217], v[64:67]
	v_mfma_f32_16x16x32_bf16 v[116:119], v[170:173], v[194:197], v[116:119]
	v_mfma_f32_16x16x32_bf16 v[112:115], v[178:181], v[194:197], v[112:115]
	v_mfma_f32_16x16x32_bf16 v[100:103], v[170:173], v[202:205], v[100:103]
	v_mfma_f32_16x16x32_bf16 v[96:99], v[178:181], v[202:205], v[96:99]
	v_mfma_f32_16x16x32_bf16 v[84:87], v[170:173], v[210:213], v[84:87]
	v_mfma_f32_16x16x32_bf16 v[80:83], v[178:181], v[210:213], v[80:83]
	v_mfma_f32_16x16x32_bf16 v[68:71], v[170:173], v[218:221], v[68:71]
	v_mfma_f32_16x16x32_bf16 v[64:67], v[178:181], v[218:221], v[64:67]
	s_barrier
	s_add_i32 s0, s56, s40
	v_lshl_add_u64 v[222:223], s[30:31], 0, v[132:133]
	s_mov_b32 m0, s0
	ds_read_b128 v[190:193], v153 offset:16384
	ds_read_b128 v[194:197], v233 offset:16384
	ds_read_b128 v[198:201], v153 offset:18432
	ds_read_b128 v[202:205], v233 offset:18432
	ds_read_b128 v[206:209], v153 offset:20480
	ds_read_b128 v[210:213], v233 offset:20480
	ds_read_b128 v[214:217], v153 offset:22528
	ds_read_b128 v[218:221], v233 offset:22528
	global_load_lds_dwordx4 v[222:223], off
	s_add_i32 m0, s0, 0x2000
	s_add_u32 s0, s30, 0x40000
	v_lshl_add_u64 v[224:225], s[30:31], 0, v[128:129]
	s_addc_u32 s1, s31, 0
	s_add_i32 s2, s57, s40
	global_load_lds_dwordx4 v[224:225], off
	v_lshl_add_u64 v[226:227], s[0:1], 0, v[132:133]
	s_mov_b32 m0, s2
	v_lshl_add_u64 v[228:229], s[34:35], 0, v[130:131]
	global_load_lds_dwordx4 v[226:227], off
	v_lshl_add_u64 v[226:227], s[0:1], 0, v[128:129]
	s_add_i32 m0, s2, 0x2000
	s_nop 0
	global_load_lds_dwordx4 v[226:227], off
	v_lshl_add_u64 v[226:227], s[34:35], 0, v[134:135]
	s_mov_b32 m0, s27
	s_nop 0
	global_load_lds_dwordx4 v[226:227], off
	s_mov_b32 m0, s43
	s_nop 0
	global_load_lds_dwordx4 v[228:229], off
	s_waitcnt vmcnt(8)
	s_waitcnt lgkmcnt(0)
	s_barrier
; #define PG8_STAGE(bufoff, gbase, voff) do { _Pragma("unroll") for (int _i = 0; _i < 2; ++_i) \
;         __builtin_amdgcn_global_load_lds((const unsigned*)((const char*)(gbase) + (voff)[_i]), (PG8_LAS unsigned*)(lds + (bufoff) + ldsw + _i * 8192), 16, 0, 0); } while (0)
; #define PG8_LDA(dst, b, h) do { _Pragma("unroll") for (int m = 0; m < 4; ++m) _Pragma("unroll") for (int k = 0; k < 2; ++k) dst[m][k] = *(const PG8_LAS bf16x8*)(lds + PG8_SA(b, h) + aoff + m * 2048 + k * 1024); } while (0)
; #define PG8_LDB(dst, b, h) do { _Pragma("unroll") for (int n = 0; n < 2; ++n) _Pragma("unroll") for (int k = 0; k < 2; ++k) dst[n][k] = *(const PG8_LAS bf16x8*)(lds + PG8_SB(b, h) + boff + n * 2048 + k * 1024); } while (0)
; #define PG8_MMA(ai, bj, At, Bt) do { __builtin_amdgcn_s_setprio(1); _Pragma("unroll") for (int m = 0; m < 4; ++m) _Pragma("unroll") for (int n = 0; n < 2; ++n) _Pragma("unroll") for (int k = 0; k < 2; ++k) \
;         acc[ai][bj][m][n] = __builtin_amdgcn_mfma_f32_16x16x32_bf16(Bt[n][k], At[m][k], acc[ai][bj][m][n], 0, 0, 0); __builtin_amdgcn_s_setprio(0); } while (0)
; #define PG8_WAIT_V(n) asm volatile("s_waitcnt vmcnt(" #n ")" ::: "memory")
; #define PG8_WAIT_L(n) asm volatile("s_waitcnt lgkmcnt(" #n ")" ::: "memory")
; #define PG8_BAR __builtin_amdgcn_s_barrier()
; #define PG8_SCHED __builtin_amdgcn_sched_barrier(0)
; template <class Epi, class Sched, bool ALIGN_EPI = false, bool SP2 = false>
; __device__ __forceinline__ void gemm_phase(PG8_LAS unsigned char* lds, const Gemm g, const Sched& S, const Epi& E) {
;     ...
;             PG8_WAIT_V(8); PG8_WAIT_L(0); PG8_BAR; PG8_MMA(0, 0, At, B0); PG8_MMA(0, 1, At, B1); PG8_BAR; PG8_SCHED;
;             PG8_LDA(At, 0, 1); PG8_STAGE(PG8_SB(0, 0), b2, voffB); PG8_STAGE(PG8_SB(0, 1), b2 + hstep, voffB); PG8_STAGE(PG8_SA(0, 0), a2, voffA);
;             PG8_WAIT_V(8); PG8_WAIT_L(0); PG8_BAR; PG8_MMA(1, 0, At, B0); PG8_MMA(1, 1, At, B1); PG8_BAR; PG8_SCHED;
;             PG8_LDB(B0, 1, 0); PG8_LDB(B1, 1, 1); PG8_SCHED; PG8_LDA(At, 1, 0); PG8_STAGE(PG8_SA(0, 1), a2 + hstep, voffA);
;             PG8_WAIT_V(8); PG8_WAIT_L(0); PG8_BAR; PG8_MMA(0, 0, At, B0); PG8_MMA(0, 1, At, B1); PG8_BAR; PG8_SCHED;
	s_waitcnt lgkmcnt(0)
	v_mfma_f32_16x16x32_bf16 v[60:63], v[144:147], v[190:193], v[60:63]
	v_mfma_f32_16x16x32_bf16 v[56:59], v[158:161], v[190:193], v[56:59]
	v_mfma_f32_16x16x32_bf16 v[44:47], v[144:147], v[198:201], v[44:47]
	v_mfma_f32_16x16x32_bf16 v[40:43], v[158:161], v[198:201], v[40:43]
	v_mfma_f32_16x16x32_bf16 v[28:31], v[144:147], v[206:209], v[28:31]
	v_mfma_f32_16x16x32_bf16 v[24:27], v[158:161], v[206:209], v[24:27]
	v_mfma_f32_16x16x32_bf16 v[12:15], v[144:147], v[214:217], v[12:15]
	v_mfma_f32_16x16x32_bf16 v[8:11], v[158:161], v[214:217], v[8:11]
	v_mfma_f32_16x16x32_bf16 v[60:63], v[154:157], v[194:197], v[60:63]
	v_mfma_f32_16x16x32_bf16 v[56:59], v[162:165], v[194:197], v[56:59]
	v_mfma_f32_16x16x32_bf16 v[44:47], v[154:157], v[202:205], v[44:47]
	v_mfma_f32_16x16x32_bf16 v[40:43], v[162:165], v[202:205], v[40:43]
	v_mfma_f32_16x16x32_bf16 v[28:31], v[154:157], v[210:213], v[28:31]
	v_mfma_f32_16x16x32_bf16 v[24:27], v[162:165], v[210:213], v[24:27]
	v_mfma_f32_16x16x32_bf16 v[12:15], v[154:157], v[218:221], v[12:15]
	v_mfma_f32_16x16x32_bf16 v[8:11], v[162:165], v[218:221], v[8:11]
	v_mfma_f32_16x16x32_bf16 v[52:55], v[166:169], v[190:193], v[52:55]
	v_mfma_f32_16x16x32_bf16 v[48:51], v[174:177], v[190:193], v[48:51]
	v_mfma_f32_16x16x32_bf16 v[36:39], v[166:169], v[198:201], v[36:39]
	v_mfma_f32_16x16x32_bf16 v[32:35], v[174:177], v[198:201], v[32:35]
	v_mfma_f32_16x16x32_bf16 v[20:23], v[166:169], v[206:209], v[20:23]
	v_mfma_f32_16x16x32_bf16 v[16:19], v[174:177], v[206:209], v[16:19]
	v_mfma_f32_16x16x32_bf16 v[4:7], v[166:169], v[214:217], v[4:7]
	v_mfma_f32_16x16x32_bf16 v[0:3], v[174:177], v[214:217], v[0:3]
	v_mfma_f32_16x16x32_bf16 v[52:55], v[170:173], v[194:197], v[52:55]
	v_mfma_f32_16x16x32_bf16 v[48:51], v[178:181], v[194:197], v[48:51]
	v_mfma_f32_16x16x32_bf16 v[36:39], v[170:173], v[202:205], v[36:39]
	v_mfma_f32_16x16x32_bf16 v[32:35], v[178:181], v[202:205], v[32:35]
	v_mfma_f32_16x16x32_bf16 v[20:23], v[170:173], v[210:213], v[20:23]
	v_mfma_f32_16x16x32_bf16 v[16:19], v[178:181], v[210:213], v[16:19]
	v_mfma_f32_16x16x32_bf16 v[4:7], v[170:173], v[218:221], v[4:7]
	v_mfma_f32_16x16x32_bf16 v[0:3], v[178:181], v[218:221], v[0:3]
	s_barrier
	s_add_i32 s2, 0, 0x18000
	s_add_i32 s3, 0, 0x1c000
	v_add_u32_e32 v162, s2, v149
	v_add_u32_e32 v237, s2, v234
	v_add_u32_e32 v178, s3, v149
	v_add_u32_e32 v238, s3, v234
	ds_read_b128 v[144:147], v162
	ds_read_b128 v[154:157], v237
	ds_read_b128 v[158:161], v162 offset:2048
	ds_read_b128 v[162:165], v237 offset:2048
	ds_read_b128 v[166:169], v178
	ds_read_b128 v[170:173], v238
	ds_read_b128 v[174:177], v178 offset:2048
	ds_read_b128 v[178:181], v238 offset:2048
	s_add_u32 s0, s34, 0x40000
	s_addc_u32 s1, s35, 0
	s_mov_b32 m0, s47
	v_lshl_add_u64 v[230:231], s[0:1], 0, v[134:135]
	ds_read_b128 v[190:193], v153 offset:32768
	ds_read_b128 v[194:197], v233 offset:32768
	ds_read_b128 v[198:201], v153 offset:34816
	ds_read_b128 v[202:205], v233 offset:34816
	ds_read_b128 v[206:209], v153 offset:36864
	ds_read_b128 v[210:213], v233 offset:36864
	ds_read_b128 v[214:217], v153 offset:38912
	ds_read_b128 v[218:221], v233 offset:38912
	global_load_lds_dwordx4 v[230:231], off
	v_lshl_add_u64 v[230:231], s[0:1], 0, v[130:131]
	s_mov_b32 m0, s50
	s_nop 0
	global_load_lds_dwordx4 v[230:231], off
	s_waitcnt vmcnt(8)
	s_waitcnt lgkmcnt(0)
	s_barrier
	s_waitcnt lgkmcnt(0)
	v_mfma_f32_16x16x32_bf16 v[124:127], v[144:147], v[190:193], v[124:127]
	v_mfma_f32_16x16x32_bf16 v[120:123], v[158:161], v[190:193], v[120:123]
	v_mfma_f32_16x16x32_bf16 v[108:111], v[144:147], v[198:201], v[108:111]
	v_mfma_f32_16x16x32_bf16 v[104:107], v[158:161], v[198:201], v[104:107]
	v_mfma_f32_16x16x32_bf16 v[92:95], v[144:147], v[206:209], v[92:95]
	v_mfma_f32_16x16x32_bf16 v[88:91], v[158:161], v[206:209], v[88:91]
	v_mfma_f32_16x16x32_bf16 v[76:79], v[144:147], v[214:217], v[76:79]
	v_mfma_f32_16x16x32_bf16 v[72:75], v[158:161], v[214:217], v[72:75]
	v_mfma_f32_16x16x32_bf16 v[124:127], v[154:157], v[194:197], v[124:127]
	v_mfma_f32_16x16x32_bf16 v[120:123], v[162:165], v[194:197], v[120:123]
	v_mfma_f32_16x16x32_bf16 v[108:111], v[154:157], v[202:205], v[108:111]
	v_mfma_f32_16x16x32_bf16 v[104:107], v[162:165], v[202:205], v[104:107]
	v_mfma_f32_16x16x32_bf16 v[92:95], v[154:157], v[210:213], v[92:95]
	v_mfma_f32_16x16x32_bf16 v[88:91], v[162:165], v[210:213], v[88:91]
	v_mfma_f32_16x16x32_bf16 v[76:79], v[154:157], v[218:221], v[76:79]
	v_mfma_f32_16x16x32_bf16 v[72:75], v[162:165], v[218:221], v[72:75]
	v_mfma_f32_16x16x32_bf16 v[116:119], v[166:169], v[190:193], v[116:119]
	v_mfma_f32_16x16x32_bf16 v[112:115], v[174:177], v[190:193], v[112:115]
	v_mfma_f32_16x16x32_bf16 v[100:103], v[166:169], v[198:201], v[100:103]
	v_mfma_f32_16x16x32_bf16 v[96:99], v[174:177], v[198:201], v[96:99]
	v_mfma_f32_16x16x32_bf16 v[84:87], v[166:169], v[206:209], v[84:87]
	v_mfma_f32_16x16x32_bf16 v[80:83], v[174:177], v[206:209], v[80:83]
	v_mfma_f32_16x16x32_bf16 v[68:71], v[166:169], v[214:217], v[68:71]
	v_mfma_f32_16x16x32_bf16 v[64:67], v[174:177], v[214:217], v[64:67]
	v_mfma_f32_16x16x32_bf16 v[116:119], v[170:173], v[194:197], v[116:119]
	v_mfma_f32_16x16x32_bf16 v[112:115], v[178:181], v[194:197], v[112:115]
	v_mfma_f32_16x16x32_bf16 v[100:103], v[170:173], v[202:205], v[100:103]
	v_mfma_f32_16x16x32_bf16 v[96:99], v[178:181], v[202:205], v[96:99]
	v_mfma_f32_16x16x32_bf16 v[84:87], v[170:173], v[210:213], v[84:87]
	v_mfma_f32_16x16x32_bf16 v[80:83], v[178:181], v[210:213], v[80:83]
	v_mfma_f32_16x16x32_bf16 v[68:71], v[170:173], v[218:221], v[68:71]
	v_mfma_f32_16x16x32_bf16 v[64:67], v[178:181], v[218:221], v[64:67]
	s_barrier
; #define PG8_STAGE(bufoff, gbase, voff) do { _Pragma("unroll") for (int _i = 0; _i < 2; ++_i) \
;         __builtin_amdgcn_global_load_lds((const unsigned*)((const char*)(gbase) + (voff)[_i]), (PG8_LAS unsigned*)(lds + (bufoff) + ldsw + _i * 8192), 16, 0, 0); } while (0)
; #define PG8_LDA(dst, b, h) do { _Pragma("unroll") for (int m = 0; m < 4; ++m) _Pragma("unroll") for (int k = 0; k < 2; ++k) dst[m][k] = *(const PG8_LAS bf16x8*)(lds + PG8_SA(b, h) + aoff + m * 2048 + k * 1024); } while (0)
; #define PG8_LDB(dst, b, h) do { _Pragma("unroll") for (int n = 0; n < 2; ++n) _Pragma("unroll") for (int k = 0; k < 2; ++k) dst[n][k] = *(const PG8_LAS bf16x8*)(lds + PG8_SB(b, h) + boff + n * 2048 + k * 1024); } while (0)
; #define PG8_MMA(ai, bj, At, Bt) do { __builtin_amdgcn_s_setprio(1); _Pragma("unroll") for (int m = 0; m < 4; ++m) _Pragma("unroll") for (int n = 0; n < 2; ++n) _Pragma("unroll") for (int k = 0; k < 2; ++k) \
;         acc[ai][bj][m][n] = __builtin_amdgcn_mfma_f32_16x16x32_bf16(Bt[n][k], At[m][k], acc[ai][bj][m][n], 0, 0, 0); __builtin_amdgcn_s_setprio(0); } while (0)
; #define PG8_WAIT_V(n) asm volatile("s_waitcnt vmcnt(" #n ")" ::: "memory")
; #define PG8_WAIT_L(n) asm volatile("s_waitcnt lgkmcnt(" #n ")" ::: "memory")
; #define PG8_BAR __builtin_amdgcn_s_barrier()
; #define PG8_SCHED __builtin_amdgcn_sched_barrier(0)
; template <class Epi, class Sched, bool ALIGN_EPI = false, bool SP2 = false>
; __device__ __forceinline__ void gemm_phase(PG8_LAS unsigned char* lds, const Gemm g, const Sched& S, const Epi& E) {
;     ...
;             PG8_LDB(B0, 1, 0); PG8_LDB(B1, 1, 1); PG8_SCHED; PG8_LDA(At, 1, 0); PG8_STAGE(PG8_SA(0, 1), a2 + hstep, voffA);
;             PG8_WAIT_V(8); PG8_WAIT_L(0); PG8_BAR; PG8_MMA(0, 0, At, B0); PG8_MMA(0, 1, At, B1); PG8_BAR; PG8_SCHED;
;             PG8_LDA(At, 1, 1); PG8_STAGE(PG8_SB(1, 0), b3, voffB); PG8_STAGE(PG8_SB(1, 1), b3 + hstep, voffB); PG8_STAGE(PG8_SA(1, 0), a3, voffA);
;             PG8_WAIT_V(8); PG8_WAIT_L(0); PG8_BAR; PG8_MMA(1, 0, At, B0); PG8_MMA(1, 1, At, B1); PG8_BAR; PG8_SCHED;
	s_add_i32 s0, s2, s40
	v_lshl_add_u64 v[222:223], v[222:223], 0, s[14:15]
	s_mov_b32 m0, s0
	ds_read_b128 v[190:193], v153 offset:49152
	ds_read_b128 v[194:197], v233 offset:49152
	ds_read_b128 v[198:201], v153 offset:51200
	ds_read_b128 v[202:205], v233 offset:51200
	ds_read_b128 v[206:209], v153 offset:53248
	ds_read_b128 v[210:213], v233 offset:53248
	ds_read_b128 v[214:217], v153 offset:55296
	ds_read_b128 v[218:221], v233 offset:55296
	global_load_lds_dwordx4 v[222:223], off
	s_add_i32 m0, s0, 0x2000
	s_add_u32 s0, s30, 0x40080
	v_lshl_add_u64 v[222:223], v[224:225], 0, s[14:15]
	s_addc_u32 s1, s31, 0
	s_add_i32 s2, s3, s40
	global_load_lds_dwordx4 v[222:223], off
	v_lshl_add_u64 v[222:223], s[0:1], 0, v[132:133]
	s_mov_b32 m0, s2
	s_nop 0
	global_load_lds_dwordx4 v[222:223], off
	v_lshl_add_u64 v[222:223], s[0:1], 0, v[128:129]
	s_add_i32 m0, s2, 0x2000
	s_nop 0
	global_load_lds_dwordx4 v[222:223], off
	v_lshl_add_u64 v[222:223], v[226:227], 0, s[14:15]
	s_mov_b32 m0, s52
	s_nop 0
	global_load_lds_dwordx4 v[222:223], off
	v_lshl_add_u64 v[222:223], v[228:229], 0, s[14:15]
	s_mov_b32 m0, s53
	s_nop 0
	global_load_lds_dwordx4 v[222:223], off
	s_waitcnt vmcnt(8)
	s_waitcnt lgkmcnt(0)
	s_barrier
	s_waitcnt lgkmcnt(0)
	v_mfma_f32_16x16x32_bf16 v[60:63], v[144:147], v[190:193], v[60:63]
	v_mfma_f32_16x16x32_bf16 v[56:59], v[158:161], v[190:193], v[56:59]
	v_mfma_f32_16x16x32_bf16 v[44:47], v[144:147], v[198:201], v[44:47]
	v_mfma_f32_16x16x32_bf16 v[40:43], v[158:161], v[198:201], v[40:43]
	v_mfma_f32_16x16x32_bf16 v[28:31], v[144:147], v[206:209], v[28:31]
	v_mfma_f32_16x16x32_bf16 v[24:27], v[158:161], v[206:209], v[24:27]
	v_mfma_f32_16x16x32_bf16 v[12:15], v[144:147], v[214:217], v[12:15]
	v_mfma_f32_16x16x32_bf16 v[8:11], v[158:161], v[214:217], v[8:11]
	v_mfma_f32_16x16x32_bf16 v[60:63], v[154:157], v[194:197], v[60:63]
	v_mfma_f32_16x16x32_bf16 v[56:59], v[162:165], v[194:197], v[56:59]
	v_mfma_f32_16x16x32_bf16 v[44:47], v[154:157], v[202:205], v[44:47]
	v_mfma_f32_16x16x32_bf16 v[40:43], v[162:165], v[202:205], v[40:43]
	v_mfma_f32_16x16x32_bf16 v[28:31], v[154:157], v[210:213], v[28:31]
	v_mfma_f32_16x16x32_bf16 v[24:27], v[162:165], v[210:213], v[24:27]
	v_mfma_f32_16x16x32_bf16 v[12:15], v[154:157], v[218:221], v[12:15]
	v_mfma_f32_16x16x32_bf16 v[8:11], v[162:165], v[218:221], v[8:11]
	v_mfma_f32_16x16x32_bf16 v[52:55], v[166:169], v[190:193], v[52:55]
	v_mfma_f32_16x16x32_bf16 v[48:51], v[174:177], v[190:193], v[48:51]
	v_mfma_f32_16x16x32_bf16 v[36:39], v[166:169], v[198:201], v[36:39]
	v_mfma_f32_16x16x32_bf16 v[32:35], v[174:177], v[198:201], v[32:35]
	v_mfma_f32_16x16x32_bf16 v[20:23], v[166:169], v[206:209], v[20:23]
	v_mfma_f32_16x16x32_bf16 v[16:19], v[174:177], v[206:209], v[16:19]
	v_mfma_f32_16x16x32_bf16 v[4:7], v[166:169], v[214:217], v[4:7]
	v_mfma_f32_16x16x32_bf16 v[0:3], v[174:177], v[214:217], v[0:3]
	v_mfma_f32_16x16x32_bf16 v[52:55], v[170:173], v[194:197], v[52:55]
	v_mfma_f32_16x16x32_bf16 v[48:51], v[178:181], v[194:197], v[48:51]
	v_mfma_f32_16x16x32_bf16 v[36:39], v[170:173], v[202:205], v[36:39]
	v_mfma_f32_16x16x32_bf16 v[32:35], v[178:181], v[202:205], v[32:35]
	v_mfma_f32_16x16x32_bf16 v[20:23], v[170:173], v[210:213], v[20:23]
	v_mfma_f32_16x16x32_bf16 v[16:19], v[178:181], v[210:213], v[16:19]
	v_mfma_f32_16x16x32_bf16 v[4:7], v[170:173], v[218:221], v[4:7]
	v_mfma_f32_16x16x32_bf16 v[0:3], v[178:181], v[218:221], v[0:3]
	s_barrier
	s_add_i32 s64, s64, 2
	s_add_u32 s28, s28, 0x100
	s_addc_u32 s29, s29, 0
	s_add_u32 s62, s62, 0x100
	s_addc_u32 s63, s63, 0
	s_cmp_gt_u32 s64, 13
	s_cbranch_scc0 .LBB0_212
	s_and_b64 vcc, exec, s[16:17]
	s_cbranch_vccz .LBB0_215
	s_barrier

; #define PG8_WAIT_V(n) asm volatile("s_waitcnt vmcnt(" #n ")" ::: "memory")
; #define PG8_BAR __builtin_amdgcn_s_barrier()
; template <class Epi, class Sched, bool ALIGN_EPI = false, bool SP2 = false>
; __device__ __forceinline__ void gemm_phase(PG8_LAS unsigned char* lds, const Gemm g, const Sched& S, const Epi& E) {
;     ...
;     PG8_WAIT_V(0);
;     if constexpr (!ALIGN_EPI) { if (wr == 0) PG8_BAR; }
;     PG8_BAR;
.LBB0_218:
	s_waitcnt vmcnt(0)
	s_setprio 0
	s_barrier

; __device__ __forceinline__ int fresh_tid() { int t = (int)threadIdx.x; asm volatile("" : "+v"(t)); return t; }
; #define PG8_STAGE(bufoff, gbase, voff) do { _Pragma("unroll") for (int _i = 0; _i < 2; ++_i) \
;         __builtin_amdgcn_global_load_lds((const unsigned*)((const char*)(gbase) + (voff)[_i]), (PG8_LAS unsigned*)(lds + (bufoff) + ldsw + _i * 8192), 16, 0, 0); } while (0)
; template <class Epi, class Sched, bool ALIGN_EPI = false, bool SP2 = false>
; __device__ __forceinline__ void gemm_phase(PG8_LAS unsigned char* lds, const Gemm g, const Sched& S, const Epi& E) {
;     const int tid = fresh_tid(), wid = __builtin_amdgcn_readfirstlane(tid >> 6), lane = tid & 63, wr = wid >> 2, wc = wid & 3, fr = lane & 15, fq = lane >> 4;
;     const int K = g.K, nt = K / BK;
;     unsigned voffA[2], voffB[2];
; #pragma unroll
;     for (int i = 0; i < 2; ++i) { int R, C; stage_rc(tid * 16 + i * 8192, R, C); const int Rb = Epi::PERM ? ((R & ~31) + perm32(R & 31)) : R;
;         voffA[i] = (unsigned)(R * K + C) * 2u; voffB[i] = (unsigned)(Rb * K + C) * 2u; }
;     const size_t kstep = (size_t)(BK * 2);
;     const size_t hstep = (size_t)HALF * K * 2;
;     const size_t tstep = 2 * hstep;
;     const unsigned ldsw = (unsigned)wid * 1024u;
;     const int aoff = lds_byte(wr * 64 + fr, fq * 8), boff = lds_byte(wc * 32 + fr, fq * 8);
;     ...
;     const char* cA = (const char*)g.A + (size_t)cur.pm * tstep; const char* cB = (const char*)g.Bt + (size_t)cur.pn * tstep;
;     S.a_ready(cur);
;     if constexpr (SP2) {
;         PG8_STAGE(PG8_SB(0, 0), cB, voffB); PG8_STAGE(PG8_SB(0, 1), cB + hstep, voffB); PG8_STAGE(PG8_SA(0, 0), cA, voffA); PG8_STAGE(PG8_SA(0, 1), cA + hstep, voffA);
;         if (wr == 1) PG8_BAR;
;         PG8_WAIT_V(2); PG8_BAR;
;         PG8_STAGE(PG8_SB(1, 0), cB + kstep, voffB); PG8_STAGE(PG8_SA(1, 0), cA + kstep, voffA); PG8_STAGE(PG8_SB(1, 1), cB + hstep + kstep, voffB);
;         PG8_WAIT_V(6); PG8_BAR;
;     } else {
;         PG8_STAGE(PG8_SB(0, 0), cB, voffB); PG8_STAGE(PG8_SA(0, 0), cA, voffA); PG8_STAGE(PG8_SB(0, 1), cB + hstep, voffB); PG8_STAGE(PG8_SA(0, 1), cA + hstep, voffA);
;         if (wr == 1) PG8_BAR;
;         PG8_WAIT_V(4); PG8_BAR;
;         PG8_STAGE(PG8_SB(1, 0), cB + kstep, voffB); PG8_STAGE(PG8_SA(1, 0), cA + kstep, voffA); PG8_STAGE(PG8_SB(1, 1), cB + hstep + kstep, voffB);
;         PG8_WAIT_V(6); PG8_BAR;
.LBB0_287:
	v_ashrrev_i32_e32 v1, 31, v8
	v_lshrrev_b32_e32 v1, 26, v1
	v_add_u32_e32 v1, v8, v1
	v_ashrrev_i32_e32 v9, 6, v1
	v_bfe_i32 v1, v8, 27, 1
	v_lshlrev_b32_e32 v0, 4, v8
	v_lshrrev_b32_e32 v1, 22, v1
	v_add_u32_e32 v1, v0, v1
	v_and_b32_e32 v1, 0xfffffc00, v1
	v_sub_u32_e32 v1, v0, v1
	v_lshrrev_b32_e32 v2, 4, v1
	v_bitop3_b32 v2, v2, v1, 32 bitop3:0x6c
	v_ashrrev_i32_e32 v1, 31, v1
	v_lshrrev_b32_e32 v1, 26, v1
	v_lshlrev_b32_e32 v3, 3, v9
	v_add_u32_e32 v1, v2, v1
	v_and_b32_e32 v3, -16, v3
	v_ashrrev_i32_e32 v11, 6, v1
	v_add_u32_e32 v1, v11, v3
	v_lshlrev_b32_e32 v3, 5, v9
	s_ashr_i32 s0, s11, 3
	v_and_b32_e32 v10, 32, v3
	v_mul_i32_i24_e32 v3, 64, v11
	s_waitcnt lgkmcnt(0)
	s_add_u32 s41, s12, 0xb200000
	v_sub_u32_e32 v2, v2, v3
	v_mov_b32_e32 v3, 1
	s_addc_u32 s42, s13, 0
	v_ashrrev_i16_sdwa v2, v3, sext(v2) dst_sel:DWORD dst_unused:UNUSED_PAD src0_sel:DWORD src1_sel:BYTE_0
	v_lshlrev_b32_e32 v4, 1, v1
	v_lshrrev_b32_e32 v5, 2, v1
	v_and_b32_e32 v6, 3, v11
	s_mov_b32 s1, 0xffffe0
	s_add_u32 s43, s8, 0xc00000
	v_bfe_i32 v12, v2, 0, 16
	v_and_b32_e32 v4, 24, v4
	v_and_b32_e32 v5, 4, v5
	v_and_or_b32 v6, v1, s1, v6
	s_movk_i32 s8, 0xb00
	v_add_u32_e32 v2, v10, v12
	v_or3_b32 v4, v6, v5, v4
	v_mul_lo_u32 v1, v1, s8
	v_add_lshl_u32 v128, v2, v1, 1
	v_mul_u32_u24_e32 v1, 0xb00, v4
	v_add_u32_e32 v0, 0x2000, v0
	v_add_lshl_u32 v130, v1, v2, 1
	v_ashrrev_i32_e32 v1, 31, v0
	v_lshrrev_b32_e32 v1, 22, v1
	v_add_u32_e32 v1, v0, v1
	v_ashrrev_i32_e32 v13, 10, v1
	v_mul_i32_i24_e32 v1, 0x400, v13
	v_sub_u32_e32 v0, v0, v1
	v_lshrrev_b32_e32 v1, 4, v0
	v_bitop3_b32 v0, v1, v0, 32 bitop3:0x6c
	v_ashrrev_i32_e32 v2, 31, v0
	v_lshrrev_b32_e32 v2, 26, v2
	v_lshlrev_b32_e32 v1, 3, v13
	v_add_u32_e32 v2, v0, v2
	v_and_b32_e32 v1, -16, v1
	v_ashrrev_i32_e32 v14, 6, v2
	v_lshlrev_b32_e32 v4, 5, v13
	s_addc_u32 s47, s9, 0
	v_add_u32_e32 v1, v14, v1
	v_and_b32_e32 v15, 32, v4
	v_and_b32_e32 v4, 3, v14
	s_add_i32 s0, s16, s0
	v_and_or_b32 v4, v1, s1, v4
	s_ashr_i32 s1, s0, 31
	s_lshr_b32 s1, s1, 27
	s_add_i32 s1, s0, s1
	s_ashr_i32 s3, s1, 5
	s_andn2_b32 s1, s1, 31
	s_sub_i32 s0, s0, s1
	s_bfe_i32 s1, s0, 0x80000
	s_bfe_u32 s1, s1, 0x3000c
	s_add_i32 s1, s0, s1
	s_bfe_i32 s12, s1, 0x80000
	s_and_b32 s1, s1, 0xf8
	s_sub_i32 s0, s1, s0
	s_sext_i32_i16 s12, s12
	s_sext_i32_i8 s0, s0
	s_lshl_b32 s1, s3, 3
	s_ashr_i32 s9, s10, 6
	v_and_b32_e32 v2, 0xc0, v2
	s_lshr_b32 s18, s12, 3
	s_sub_i32 s0, s0, s1
	s_ashr_i32 s12, s12, 3
	v_sub_u32_e32 v0, v0, v2
	s_ashr_i32 s11, s10, 8
	s_lshl_b32 s52, s9, 10
	s_addk_i32 s0, 0x7f
	s_mul_hi_i32 s13, s12, 0x160000
	s_mul_i32 s12, s12, 0x160000
	v_ashrrev_i16_sdwa v0, v3, sext(v0) dst_sel:DWORD dst_unused:UNUSED_PAD src0_sel:DWORD src1_sel:BYTE_0
	v_lshlrev_b32_e32 v2, 1, v1
	v_lshrrev_b32_e32 v3, 2, v1
	s_add_u32 s34, s43, s12
	v_bfe_i32 v16, v0, 0, 16
	v_and_b32_e32 v2, 24, v2
	v_and_b32_e32 v3, 4, v3
	s_addc_u32 s35, s47, s13
	s_add_i32 s53, s52, 0
	v_add_u32_e32 v0, v15, v16
	v_or3_b32 v2, v4, v3, v2
	v_mul_lo_u32 v1, v1, s8
	s_add_i32 m0, s53, 0x10000
	v_add_lshl_u32 v132, v0, v1, 1
	v_mul_u32_u24_e32 v1, 0xb00, v2
	v_readfirstlane_b32 vcc_lo, v8
	s_nop 3
	s_lshr_b32 vcc_lo, vcc_lo, 8
	s_cmp_eq_u32 vcc_lo, 0
	s_cbranch_scc0 .Lmy_prio_1
	s_setprio 1
.Lmy_prio_1:
	v_bfe_u32 v239, v8, 3, 3
	v_and_b32_e32 v240, 7, v8
	v_xor_b32_e32 v240, v240, v239
	v_lshlrev_b32_e32 v240, 4, v240
	v_lshrrev_b32_e32 v241, 6, v8
	v_lshl_add_u32 v242, v241, 3, v239
	v_mov_b32_e32 v243, 0x1600
	v_mad_u32_u24 v128, v242, v243, v240
	v_add_u32_e32 v132, 0x58000, v128
	v_lshrrev_b32_e32 v244, 2, v241
	v_lshlrev_b32_e32 v244, 5, v244
	v_and_b32_e32 v245, 1, v241
	v_lshrrev_b32_e32 v246, 2, v239
	v_lshl_add_u32 v245, v245, 1, v246
	v_lshl_add_u32 v244, v245, 3, v244
	v_bfe_u32 v245, v241, 1, 1
	v_lshl_add_u32 v244, v245, 2, v244
	v_and_b32_e32 v245, 3, v239
	v_add_u32_e32 v244, v244, v245
	v_mad_u32_u24 v130, v244, v243, v240
	v_add_u32_e32 v134, 0x58000, v130
	global_load_lds_dwordx4 v130, s[34:35]
	s_add_i32 m0, s53, 0x12000
	s_add_u32 s12, s34, 0xb0000
	global_load_lds_dwordx4 v134, s[34:35]
	s_addc_u32 s13, s35, 0
	s_add_i32 m0, s53, 0x14000
	s_mul_i32 s3, s0, 0x160000
	global_load_lds_dwordx4 v130, s[12:13]
	s_add_i32 m0, s53, 0x16000
	s_mul_hi_u32 s1, s0, 0x160000
	s_add_u32 s30, s41, s3
	s_addc_u32 s31, s42, s1
	s_add_i32 s54, s53, 0x2000
	global_load_lds_dwordx4 v134, s[12:13]
	s_mov_b32 m0, s53
	s_add_u32 s12, s30, 0xb0000
	global_load_lds_dwordx4 v128, s[30:31]
	s_mov_b32 m0, s54
	s_addc_u32 s13, s31, 0
	s_add_i32 s55, s53, 0x4000
	global_load_lds_dwordx4 v132, s[30:31]
	s_mov_b32 m0, s55
	s_add_i32 s56, s53, 0x6000
	global_load_lds_dwordx4 v128, s[12:13]
	s_mov_b32 m0, s56
	v_mov_b32_e32 v131, 0
	global_load_lds_dwordx4 v132, s[12:13]
	v_mov_b32_e32 v135, v131
	v_mov_b32_e32 v129, v131
	v_mov_b32_e32 v133, v131
	s_cmp_eq_u32 s11, 1
	s_mov_b32 s57, 0
	v_lshl_add_u64 v[6:7], s[34:35], 0, v[130:131]
	v_lshl_add_u64 v[4:5], s[34:35], 0, v[134:135]
	v_lshl_add_u64 v[0:1], s[30:31], 0, v[128:129]
	s_cselect_b64 s[12:13], -1, 0
	s_cmp_lg_u32 s11, 1
	v_lshl_add_u64 v[2:3], s[30:31], 0, v[132:133]
	s_cbranch_scc1 .LBB0_289
	s_barrier

; #define PG8_STAGE(bufoff, gbase, voff) do { _Pragma("unroll") for (int _i = 0; _i < 2; ++_i) \
;         __builtin_amdgcn_global_load_lds((const unsigned*)((const char*)(gbase) + (voff)[_i]), (PG8_LAS unsigned*)(lds + (bufoff) + ldsw + _i * 8192), 16, 0, 0); } while (0)
; #define PG8_LDA(dst, b, h) do { _Pragma("unroll") for (int m = 0; m < 4; ++m) _Pragma("unroll") for (int k = 0; k < 2; ++k) dst[m][k] = *(const PG8_LAS bf16x8*)(lds + PG8_SA(b, h) + aoff + m * 2048 + k * 1024); } while (0)
; #define PG8_LDB(dst, b, h) do { _Pragma("unroll") for (int n = 0; n < 2; ++n) _Pragma("unroll") for (int k = 0; k < 2; ++k) dst[n][k] = *(const PG8_LAS bf16x8*)(lds + PG8_SB(b, h) + boff + n * 2048 + k * 1024); } while (0)
; #define PG8_MMA(ai, bj, At, Bt) do { __builtin_amdgcn_s_setprio(1); _Pragma("unroll") for (int m = 0; m < 4; ++m) _Pragma("unroll") for (int n = 0; n < 2; ++n) _Pragma("unroll") for (int k = 0; k < 2; ++k) \
;         acc[ai][bj][m][n] = __builtin_amdgcn_mfma_f32_16x16x32_bf16(Bt[n][k], At[m][k], acc[ai][bj][m][n], 0, 0, 0); __builtin_amdgcn_s_setprio(0); } while (0)
; #define PG8_WAIT_V(n) asm volatile("s_waitcnt vmcnt(" #n ")" ::: "memory")
; #define PG8_WAIT_L(n) asm volatile("s_waitcnt lgkmcnt(" #n ")" ::: "memory")
; #define PG8_BAR __builtin_amdgcn_s_barrier()
; #define PG8_SCHED __builtin_amdgcn_sched_barrier(0)
; template <class Epi, class Sched, bool ALIGN_EPI = false, bool SP2 = false>
; __device__ __forceinline__ void gemm_phase(PG8_LAS unsigned char* lds, const Gemm g, const Sched& S, const Epi& E) {
;     ...
;             if constexpr (SP2) {
;             PG8_LDB(B0, 0, 0); PG8_LDB(B1, 0, 1); PG8_SCHED; PG8_LDA(At, 0, 0); PG8_STAGE(PG8_SA(1, 1), a1 + hstep, voffA);
;             PG8_WAIT_V(8); PG8_WAIT_L(0); PG8_BAR; PG8_MMA(0, 0, At, B0); PG8_MMA(0, 1, At, B1); PG8_BAR; PG8_SCHED;
;             PG8_LDA(At, 0, 1); PG8_STAGE(PG8_SB(0, 0), b2, voffB); PG8_STAGE(PG8_SB(0, 1), b2 + hstep, voffB); PG8_STAGE(PG8_SA(0, 0), a2, voffA);
;             PG8_WAIT_V(8); PG8_WAIT_L(0); PG8_BAR; PG8_MMA(1, 0, At, B0); PG8_MMA(1, 1, At, B1); PG8_BAR; PG8_SCHED;
.LBB0_303:
	ds_read_b128 v[150:153], v147
	ds_read_b128 v[154:157], v235
	ds_read_b128 v[158:161], v147 offset:2048
	ds_read_b128 v[162:165], v235 offset:2048
	ds_read_b128 v[166:169], v148
	ds_read_b128 v[170:173], v236
	ds_read_b128 v[174:177], v148 offset:2048
	ds_read_b128 v[178:181], v236 offset:2048
	s_add_u32 s34, s30, 0x100
	s_addc_u32 s35, s31, 0
	s_cmp_eq_u32 s74, 40
	s_cselect_b32 s39, s9, s35
	s_cselect_b32 s38, s8, s34
	s_cselect_b32 s37, s29, s73
	s_cselect_b32 s36, s28, s72
	v_lshl_add_u64 v[222:223], s[30:31], 0, v[136:137]
	s_add_i32 m0, s53, 0xc000
	ds_read_b128 v[190:193], v149
	ds_read_b128 v[194:197], v233
	ds_read_b128 v[198:201], v149 offset:2048
	ds_read_b128 v[202:205], v233 offset:2048
	ds_read_b128 v[206:209], v149 offset:4096
	ds_read_b128 v[210:213], v233 offset:4096
	ds_read_b128 v[214:217], v149 offset:6144
	ds_read_b128 v[218:221], v233 offset:6144
	global_load_lds_dwordx4 v[222:223], off
	v_lshl_add_u64 v[222:223], s[30:31], 0, v[138:139]
	s_add_i32 m0, s53, 0xe000
	s_nop 0
	global_load_lds_dwordx4 v[222:223], off
	s_waitcnt vmcnt(8)
	s_waitcnt lgkmcnt(0)
	s_barrier
	s_waitcnt lgkmcnt(0)
	v_mfma_f32_16x16x32_bf16 v[124:127], v[150:153], v[190:193], v[124:127]
	v_mfma_f32_16x16x32_bf16 v[120:123], v[158:161], v[190:193], v[120:123]
	v_mfma_f32_16x16x32_bf16 v[116:119], v[150:153], v[198:201], v[116:119]
	v_mfma_f32_16x16x32_bf16 v[112:115], v[158:161], v[198:201], v[112:115]
	v_mfma_f32_16x16x32_bf16 v[108:111], v[150:153], v[206:209], v[108:111]
	v_mfma_f32_16x16x32_bf16 v[104:107], v[158:161], v[206:209], v[104:107]
	v_mfma_f32_16x16x32_bf16 v[100:103], v[150:153], v[214:217], v[100:103]
	v_mfma_f32_16x16x32_bf16 v[96:99], v[158:161], v[214:217], v[96:99]
	v_mfma_f32_16x16x32_bf16 v[124:127], v[154:157], v[194:197], v[124:127]
	v_mfma_f32_16x16x32_bf16 v[120:123], v[162:165], v[194:197], v[120:123]
	v_mfma_f32_16x16x32_bf16 v[116:119], v[154:157], v[202:205], v[116:119]
	v_mfma_f32_16x16x32_bf16 v[112:115], v[162:165], v[202:205], v[112:115]
	v_mfma_f32_16x16x32_bf16 v[108:111], v[154:157], v[210:213], v[108:111]
	v_mfma_f32_16x16x32_bf16 v[104:107], v[162:165], v[210:213], v[104:107]
	v_mfma_f32_16x16x32_bf16 v[100:103], v[154:157], v[218:221], v[100:103]
	v_mfma_f32_16x16x32_bf16 v[96:99], v[162:165], v[218:221], v[96:99]
	v_mfma_f32_16x16x32_bf16 v[76:79], v[166:169], v[190:193], v[76:79]
	v_mfma_f32_16x16x32_bf16 v[68:71], v[174:177], v[190:193], v[68:71]
	v_mfma_f32_16x16x32_bf16 v[60:63], v[166:169], v[198:201], v[60:63]
	v_mfma_f32_16x16x32_bf16 v[52:55], v[174:177], v[198:201], v[52:55]
	v_mfma_f32_16x16x32_bf16 v[44:47], v[166:169], v[206:209], v[44:47]
	v_mfma_f32_16x16x32_bf16 v[40:43], v[174:177], v[206:209], v[40:43]
	v_mfma_f32_16x16x32_bf16 v[36:39], v[166:169], v[214:217], v[36:39]
	v_mfma_f32_16x16x32_bf16 v[32:35], v[174:177], v[214:217], v[32:35]
	v_mfma_f32_16x16x32_bf16 v[76:79], v[170:173], v[194:197], v[76:79]
	v_mfma_f32_16x16x32_bf16 v[68:71], v[178:181], v[194:197], v[68:71]
	v_mfma_f32_16x16x32_bf16 v[60:63], v[170:173], v[202:205], v[60:63]
	v_mfma_f32_16x16x32_bf16 v[52:55], v[178:181], v[202:205], v[52:55]
	v_mfma_f32_16x16x32_bf16 v[44:47], v[170:173], v[210:213], v[44:47]
	v_mfma_f32_16x16x32_bf16 v[40:43], v[178:181], v[210:213], v[40:43]
	v_mfma_f32_16x16x32_bf16 v[36:39], v[170:173], v[218:221], v[36:39]
	v_mfma_f32_16x16x32_bf16 v[32:35], v[178:181], v[218:221], v[32:35]
	s_barrier
	s_add_i32 s3, s62, s52
	v_lshl_add_u64 v[222:223], s[36:37], 0, v[130:131]
	s_mov_b32 m0, s3
	ds_read_b128 v[190:193], v149 offset:16384
	ds_read_b128 v[194:197], v233 offset:16384
	ds_read_b128 v[198:201], v149 offset:18432
	ds_read_b128 v[202:205], v233 offset:18432
	ds_read_b128 v[206:209], v149 offset:20480
	ds_read_b128 v[210:213], v233 offset:20480
	ds_read_b128 v[214:217], v149 offset:22528
	ds_read_b128 v[218:221], v233 offset:22528
	global_load_lds_dwordx4 v[222:223], off
	s_add_i32 m0, s3, 0x2000
	s_add_u32 s10, s36, 0xb0000
	v_lshl_add_u64 v[224:225], s[36:37], 0, v[134:135]
	s_addc_u32 s11, s37, 0
	s_add_i32 s3, s63, s52
	global_load_lds_dwordx4 v[224:225], off
	v_lshl_add_u64 v[226:227], s[10:11], 0, v[130:131]
	s_mov_b32 m0, s3
	v_lshl_add_u64 v[228:229], s[38:39], 0, v[132:133]
	global_load_lds_dwordx4 v[226:227], off
	v_lshl_add_u64 v[226:227], s[10:11], 0, v[134:135]
	s_add_i32 m0, s3, 0x2000
	s_nop 0
	global_load_lds_dwordx4 v[226:227], off
	v_lshl_add_u64 v[226:227], s[38:39], 0, v[128:129]
	s_mov_b32 m0, s53
	s_nop 0
	global_load_lds_dwordx4 v[226:227], off
	s_mov_b32 m0, s54
	s_nop 0
	global_load_lds_dwordx4 v[228:229], off
	s_waitcnt vmcnt(8)
	s_waitcnt lgkmcnt(0)
	s_barrier
; #define PG8_STAGE(bufoff, gbase, voff) do { _Pragma("unroll") for (int _i = 0; _i < 2; ++_i) \
;         __builtin_amdgcn_global_load_lds((const unsigned*)((const char*)(gbase) + (voff)[_i]), (PG8_LAS unsigned*)(lds + (bufoff) + ldsw + _i * 8192), 16, 0, 0); } while (0)
; #define PG8_LDA(dst, b, h) do { _Pragma("unroll") for (int m = 0; m < 4; ++m) _Pragma("unroll") for (int k = 0; k < 2; ++k) dst[m][k] = *(const PG8_LAS bf16x8*)(lds + PG8_SA(b, h) + aoff + m * 2048 + k * 1024); } while (0)
; #define PG8_LDB(dst, b, h) do { _Pragma("unroll") for (int n = 0; n < 2; ++n) _Pragma("unroll") for (int k = 0; k < 2; ++k) dst[n][k] = *(const PG8_LAS bf16x8*)(lds + PG8_SB(b, h) + boff + n * 2048 + k * 1024); } while (0)
; #define PG8_MMA(ai, bj, At, Bt) do { __builtin_amdgcn_s_setprio(1); _Pragma("unroll") for (int m = 0; m < 4; ++m) _Pragma("unroll") for (int n = 0; n < 2; ++n) _Pragma("unroll") for (int k = 0; k < 2; ++k) \
;         acc[ai][bj][m][n] = __builtin_amdgcn_mfma_f32_16x16x32_bf16(Bt[n][k], At[m][k], acc[ai][bj][m][n], 0, 0, 0); __builtin_amdgcn_s_setprio(0); } while (0)
; #define PG8_WAIT_V(n) asm volatile("s_waitcnt vmcnt(" #n ")" ::: "memory")
; #define PG8_WAIT_L(n) asm volatile("s_waitcnt lgkmcnt(" #n ")" ::: "memory")
; #define PG8_BAR __builtin_amdgcn_s_barrier()
; #define PG8_SCHED __builtin_amdgcn_sched_barrier(0)
; template <class Epi, class Sched, bool ALIGN_EPI = false, bool SP2 = false>
; __device__ __forceinline__ void gemm_phase(PG8_LAS unsigned char* lds, const Gemm g, const Sched& S, const Epi& E) {
;     ...
;             PG8_WAIT_V(8); PG8_WAIT_L(0); PG8_BAR; PG8_MMA(0, 0, At, B0); PG8_MMA(0, 1, At, B1); PG8_BAR; PG8_SCHED;
;             PG8_LDA(At, 0, 1); PG8_STAGE(PG8_SB(0, 0), b2, voffB); PG8_STAGE(PG8_SB(0, 1), b2 + hstep, voffB); PG8_STAGE(PG8_SA(0, 0), a2, voffA);
;             PG8_WAIT_V(8); PG8_WAIT_L(0); PG8_BAR; PG8_MMA(1, 0, At, B0); PG8_MMA(1, 1, At, B1); PG8_BAR; PG8_SCHED;
;             PG8_LDB(B0, 1, 0); PG8_LDB(B1, 1, 1); PG8_SCHED; PG8_LDA(At, 1, 0); PG8_STAGE(PG8_SA(0, 1), a2 + hstep, voffA);
;             PG8_WAIT_V(8); PG8_WAIT_L(0); PG8_BAR; PG8_MMA(0, 0, At, B0); PG8_MMA(0, 1, At, B1); PG8_BAR; PG8_SCHED;
	s_waitcnt lgkmcnt(0)
	v_mfma_f32_16x16x32_bf16 v[92:95], v[150:153], v[190:193], v[92:95]
	v_mfma_f32_16x16x32_bf16 v[88:91], v[158:161], v[190:193], v[88:91]
	v_mfma_f32_16x16x32_bf16 v[84:87], v[150:153], v[198:201], v[84:87]
	v_mfma_f32_16x16x32_bf16 v[80:83], v[158:161], v[198:201], v[80:83]
	v_mfma_f32_16x16x32_bf16 v[72:75], v[150:153], v[206:209], v[72:75]
	v_mfma_f32_16x16x32_bf16 v[64:67], v[158:161], v[206:209], v[64:67]
	v_mfma_f32_16x16x32_bf16 v[56:59], v[150:153], v[214:217], v[56:59]
	v_mfma_f32_16x16x32_bf16 v[48:51], v[158:161], v[214:217], v[48:51]
	v_mfma_f32_16x16x32_bf16 v[92:95], v[154:157], v[194:197], v[92:95]
	v_mfma_f32_16x16x32_bf16 v[88:91], v[162:165], v[194:197], v[88:91]
	v_mfma_f32_16x16x32_bf16 v[84:87], v[154:157], v[202:205], v[84:87]
	v_mfma_f32_16x16x32_bf16 v[80:83], v[162:165], v[202:205], v[80:83]
	v_mfma_f32_16x16x32_bf16 v[72:75], v[154:157], v[210:213], v[72:75]
	v_mfma_f32_16x16x32_bf16 v[64:67], v[162:165], v[210:213], v[64:67]
	v_mfma_f32_16x16x32_bf16 v[56:59], v[154:157], v[218:221], v[56:59]
	v_mfma_f32_16x16x32_bf16 v[48:51], v[162:165], v[218:221], v[48:51]
	v_mfma_f32_16x16x32_bf16 v[28:31], v[166:169], v[190:193], v[28:31]
	v_mfma_f32_16x16x32_bf16 v[24:27], v[174:177], v[190:193], v[24:27]
	v_mfma_f32_16x16x32_bf16 v[20:23], v[166:169], v[198:201], v[20:23]
	v_mfma_f32_16x16x32_bf16 v[16:19], v[174:177], v[198:201], v[16:19]
	v_mfma_f32_16x16x32_bf16 v[12:15], v[166:169], v[206:209], v[12:15]
	v_mfma_f32_16x16x32_bf16 v[8:11], v[174:177], v[206:209], v[8:11]
	v_mfma_f32_16x16x32_bf16 v[4:7], v[166:169], v[214:217], v[4:7]
	v_mfma_f32_16x16x32_bf16 v[0:3], v[174:177], v[214:217], v[0:3]
	v_mfma_f32_16x16x32_bf16 v[28:31], v[170:173], v[194:197], v[28:31]
	v_mfma_f32_16x16x32_bf16 v[24:27], v[178:181], v[194:197], v[24:27]
	v_mfma_f32_16x16x32_bf16 v[20:23], v[170:173], v[202:205], v[20:23]
	v_mfma_f32_16x16x32_bf16 v[16:19], v[178:181], v[202:205], v[16:19]
	v_mfma_f32_16x16x32_bf16 v[12:15], v[170:173], v[210:213], v[12:15]
	v_mfma_f32_16x16x32_bf16 v[8:11], v[178:181], v[210:213], v[8:11]
	v_mfma_f32_16x16x32_bf16 v[4:7], v[170:173], v[218:221], v[4:7]
	v_mfma_f32_16x16x32_bf16 v[0:3], v[178:181], v[218:221], v[0:3]
	s_barrier
	s_add_i32 s3, 0, 0x18000
	s_add_i32 s30, 0, 0x1c000
	v_add_u32_e32 v162, s3, v145
	v_add_u32_e32 v237, s3, v234
	v_add_u32_e32 v178, s30, v145
	v_add_u32_e32 v238, s30, v234
	ds_read_b128 v[150:153], v162
	ds_read_b128 v[154:157], v237
	ds_read_b128 v[158:161], v162 offset:2048
	ds_read_b128 v[162:165], v237 offset:2048
	ds_read_b128 v[166:169], v178
	ds_read_b128 v[170:173], v238
	ds_read_b128 v[174:177], v178 offset:2048
	ds_read_b128 v[178:181], v238 offset:2048
	s_add_u32 s10, s38, 0xb0000
	s_addc_u32 s11, s39, 0
	s_mov_b32 m0, s55
	v_lshl_add_u64 v[230:231], s[10:11], 0, v[128:129]
	ds_read_b128 v[190:193], v149 offset:32768
	ds_read_b128 v[194:197], v233 offset:32768
	ds_read_b128 v[198:201], v149 offset:34816
	ds_read_b128 v[202:205], v233 offset:34816
	ds_read_b128 v[206:209], v149 offset:36864
	ds_read_b128 v[210:213], v233 offset:36864
	ds_read_b128 v[214:217], v149 offset:38912
	ds_read_b128 v[218:221], v233 offset:38912
	global_load_lds_dwordx4 v[230:231], off
	v_lshl_add_u64 v[230:231], s[10:11], 0, v[132:133]
	s_mov_b32 m0, s56
	s_nop 0
	global_load_lds_dwordx4 v[230:231], off
	s_waitcnt vmcnt(8)
	s_waitcnt lgkmcnt(0)
	s_barrier
	s_waitcnt lgkmcnt(0)
	v_mfma_f32_16x16x32_bf16 v[124:127], v[150:153], v[190:193], v[124:127]
	v_mfma_f32_16x16x32_bf16 v[120:123], v[158:161], v[190:193], v[120:123]
	v_mfma_f32_16x16x32_bf16 v[116:119], v[150:153], v[198:201], v[116:119]
	v_mfma_f32_16x16x32_bf16 v[112:115], v[158:161], v[198:201], v[112:115]
	v_mfma_f32_16x16x32_bf16 v[108:111], v[150:153], v[206:209], v[108:111]
	v_mfma_f32_16x16x32_bf16 v[104:107], v[158:161], v[206:209], v[104:107]
	v_mfma_f32_16x16x32_bf16 v[100:103], v[150:153], v[214:217], v[100:103]
	v_mfma_f32_16x16x32_bf16 v[96:99], v[158:161], v[214:217], v[96:99]
	v_mfma_f32_16x16x32_bf16 v[124:127], v[154:157], v[194:197], v[124:127]
	v_mfma_f32_16x16x32_bf16 v[120:123], v[162:165], v[194:197], v[120:123]
	v_mfma_f32_16x16x32_bf16 v[116:119], v[154:157], v[202:205], v[116:119]
	v_mfma_f32_16x16x32_bf16 v[112:115], v[162:165], v[202:205], v[112:115]
	v_mfma_f32_16x16x32_bf16 v[108:111], v[154:157], v[210:213], v[108:111]
	v_mfma_f32_16x16x32_bf16 v[104:107], v[162:165], v[210:213], v[104:107]
	v_mfma_f32_16x16x32_bf16 v[100:103], v[154:157], v[218:221], v[100:103]
	v_mfma_f32_16x16x32_bf16 v[96:99], v[162:165], v[218:221], v[96:99]
	v_mfma_f32_16x16x32_bf16 v[76:79], v[166:169], v[190:193], v[76:79]
	v_mfma_f32_16x16x32_bf16 v[68:71], v[174:177], v[190:193], v[68:71]
	v_mfma_f32_16x16x32_bf16 v[60:63], v[166:169], v[198:201], v[60:63]
	v_mfma_f32_16x16x32_bf16 v[52:55], v[174:177], v[198:201], v[52:55]
	v_mfma_f32_16x16x32_bf16 v[44:47], v[166:169], v[206:209], v[44:47]
	v_mfma_f32_16x16x32_bf16 v[40:43], v[174:177], v[206:209], v[40:43]
	v_mfma_f32_16x16x32_bf16 v[36:39], v[166:169], v[214:217], v[36:39]
	v_mfma_f32_16x16x32_bf16 v[32:35], v[174:177], v[214:217], v[32:35]
	v_mfma_f32_16x16x32_bf16 v[76:79], v[170:173], v[194:197], v[76:79]
	v_mfma_f32_16x16x32_bf16 v[68:71], v[178:181], v[194:197], v[68:71]
	v_mfma_f32_16x16x32_bf16 v[60:63], v[170:173], v[202:205], v[60:63]
	v_mfma_f32_16x16x32_bf16 v[52:55], v[178:181], v[202:205], v[52:55]
	v_mfma_f32_16x16x32_bf16 v[44:47], v[170:173], v[210:213], v[44:47]
	v_mfma_f32_16x16x32_bf16 v[40:43], v[178:181], v[210:213], v[40:43]
	v_mfma_f32_16x16x32_bf16 v[36:39], v[170:173], v[218:221], v[36:39]
	v_mfma_f32_16x16x32_bf16 v[32:35], v[178:181], v[218:221], v[32:35]
	s_barrier
; #define PG8_STAGE(bufoff, gbase, voff) do { _Pragma("unroll") for (int _i = 0; _i < 2; ++_i) \
;         __builtin_amdgcn_global_load_lds((const unsigned*)((const char*)(gbase) + (voff)[_i]), (PG8_LAS unsigned*)(lds + (bufoff) + ldsw + _i * 8192), 16, 0, 0); } while (0)
; #define PG8_LDA(dst, b, h) do { _Pragma("unroll") for (int m = 0; m < 4; ++m) _Pragma("unroll") for (int k = 0; k < 2; ++k) dst[m][k] = *(const PG8_LAS bf16x8*)(lds + PG8_SA(b, h) + aoff + m * 2048 + k * 1024); } while (0)
; #define PG8_LDB(dst, b, h) do { _Pragma("unroll") for (int n = 0; n < 2; ++n) _Pragma("unroll") for (int k = 0; k < 2; ++k) dst[n][k] = *(const PG8_LAS bf16x8*)(lds + PG8_SB(b, h) + boff + n * 2048 + k * 1024); } while (0)
; #define PG8_MMA(ai, bj, At, Bt) do { __builtin_amdgcn_s_setprio(1); _Pragma("unroll") for (int m = 0; m < 4; ++m) _Pragma("unroll") for (int n = 0; n < 2; ++n) _Pragma("unroll") for (int k = 0; k < 2; ++k) \
;         acc[ai][bj][m][n] = __builtin_amdgcn_mfma_f32_16x16x32_bf16(Bt[n][k], At[m][k], acc[ai][bj][m][n], 0, 0, 0); __builtin_amdgcn_s_setprio(0); } while (0)
; #define PG8_WAIT_V(n) asm volatile("s_waitcnt vmcnt(" #n ")" ::: "memory")
; #define PG8_WAIT_L(n) asm volatile("s_waitcnt lgkmcnt(" #n ")" ::: "memory")
; #define PG8_BAR __builtin_amdgcn_s_barrier()
; #define PG8_SCHED __builtin_amdgcn_sched_barrier(0)
; template <class Epi, class Sched, bool ALIGN_EPI = false, bool SP2 = false>
; __device__ __forceinline__ void gemm_phase(PG8_LAS unsigned char* lds, const Gemm g, const Sched& S, const Epi& E) {
;     ...
;             PG8_LDB(B0, 1, 0); PG8_LDB(B1, 1, 1); PG8_SCHED; PG8_LDA(At, 1, 0); PG8_STAGE(PG8_SA(0, 1), a2 + hstep, voffA);
;             PG8_WAIT_V(8); PG8_WAIT_L(0); PG8_BAR; PG8_MMA(0, 0, At, B0); PG8_MMA(0, 1, At, B1); PG8_BAR; PG8_SCHED;
;             PG8_LDA(At, 1, 1); PG8_STAGE(PG8_SB(1, 0), b3, voffB); PG8_STAGE(PG8_SB(1, 1), b3 + hstep, voffB); PG8_STAGE(PG8_SA(1, 0), a3, voffA);
;             PG8_WAIT_V(8); PG8_WAIT_L(0); PG8_BAR; PG8_MMA(1, 0, At, B0); PG8_MMA(1, 1, At, B1); PG8_BAR; PG8_SCHED;
	s_add_i32 s3, s3, s52
	v_lshl_add_u64 v[222:223], v[222:223], 0, s[16:17]
	s_mov_b32 m0, s3
	ds_read_b128 v[190:193], v149 offset:49152
	ds_read_b128 v[194:197], v233 offset:49152
	ds_read_b128 v[198:201], v149 offset:51200
	ds_read_b128 v[202:205], v233 offset:51200
	ds_read_b128 v[206:209], v149 offset:53248
	ds_read_b128 v[210:213], v233 offset:53248
	ds_read_b128 v[214:217], v149 offset:55296
	ds_read_b128 v[218:221], v233 offset:55296
	global_load_lds_dwordx4 v[222:223], off
	s_add_i32 m0, s3, 0x2000
	s_add_u32 s10, s36, 0xb0080
	v_lshl_add_u64 v[222:223], v[224:225], 0, s[16:17]
	s_addc_u32 s11, s37, 0
	s_add_i32 s3, s30, s52
	global_load_lds_dwordx4 v[222:223], off
	v_lshl_add_u64 v[222:223], s[10:11], 0, v[130:131]
	s_mov_b32 m0, s3
	s_nop 0
	global_load_lds_dwordx4 v[222:223], off
	v_lshl_add_u64 v[222:223], s[10:11], 0, v[134:135]
	s_add_i32 m0, s3, 0x2000
	s_nop 0
	global_load_lds_dwordx4 v[222:223], off
	v_lshl_add_u64 v[222:223], v[226:227], 0, s[16:17]
	s_mov_b32 m0, s58
	s_nop 0
	global_load_lds_dwordx4 v[222:223], off
	v_lshl_add_u64 v[222:223], v[228:229], 0, s[16:17]
	s_mov_b32 m0, s59
	s_nop 0
	global_load_lds_dwordx4 v[222:223], off
	s_waitcnt vmcnt(8)
	s_waitcnt lgkmcnt(0)
	s_barrier
	s_waitcnt lgkmcnt(0)
	v_mfma_f32_16x16x32_bf16 v[92:95], v[150:153], v[190:193], v[92:95]
	v_mfma_f32_16x16x32_bf16 v[88:91], v[158:161], v[190:193], v[88:91]
	v_mfma_f32_16x16x32_bf16 v[84:87], v[150:153], v[198:201], v[84:87]
	v_mfma_f32_16x16x32_bf16 v[80:83], v[158:161], v[198:201], v[80:83]
	v_mfma_f32_16x16x32_bf16 v[72:75], v[150:153], v[206:209], v[72:75]
	v_mfma_f32_16x16x32_bf16 v[64:67], v[158:161], v[206:209], v[64:67]
	v_mfma_f32_16x16x32_bf16 v[56:59], v[150:153], v[214:217], v[56:59]
	v_mfma_f32_16x16x32_bf16 v[48:51], v[158:161], v[214:217], v[48:51]
	v_mfma_f32_16x16x32_bf16 v[92:95], v[154:157], v[194:197], v[92:95]
	v_mfma_f32_16x16x32_bf16 v[88:91], v[162:165], v[194:197], v[88:91]
	v_mfma_f32_16x16x32_bf16 v[84:87], v[154:157], v[202:205], v[84:87]
	v_mfma_f32_16x16x32_bf16 v[80:83], v[162:165], v[202:205], v[80:83]
	v_mfma_f32_16x16x32_bf16 v[72:75], v[154:157], v[210:213], v[72:75]
	v_mfma_f32_16x16x32_bf16 v[64:67], v[162:165], v[210:213], v[64:67]
	v_mfma_f32_16x16x32_bf16 v[56:59], v[154:157], v[218:221], v[56:59]
	v_mfma_f32_16x16x32_bf16 v[48:51], v[162:165], v[218:221], v[48:51]
	v_mfma_f32_16x16x32_bf16 v[28:31], v[166:169], v[190:193], v[28:31]
	v_mfma_f32_16x16x32_bf16 v[24:27], v[174:177], v[190:193], v[24:27]
	v_mfma_f32_16x16x32_bf16 v[20:23], v[166:169], v[198:201], v[20:23]
	v_mfma_f32_16x16x32_bf16 v[16:19], v[174:177], v[198:201], v[16:19]
	v_mfma_f32_16x16x32_bf16 v[12:15], v[166:169], v[206:209], v[12:15]
	v_mfma_f32_16x16x32_bf16 v[8:11], v[174:177], v[206:209], v[8:11]
	v_mfma_f32_16x16x32_bf16 v[4:7], v[166:169], v[214:217], v[4:7]
	v_mfma_f32_16x16x32_bf16 v[0:3], v[174:177], v[214:217], v[0:3]
	v_mfma_f32_16x16x32_bf16 v[28:31], v[170:173], v[194:197], v[28:31]
	v_mfma_f32_16x16x32_bf16 v[24:27], v[178:181], v[194:197], v[24:27]
	v_mfma_f32_16x16x32_bf16 v[20:23], v[170:173], v[202:205], v[20:23]
	v_mfma_f32_16x16x32_bf16 v[16:19], v[178:181], v[202:205], v[16:19]
	v_mfma_f32_16x16x32_bf16 v[12:15], v[170:173], v[210:213], v[12:15]
	v_mfma_f32_16x16x32_bf16 v[8:11], v[178:181], v[210:213], v[8:11]
	v_mfma_f32_16x16x32_bf16 v[4:7], v[170:173], v[218:221], v[4:7]
	v_mfma_f32_16x16x32_bf16 v[0:3], v[178:181], v[218:221], v[0:3]
	s_barrier
	s_add_i32 s74, s74, 2
	s_add_u32 s72, s72, 0x100
	s_addc_u32 s73, s73, 0
	s_cmp_gt_u32 s74, 41
	s_mov_b64 s[30:31], s[34:35]
	s_cbranch_scc0 .LBB0_303
	s_and_b64 vcc, exec, s[18:19]
	s_cbranch_vccz .LBB0_306
	s_barrier

; __device__ __forceinline__ int fresh_tid() { int t = (int)threadIdx.x; asm volatile("" : "+v"(t)); return t; }
; #define PG8_STAGE(bufoff, gbase, voff) do { _Pragma("unroll") for (int _i = 0; _i < 2; ++_i) \
;         __builtin_amdgcn_global_load_lds((const unsigned*)((const char*)(gbase) + (voff)[_i]), (PG8_LAS unsigned*)(lds + (bufoff) + ldsw + _i * 8192), 16, 0, 0); } while (0)
; template <class Epi, class Sched, bool ALIGN_EPI = false, bool SP2 = false>
; __device__ __forceinline__ void gemm_phase(PG8_LAS unsigned char* lds, const Gemm g, const Sched& S, const Epi& E) {
;     const int tid = fresh_tid(), wid = __builtin_amdgcn_readfirstlane(tid >> 6), lane = tid & 63, wr = wid >> 2, wc = wid & 3, fr = lane & 15, fq = lane >> 4;
;     const int K = g.K, nt = K / BK;
;     unsigned voffA[2], voffB[2];
; #pragma unroll
;     for (int i = 0; i < 2; ++i) { int R, C; stage_rc(tid * 16 + i * 8192, R, C); const int Rb = Epi::PERM ? ((R & ~31) + perm32(R & 31)) : R;
;         voffA[i] = (unsigned)(R * K + C) * 2u; voffB[i] = (unsigned)(Rb * K + C) * 2u; }
;     const size_t kstep = (size_t)(BK * 2);
;     const size_t hstep = (size_t)HALF * K * 2;
;     const size_t tstep = 2 * hstep;
;     const unsigned ldsw = (unsigned)wid * 1024u;
;     const int aoff = lds_byte(wr * 64 + fr, fq * 8), boff = lds_byte(wc * 32 + fr, fq * 8);
;     ...
;     const char* cA = (const char*)g.A + (size_t)cur.pm * tstep; const char* cB = (const char*)g.Bt + (size_t)cur.pn * tstep;
;     S.a_ready(cur);
;     if constexpr (SP2) {
;         PG8_STAGE(PG8_SB(0, 0), cB, voffB); PG8_STAGE(PG8_SB(0, 1), cB + hstep, voffB); PG8_STAGE(PG8_SA(0, 0), cA, voffA); PG8_STAGE(PG8_SA(0, 1), cA + hstep, voffA);
;         if (wr == 1) PG8_BAR;
;         PG8_WAIT_V(2); PG8_BAR;
;         PG8_STAGE(PG8_SB(1, 0), cB + kstep, voffB); PG8_STAGE(PG8_SA(1, 0), cA + kstep, voffA); PG8_STAGE(PG8_SB(1, 1), cB + hstep + kstep, voffB);
;         PG8_WAIT_V(6); PG8_BAR;
;     } else {
;         PG8_STAGE(PG8_SB(0, 0), cB, voffB); PG8_STAGE(PG8_SA(0, 0), cA, voffA); PG8_STAGE(PG8_SB(0, 1), cB + hstep, voffB); PG8_STAGE(PG8_SA(0, 1), cA + hstep, voffA);
;         if (wr == 1) PG8_BAR;
;         PG8_WAIT_V(4); PG8_BAR;
;         PG8_STAGE(PG8_SB(1, 0), cB + kstep, voffB); PG8_STAGE(PG8_SA(1, 0), cA + kstep, voffA); PG8_STAGE(PG8_SB(1, 1), cB + hstep + kstep, voffB);
;         PG8_WAIT_V(6); PG8_BAR;
.LBB0_485:
	s_andn2_b64 vcc, exec, s[14:15]
	s_cbranch_vccnz .LBB0_533
	v_ashrrev_i32_e32 v1, 31, v8
	v_lshrrev_b32_e32 v1, 26, v1
	v_add_u32_e32 v1, v8, v1
	v_ashrrev_i32_e32 v9, 6, v1
	v_bfe_i32 v1, v8, 27, 1
	v_lshlrev_b32_e32 v0, 4, v8
	v_lshrrev_b32_e32 v1, 22, v1
	v_add_u32_e32 v1, v0, v1
	v_and_b32_e32 v1, 0xfffffc00, v1
	v_sub_u32_e32 v1, v0, v1
	v_lshrrev_b32_e32 v2, 4, v1
	v_bitop3_b32 v2, v2, v1, 32 bitop3:0x6c
	v_ashrrev_i32_e32 v1, 31, v1
	v_lshrrev_b32_e32 v1, 26, v1
	v_add_u32_e32 v1, v2, v1
	v_ashrrev_i32_e32 v10, 6, v1
	s_load_dwordx2 s[0:1], s[10:11], 0x110
	s_load_dwordx2 s[14:15], s[12:13], 0x110
	v_lshlrev_b32_e32 v3, 3, v9
	v_mul_i32_i24_e32 v4, 64, v10
	v_and_b32_e32 v3, -16, v3
	v_sub_u32_e32 v2, v2, v4
	v_mov_b32_e32 v4, 1
	v_add_u32_e32 v1, v10, v3
	v_lshlrev_b32_e32 v3, 5, v9
	v_ashrrev_i16_sdwa v2, v4, sext(v2) dst_sel:DWORD dst_unused:UNUSED_PAD src0_sel:DWORD src1_sel:BYTE_0
	v_and_b32_e32 v3, 32, v3
	v_bfe_i32 v11, v2, 0, 16
	s_waitcnt lgkmcnt(0)
	s_add_u32 s38, s0, 0x3000000
	v_and_b32_e32 v6, 3, v10
	s_mov_b32 s0, 0x1fffe0
	v_add_lshl_u32 v3, v3, v11, 1
	v_add_u32_e32 v0, 0x2000, v0
	v_lshlrev_b32_e32 v2, 1, v1
	v_lshrrev_b32_e32 v5, 2, v1
	v_and_or_b32 v6, v1, s0, v6
	v_lshl_add_u32 v128, v1, 11, v3
	v_ashrrev_i32_e32 v1, 31, v0
	v_lshrrev_b32_e32 v1, 22, v1
	v_add_u32_e32 v1, v0, v1
	v_ashrrev_i32_e32 v12, 10, v1
	v_mul_i32_i24_e32 v1, 0x400, v12
	v_sub_u32_e32 v0, v0, v1
	v_and_b32_e32 v2, 24, v2
	v_and_b32_e32 v5, 4, v5
	v_lshrrev_b32_e32 v1, 4, v0
	v_or3_b32 v2, v6, v5, v2
	v_bitop3_b32 v0, v1, v0, 32 bitop3:0x6c
	v_lshl_add_u32 v130, v2, 11, v3
	v_ashrrev_i32_e32 v2, 31, v0
	v_lshrrev_b32_e32 v2, 26, v2
	v_add_u32_e32 v2, v0, v2
	s_addc_u32 s39, s1, 0
	v_lshlrev_b32_e32 v1, 3, v12
	v_ashrrev_i32_e32 v13, 6, v2
	v_and_b32_e32 v2, 0xc0, v2
	s_add_u32 s40, s14, 0x1200000
	v_and_b32_e32 v1, -16, v1
	v_sub_u32_e32 v0, v0, v2
	s_addc_u32 s41, s15, 0
	v_add_u32_e32 v1, v13, v1
	v_ashrrev_i16_sdwa v0, v4, sext(v0) dst_sel:DWORD dst_unused:UNUSED_PAD src0_sel:DWORD src1_sel:BYTE_0
	v_and_b32_e32 v4, 3, v13
	s_ashr_i32 s14, s16, 6
	s_ashr_i32 s27, s26, 31
	s_ashr_i32 s29, s28, 31
	s_ashr_i32 s17, s16, 8
	v_and_or_b32 v4, v1, s0, v4
	s_lshl_b32 s42, s14, 10
	s_lshl_b64 s[0:1], s[26:27], 19
	s_lshl_b64 s[10:11], s[28:29], 19
	s_add_u32 s34, s40, s10
	v_lshlrev_b32_e32 v3, 5, v12
	v_bfe_i32 v14, v0, 0, 16
	v_lshlrev_b32_e32 v0, 1, v1
	v_lshrrev_b32_e32 v2, 2, v1
	s_addc_u32 s35, s41, s11
	s_add_i32 s43, s42, 0
	v_and_b32_e32 v3, 32, v3
	v_and_b32_e32 v0, 24, v0
	v_and_b32_e32 v2, 4, v2
	s_add_i32 m0, s43, 0x10000
	v_or3_b32 v0, v4, v2, v0
	v_add_lshl_u32 v2, v3, v14, 1
	v_readfirstlane_b32 vcc_lo, v8
	s_nop 3
	s_lshr_b32 vcc_lo, vcc_lo, 8
	s_cmp_eq_u32 vcc_lo, 0
	s_cbranch_scc0 .Lmy_prio_2
	s_setprio 1
.Lmy_prio_2:
	v_bfe_u32 v239, v8, 3, 3
	v_and_b32_e32 v240, 7, v8
	v_xor_b32_e32 v240, v240, v239
	v_lshlrev_b32_e32 v240, 4, v240
	v_lshrrev_b32_e32 v241, 6, v8
	v_lshl_add_u32 v242, v241, 3, v239
	v_mov_b32_e32 v243, 0x800
	v_mad_u32_u24 v128, v242, v243, v240
	v_add_u32_e32 v132, 0x20000, v128
	v_lshrrev_b32_e32 v244, 2, v241
	v_lshlrev_b32_e32 v244, 5, v244
	v_and_b32_e32 v245, 1, v241
	v_lshrrev_b32_e32 v246, 2, v239
	v_lshl_add_u32 v245, v245, 1, v246
	v_lshl_add_u32 v244, v245, 3, v244
	v_bfe_u32 v245, v241, 1, 1
	v_lshl_add_u32 v244, v245, 2, v244
	v_and_b32_e32 v245, 3, v239
	v_add_u32_e32 v244, v244, v245
	v_mad_u32_u24 v130, v244, v243, v240
	v_add_u32_e32 v134, 0x20000, v130
	global_load_lds_dwordx4 v130, s[34:35]
	s_add_i32 m0, s43, 0x12000
	s_add_u32 s10, s34, 0x40000
	global_load_lds_dwordx4 v134, s[34:35]
	s_addc_u32 s11, s35, 0
	s_add_i32 m0, s43, 0x14000
	global_load_lds_dwordx4 v130, s[10:11]
	s_add_i32 m0, s43, 0x16000
	s_add_u32 s30, s38, s0
	s_addc_u32 s31, s39, s1
	s_add_i32 s47, s43, 0x2000
	global_load_lds_dwordx4 v134, s[10:11]
	s_mov_b32 m0, s43
	s_add_u32 s0, s30, 0x40000
	global_load_lds_dwordx4 v128, s[30:31]
	s_mov_b32 m0, s47
	s_addc_u32 s1, s31, 0
	s_add_i32 s52, s43, 0x4000
	global_load_lds_dwordx4 v132, s[30:31]
	s_mov_b32 m0, s52
	s_add_i32 s53, s43, 0x6000
	global_load_lds_dwordx4 v128, s[0:1]
	s_mov_b32 m0, s53
	s_load_dwordx2 s[8:9], s[8:9], 0x110
	global_load_lds_dwordx4 v132, s[0:1]
	v_mov_b32_e32 v131, 0
	v_mov_b32_e32 v135, v131
	v_mov_b32_e32 v129, v131
	v_mov_b32_e32 v133, v131
	s_cmp_eq_u32 s17, 1
	s_movk_i32 s54, 0x400
	s_mov_b32 s55, 0
	v_lshl_add_u64 v[6:7], s[34:35], 0, v[130:131]
	v_lshl_add_u64 v[4:5], s[34:35], 0, v[134:135]
	v_lshl_add_u64 v[0:1], s[30:31], 0, v[128:129]
	s_cselect_b64 s[10:11], -1, 0
	s_cmp_lg_u32 s17, 1
	v_lshl_add_u64 v[2:3], s[30:31], 0, v[132:133]
	s_cbranch_scc1 .LBB0_488
	s_barrier

; #define PG8_STAGE(bufoff, gbase, voff) do { _Pragma("unroll") for (int _i = 0; _i < 2; ++_i) \
;         __builtin_amdgcn_global_load_lds((const unsigned*)((const char*)(gbase) + (voff)[_i]), (PG8_LAS unsigned*)(lds + (bufoff) + ldsw + _i * 8192), 16, 0, 0); } while (0)
; #define PG8_LDA(dst, b, h) do { _Pragma("unroll") for (int m = 0; m < 4; ++m) _Pragma("unroll") for (int k = 0; k < 2; ++k) dst[m][k] = *(const PG8_LAS bf16x8*)(lds + PG8_SA(b, h) + aoff + m * 2048 + k * 1024); } while (0)
; #define PG8_LDB(dst, b, h) do { _Pragma("unroll") for (int n = 0; n < 2; ++n) _Pragma("unroll") for (int k = 0; k < 2; ++k) dst[n][k] = *(const PG8_LAS bf16x8*)(lds + PG8_SB(b, h) + boff + n * 2048 + k * 1024); } while (0)
; #define PG8_MMA(ai, bj, At, Bt) do { __builtin_amdgcn_s_setprio(1); _Pragma("unroll") for (int m = 0; m < 4; ++m) _Pragma("unroll") for (int n = 0; n < 2; ++n) _Pragma("unroll") for (int k = 0; k < 2; ++k) \
;         acc[ai][bj][m][n] = __builtin_amdgcn_mfma_f32_16x16x32_bf16(Bt[n][k], At[m][k], acc[ai][bj][m][n], 0, 0, 0); __builtin_amdgcn_s_setprio(0); } while (0)
; #define PG8_WAIT_V(n) asm volatile("s_waitcnt vmcnt(" #n ")" ::: "memory")
; #define PG8_WAIT_L(n) asm volatile("s_waitcnt lgkmcnt(" #n ")" ::: "memory")
; #define PG8_BAR __builtin_amdgcn_s_barrier()
; #define PG8_SCHED __builtin_amdgcn_sched_barrier(0)
; template <class Epi, class Sched, bool ALIGN_EPI = false, bool SP2 = false>
; __device__ __forceinline__ void gemm_phase(PG8_LAS unsigned char* lds, const Gemm g, const Sched& S, const Epi& E) {
;     ...
;             if constexpr (SP2) {
;             PG8_LDB(B0, 0, 0); PG8_LDB(B1, 0, 1); PG8_SCHED; PG8_LDA(At, 0, 0); PG8_STAGE(PG8_SA(1, 1), a1 + hstep, voffA);
;             PG8_WAIT_V(8); PG8_WAIT_L(0); PG8_BAR; PG8_MMA(0, 0, At, B0); PG8_MMA(0, 1, At, B1); PG8_BAR; PG8_SCHED;
;             PG8_LDA(At, 0, 1); PG8_STAGE(PG8_SB(0, 0), b2, voffB); PG8_STAGE(PG8_SB(0, 1), b2 + hstep, voffB); PG8_STAGE(PG8_SA(0, 0), a2, voffA);
;             PG8_WAIT_V(8); PG8_WAIT_L(0); PG8_BAR; PG8_MMA(1, 0, At, B0); PG8_MMA(1, 1, At, B1); PG8_BAR; PG8_SCHED;
.LBB0_494:
	ds_read_b128 v[152:155], v149
	ds_read_b128 v[156:159], v235
	ds_read_b128 v[160:163], v149 offset:2048
	ds_read_b128 v[164:167], v235 offset:2048
	ds_read_b128 v[168:171], v150
	ds_read_b128 v[172:175], v236
	ds_read_b128 v[176:179], v150 offset:2048
	ds_read_b128 v[190:193], v236 offset:2048
	s_add_u32 s0, s30, 0xfffc0080
	s_addc_u32 s1, s31, -1
	s_cmp_eq_u32 s67, 12
	s_cselect_b32 s37, s21, s1
	s_cselect_b32 s36, s27, s0
	s_cselect_b32 s35, s19, s66
	s_cselect_b32 s34, s29, s65
	v_lshl_add_u64 v[144:145], s[30:31], 0, v[136:137]
	s_add_i32 m0, s43, 0xc000
	ds_read_b128 v[194:197], v151
	ds_read_b128 v[198:201], v233
	ds_read_b128 v[202:205], v151 offset:2048
	ds_read_b128 v[206:209], v233 offset:2048
	ds_read_b128 v[210:213], v151 offset:4096
	ds_read_b128 v[214:217], v233 offset:4096
	ds_read_b128 v[218:221], v151 offset:6144
	ds_read_b128 v[222:225], v233 offset:6144
	global_load_lds_dwordx4 v[144:145], off
	v_lshl_add_u64 v[144:145], s[30:31], 0, v[138:139]
	s_add_i32 m0, s43, 0xe000
	s_nop 0
	global_load_lds_dwordx4 v[144:145], off
	s_waitcnt vmcnt(8)
	s_waitcnt lgkmcnt(0)
	s_barrier
	s_waitcnt lgkmcnt(0)
	v_mfma_f32_16x16x32_bf16 v[124:127], v[152:155], v[194:197], v[124:127]
	v_mfma_f32_16x16x32_bf16 v[120:123], v[160:163], v[194:197], v[120:123]
	v_mfma_f32_16x16x32_bf16 v[116:119], v[152:155], v[202:205], v[116:119]
	v_mfma_f32_16x16x32_bf16 v[112:115], v[160:163], v[202:205], v[112:115]
	v_mfma_f32_16x16x32_bf16 v[108:111], v[152:155], v[210:213], v[108:111]
	v_mfma_f32_16x16x32_bf16 v[104:107], v[160:163], v[210:213], v[104:107]
	v_mfma_f32_16x16x32_bf16 v[100:103], v[152:155], v[218:221], v[100:103]
	v_mfma_f32_16x16x32_bf16 v[96:99], v[160:163], v[218:221], v[96:99]
	v_mfma_f32_16x16x32_bf16 v[124:127], v[156:159], v[198:201], v[124:127]
	v_mfma_f32_16x16x32_bf16 v[120:123], v[164:167], v[198:201], v[120:123]
	v_mfma_f32_16x16x32_bf16 v[116:119], v[156:159], v[206:209], v[116:119]
	v_mfma_f32_16x16x32_bf16 v[112:115], v[164:167], v[206:209], v[112:115]
	v_mfma_f32_16x16x32_bf16 v[108:111], v[156:159], v[214:217], v[108:111]
	v_mfma_f32_16x16x32_bf16 v[104:107], v[164:167], v[214:217], v[104:107]
	v_mfma_f32_16x16x32_bf16 v[100:103], v[156:159], v[222:225], v[100:103]
	v_mfma_f32_16x16x32_bf16 v[96:99], v[164:167], v[222:225], v[96:99]
	v_mfma_f32_16x16x32_bf16 v[60:63], v[168:171], v[194:197], v[60:63]
	v_mfma_f32_16x16x32_bf16 v[56:59], v[176:179], v[194:197], v[56:59]
	v_mfma_f32_16x16x32_bf16 v[52:55], v[168:171], v[202:205], v[52:55]
	v_mfma_f32_16x16x32_bf16 v[48:51], v[176:179], v[202:205], v[48:51]
	v_mfma_f32_16x16x32_bf16 v[44:47], v[168:171], v[210:213], v[44:47]
	v_mfma_f32_16x16x32_bf16 v[40:43], v[176:179], v[210:213], v[40:43]
	v_mfma_f32_16x16x32_bf16 v[36:39], v[168:171], v[218:221], v[36:39]
	v_mfma_f32_16x16x32_bf16 v[32:35], v[176:179], v[218:221], v[32:35]
	v_mfma_f32_16x16x32_bf16 v[60:63], v[172:175], v[198:201], v[60:63]
	v_mfma_f32_16x16x32_bf16 v[56:59], v[190:193], v[198:201], v[56:59]
	v_mfma_f32_16x16x32_bf16 v[52:55], v[172:175], v[206:209], v[52:55]
	v_mfma_f32_16x16x32_bf16 v[48:51], v[190:193], v[206:209], v[48:51]
	v_mfma_f32_16x16x32_bf16 v[44:47], v[172:175], v[214:217], v[44:47]
	v_mfma_f32_16x16x32_bf16 v[40:43], v[190:193], v[214:217], v[40:43]
	v_mfma_f32_16x16x32_bf16 v[36:39], v[172:175], v[222:225], v[36:39]
	v_mfma_f32_16x16x32_bf16 v[32:35], v[190:193], v[222:225], v[32:35]
	s_barrier
	s_add_i32 s0, s62, s42
	v_lshl_add_u64 v[144:145], s[34:35], 0, v[130:131]
	s_mov_b32 m0, s0
	ds_read_b128 v[194:197], v151 offset:16384
	ds_read_b128 v[198:201], v233 offset:16384
	ds_read_b128 v[202:205], v151 offset:18432
	ds_read_b128 v[206:209], v233 offset:18432
	ds_read_b128 v[210:213], v151 offset:20480
	ds_read_b128 v[214:217], v233 offset:20480
	ds_read_b128 v[218:221], v151 offset:22528
	ds_read_b128 v[222:225], v233 offset:22528
	global_load_lds_dwordx4 v[144:145], off
	s_add_i32 m0, s0, 0x2000
	s_add_u32 s0, s34, 0x40000
	v_lshl_add_u64 v[180:181], s[34:35], 0, v[134:135]
	s_addc_u32 s1, s35, 0
	s_add_i32 s3, s63, s42
	global_load_lds_dwordx4 v[180:181], off
	v_lshl_add_u64 v[226:227], s[0:1], 0, v[130:131]
	s_mov_b32 m0, s3
	v_lshl_add_u64 v[228:229], s[36:37], 0, v[132:133]
	global_load_lds_dwordx4 v[226:227], off
	v_lshl_add_u64 v[226:227], s[0:1], 0, v[134:135]
	s_add_i32 m0, s3, 0x2000
	s_nop 0
	global_load_lds_dwordx4 v[226:227], off
	v_lshl_add_u64 v[226:227], s[36:37], 0, v[128:129]
	s_mov_b32 m0, s43
	s_nop 0
	global_load_lds_dwordx4 v[226:227], off
	s_mov_b32 m0, s47
	s_nop 0
	global_load_lds_dwordx4 v[228:229], off
	s_waitcnt vmcnt(8)
	s_waitcnt lgkmcnt(0)
	s_barrier
; #define PG8_STAGE(bufoff, gbase, voff) do { _Pragma("unroll") for (int _i = 0; _i < 2; ++_i) \
;         __builtin_amdgcn_global_load_lds((const unsigned*)((const char*)(gbase) + (voff)[_i]), (PG8_LAS unsigned*)(lds + (bufoff) + ldsw + _i * 8192), 16, 0, 0); } while (0)
; #define PG8_LDA(dst, b, h) do { _Pragma("unroll") for (int m = 0; m < 4; ++m) _Pragma("unroll") for (int k = 0; k < 2; ++k) dst[m][k] = *(const PG8_LAS bf16x8*)(lds + PG8_SA(b, h) + aoff + m * 2048 + k * 1024); } while (0)
; #define PG8_LDB(dst, b, h) do { _Pragma("unroll") for (int n = 0; n < 2; ++n) _Pragma("unroll") for (int k = 0; k < 2; ++k) dst[n][k] = *(const PG8_LAS bf16x8*)(lds + PG8_SB(b, h) + boff + n * 2048 + k * 1024); } while (0)
; #define PG8_MMA(ai, bj, At, Bt) do { __builtin_amdgcn_s_setprio(1); _Pragma("unroll") for (int m = 0; m < 4; ++m) _Pragma("unroll") for (int n = 0; n < 2; ++n) _Pragma("unroll") for (int k = 0; k < 2; ++k) \
;         acc[ai][bj][m][n] = __builtin_amdgcn_mfma_f32_16x16x32_bf16(Bt[n][k], At[m][k], acc[ai][bj][m][n], 0, 0, 0); __builtin_amdgcn_s_setprio(0); } while (0)
; #define PG8_WAIT_V(n) asm volatile("s_waitcnt vmcnt(" #n ")" ::: "memory")
; #define PG8_WAIT_L(n) asm volatile("s_waitcnt lgkmcnt(" #n ")" ::: "memory")
; #define PG8_BAR __builtin_amdgcn_s_barrier()
; #define PG8_SCHED __builtin_amdgcn_sched_barrier(0)
; template <class Epi, class Sched, bool ALIGN_EPI = false, bool SP2 = false>
; __device__ __forceinline__ void gemm_phase(PG8_LAS unsigned char* lds, const Gemm g, const Sched& S, const Epi& E) {
;     ...
;             PG8_WAIT_V(8); PG8_WAIT_L(0); PG8_BAR; PG8_MMA(0, 0, At, B0); PG8_MMA(0, 1, At, B1); PG8_BAR; PG8_SCHED;
;             PG8_LDA(At, 0, 1); PG8_STAGE(PG8_SB(0, 0), b2, voffB); PG8_STAGE(PG8_SB(0, 1), b2 + hstep, voffB); PG8_STAGE(PG8_SA(0, 0), a2, voffA);
;             PG8_WAIT_V(8); PG8_WAIT_L(0); PG8_BAR; PG8_MMA(1, 0, At, B0); PG8_MMA(1, 1, At, B1); PG8_BAR; PG8_SCHED;
;             PG8_LDB(B0, 1, 0); PG8_LDB(B1, 1, 1); PG8_SCHED; PG8_LDA(At, 1, 0); PG8_STAGE(PG8_SA(0, 1), a2 + hstep, voffA);
;             PG8_WAIT_V(8); PG8_WAIT_L(0); PG8_BAR; PG8_MMA(0, 0, At, B0); PG8_MMA(0, 1, At, B1); PG8_BAR; PG8_SCHED;
	s_waitcnt lgkmcnt(0)
	v_mfma_f32_16x16x32_bf16 v[92:95], v[152:155], v[194:197], v[92:95]
	v_mfma_f32_16x16x32_bf16 v[88:91], v[160:163], v[194:197], v[88:91]
	v_mfma_f32_16x16x32_bf16 v[84:87], v[152:155], v[202:205], v[84:87]
	v_mfma_f32_16x16x32_bf16 v[80:83], v[160:163], v[202:205], v[80:83]
	v_mfma_f32_16x16x32_bf16 v[76:79], v[152:155], v[210:213], v[76:79]
	v_mfma_f32_16x16x32_bf16 v[72:75], v[160:163], v[210:213], v[72:75]
	v_mfma_f32_16x16x32_bf16 v[68:71], v[152:155], v[218:221], v[68:71]
	v_mfma_f32_16x16x32_bf16 v[64:67], v[160:163], v[218:221], v[64:67]
	v_mfma_f32_16x16x32_bf16 v[92:95], v[156:159], v[198:201], v[92:95]
	v_mfma_f32_16x16x32_bf16 v[88:91], v[164:167], v[198:201], v[88:91]
	v_mfma_f32_16x16x32_bf16 v[84:87], v[156:159], v[206:209], v[84:87]
	v_mfma_f32_16x16x32_bf16 v[80:83], v[164:167], v[206:209], v[80:83]
	v_mfma_f32_16x16x32_bf16 v[76:79], v[156:159], v[214:217], v[76:79]
	v_mfma_f32_16x16x32_bf16 v[72:75], v[164:167], v[214:217], v[72:75]
	v_mfma_f32_16x16x32_bf16 v[68:71], v[156:159], v[222:225], v[68:71]
	v_mfma_f32_16x16x32_bf16 v[64:67], v[164:167], v[222:225], v[64:67]
	v_mfma_f32_16x16x32_bf16 v[28:31], v[168:171], v[194:197], v[28:31]
	v_mfma_f32_16x16x32_bf16 v[24:27], v[176:179], v[194:197], v[24:27]
	v_mfma_f32_16x16x32_bf16 v[20:23], v[168:171], v[202:205], v[20:23]
	v_mfma_f32_16x16x32_bf16 v[16:19], v[176:179], v[202:205], v[16:19]
	v_mfma_f32_16x16x32_bf16 v[12:15], v[168:171], v[210:213], v[12:15]
	v_mfma_f32_16x16x32_bf16 v[8:11], v[176:179], v[210:213], v[8:11]
	v_mfma_f32_16x16x32_bf16 v[4:7], v[168:171], v[218:221], v[4:7]
	v_mfma_f32_16x16x32_bf16 v[0:3], v[176:179], v[218:221], v[0:3]
	v_mfma_f32_16x16x32_bf16 v[28:31], v[172:175], v[198:201], v[28:31]
	v_mfma_f32_16x16x32_bf16 v[24:27], v[190:193], v[198:201], v[24:27]
	v_mfma_f32_16x16x32_bf16 v[20:23], v[172:175], v[206:209], v[20:23]
	v_mfma_f32_16x16x32_bf16 v[16:19], v[190:193], v[206:209], v[16:19]
	v_mfma_f32_16x16x32_bf16 v[12:15], v[172:175], v[214:217], v[12:15]
	v_mfma_f32_16x16x32_bf16 v[8:11], v[190:193], v[214:217], v[8:11]
	v_mfma_f32_16x16x32_bf16 v[4:7], v[172:175], v[222:225], v[4:7]
	v_mfma_f32_16x16x32_bf16 v[0:3], v[190:193], v[222:225], v[0:3]
	s_barrier
	s_add_i32 s3, 0, 0x18000
	s_add_i32 s45, 0, 0x1c000
	v_add_u32_e32 v164, s3, v147
	v_add_u32_e32 v237, s3, v234
	v_add_u32_e32 v189, s45, v147
	v_add_u32_e32 v238, s45, v234
	ds_read_b128 v[152:155], v164
	ds_read_b128 v[156:159], v237
	ds_read_b128 v[160:163], v164 offset:2048
	ds_read_b128 v[164:167], v237 offset:2048
	ds_read_b128 v[168:171], v189
	ds_read_b128 v[172:175], v238
	ds_read_b128 v[176:179], v189 offset:2048
	ds_read_b128 v[190:193], v238 offset:2048
	s_add_u32 s0, s36, 0x40000
	s_addc_u32 s1, s37, 0
	s_mov_b32 m0, s52
	v_lshl_add_u64 v[230:231], s[0:1], 0, v[128:129]
	ds_read_b128 v[194:197], v151 offset:32768
	ds_read_b128 v[198:201], v233 offset:32768
	ds_read_b128 v[202:205], v151 offset:34816
	ds_read_b128 v[206:209], v233 offset:34816
	ds_read_b128 v[210:213], v151 offset:36864
	ds_read_b128 v[214:217], v233 offset:36864
	ds_read_b128 v[218:221], v151 offset:38912
	ds_read_b128 v[222:225], v233 offset:38912
	global_load_lds_dwordx4 v[230:231], off
	v_lshl_add_u64 v[230:231], s[0:1], 0, v[132:133]
	s_mov_b32 m0, s53
	s_nop 0
	global_load_lds_dwordx4 v[230:231], off
	s_waitcnt vmcnt(8)
	s_waitcnt lgkmcnt(0)
	s_barrier
	s_waitcnt lgkmcnt(0)
	v_mfma_f32_16x16x32_bf16 v[124:127], v[152:155], v[194:197], v[124:127]
	v_mfma_f32_16x16x32_bf16 v[120:123], v[160:163], v[194:197], v[120:123]
	v_mfma_f32_16x16x32_bf16 v[116:119], v[152:155], v[202:205], v[116:119]
	v_mfma_f32_16x16x32_bf16 v[112:115], v[160:163], v[202:205], v[112:115]
	v_mfma_f32_16x16x32_bf16 v[108:111], v[152:155], v[210:213], v[108:111]
	v_mfma_f32_16x16x32_bf16 v[104:107], v[160:163], v[210:213], v[104:107]
	v_mfma_f32_16x16x32_bf16 v[100:103], v[152:155], v[218:221], v[100:103]
	v_mfma_f32_16x16x32_bf16 v[96:99], v[160:163], v[218:221], v[96:99]
	v_mfma_f32_16x16x32_bf16 v[124:127], v[156:159], v[198:201], v[124:127]
	v_mfma_f32_16x16x32_bf16 v[120:123], v[164:167], v[198:201], v[120:123]
	v_mfma_f32_16x16x32_bf16 v[116:119], v[156:159], v[206:209], v[116:119]
	v_mfma_f32_16x16x32_bf16 v[112:115], v[164:167], v[206:209], v[112:115]
	v_mfma_f32_16x16x32_bf16 v[108:111], v[156:159], v[214:217], v[108:111]
	v_mfma_f32_16x16x32_bf16 v[104:107], v[164:167], v[214:217], v[104:107]
	v_mfma_f32_16x16x32_bf16 v[100:103], v[156:159], v[222:225], v[100:103]
	v_mfma_f32_16x16x32_bf16 v[96:99], v[164:167], v[222:225], v[96:99]
	v_mfma_f32_16x16x32_bf16 v[60:63], v[168:171], v[194:197], v[60:63]
	v_mfma_f32_16x16x32_bf16 v[56:59], v[176:179], v[194:197], v[56:59]
	v_mfma_f32_16x16x32_bf16 v[52:55], v[168:171], v[202:205], v[52:55]
	v_mfma_f32_16x16x32_bf16 v[48:51], v[176:179], v[202:205], v[48:51]
	v_mfma_f32_16x16x32_bf16 v[44:47], v[168:171], v[210:213], v[44:47]
	v_mfma_f32_16x16x32_bf16 v[40:43], v[176:179], v[210:213], v[40:43]
	v_mfma_f32_16x16x32_bf16 v[36:39], v[168:171], v[218:221], v[36:39]
	v_mfma_f32_16x16x32_bf16 v[32:35], v[176:179], v[218:221], v[32:35]
	v_mfma_f32_16x16x32_bf16 v[60:63], v[172:175], v[198:201], v[60:63]
	v_mfma_f32_16x16x32_bf16 v[56:59], v[190:193], v[198:201], v[56:59]
	v_mfma_f32_16x16x32_bf16 v[52:55], v[172:175], v[206:209], v[52:55]
	v_mfma_f32_16x16x32_bf16 v[48:51], v[190:193], v[206:209], v[48:51]
	v_mfma_f32_16x16x32_bf16 v[44:47], v[172:175], v[214:217], v[44:47]
	v_mfma_f32_16x16x32_bf16 v[40:43], v[190:193], v[214:217], v[40:43]
	v_mfma_f32_16x16x32_bf16 v[36:39], v[172:175], v[222:225], v[36:39]
	v_mfma_f32_16x16x32_bf16 v[32:35], v[190:193], v[222:225], v[32:35]
	s_barrier
; #define PG8_STAGE(bufoff, gbase, voff) do { _Pragma("unroll") for (int _i = 0; _i < 2; ++_i) \
;         __builtin_amdgcn_global_load_lds((const unsigned*)((const char*)(gbase) + (voff)[_i]), (PG8_LAS unsigned*)(lds + (bufoff) + ldsw + _i * 8192), 16, 0, 0); } while (0)
; #define PG8_LDA(dst, b, h) do { _Pragma("unroll") for (int m = 0; m < 4; ++m) _Pragma("unroll") for (int k = 0; k < 2; ++k) dst[m][k] = *(const PG8_LAS bf16x8*)(lds + PG8_SA(b, h) + aoff + m * 2048 + k * 1024); } while (0)
; #define PG8_LDB(dst, b, h) do { _Pragma("unroll") for (int n = 0; n < 2; ++n) _Pragma("unroll") for (int k = 0; k < 2; ++k) dst[n][k] = *(const PG8_LAS bf16x8*)(lds + PG8_SB(b, h) + boff + n * 2048 + k * 1024); } while (0)
; #define PG8_MMA(ai, bj, At, Bt) do { __builtin_amdgcn_s_setprio(1); _Pragma("unroll") for (int m = 0; m < 4; ++m) _Pragma("unroll") for (int n = 0; n < 2; ++n) _Pragma("unroll") for (int k = 0; k < 2; ++k) \
;         acc[ai][bj][m][n] = __builtin_amdgcn_mfma_f32_16x16x32_bf16(Bt[n][k], At[m][k], acc[ai][bj][m][n], 0, 0, 0); __builtin_amdgcn_s_setprio(0); } while (0)
; #define PG8_WAIT_V(n) asm volatile("s_waitcnt vmcnt(" #n ")" ::: "memory")
; #define PG8_WAIT_L(n) asm volatile("s_waitcnt lgkmcnt(" #n ")" ::: "memory")
; #define PG8_BAR __builtin_amdgcn_s_barrier()
; #define PG8_SCHED __builtin_amdgcn_sched_barrier(0)
; template <class Epi, class Sched, bool ALIGN_EPI = false, bool SP2 = false>
; __device__ __forceinline__ void gemm_phase(PG8_LAS unsigned char* lds, const Gemm g, const Sched& S, const Epi& E) {
;     ...
;             PG8_LDB(B0, 1, 0); PG8_LDB(B1, 1, 1); PG8_SCHED; PG8_LDA(At, 1, 0); PG8_STAGE(PG8_SA(0, 1), a2 + hstep, voffA);
;             PG8_WAIT_V(8); PG8_WAIT_L(0); PG8_BAR; PG8_MMA(0, 0, At, B0); PG8_MMA(0, 1, At, B1); PG8_BAR; PG8_SCHED;
;             PG8_LDA(At, 1, 1); PG8_STAGE(PG8_SB(1, 0), b3, voffB); PG8_STAGE(PG8_SB(1, 1), b3 + hstep, voffB); PG8_STAGE(PG8_SA(1, 0), a3, voffA);
;             PG8_WAIT_V(8); PG8_WAIT_L(0); PG8_BAR; PG8_MMA(1, 0, At, B0); PG8_MMA(1, 1, At, B1); PG8_BAR; PG8_SCHED;
	s_add_i32 s0, s3, s42
	v_lshl_add_u64 v[144:145], v[144:145], 0, s[14:15]
	s_mov_b32 m0, s0
	ds_read_b128 v[194:197], v151 offset:49152
	ds_read_b128 v[198:201], v233 offset:49152
	ds_read_b128 v[202:205], v151 offset:51200
	ds_read_b128 v[206:209], v233 offset:51200
	ds_read_b128 v[210:213], v151 offset:53248
	ds_read_b128 v[214:217], v233 offset:53248
	ds_read_b128 v[218:221], v151 offset:55296
	ds_read_b128 v[222:225], v233 offset:55296
	global_load_lds_dwordx4 v[144:145], off
	s_add_i32 m0, s0, 0x2000
	s_add_u32 s0, s34, 0x40080
	v_lshl_add_u64 v[144:145], v[180:181], 0, s[14:15]
	s_addc_u32 s1, s35, 0
	s_add_i32 s3, s45, s42
	global_load_lds_dwordx4 v[144:145], off
	v_lshl_add_u64 v[144:145], s[0:1], 0, v[130:131]
	s_mov_b32 m0, s3
	s_nop 0
	global_load_lds_dwordx4 v[144:145], off
	v_lshl_add_u64 v[144:145], s[0:1], 0, v[134:135]
	s_add_i32 m0, s3, 0x2000
	s_nop 0
	global_load_lds_dwordx4 v[144:145], off
	v_lshl_add_u64 v[144:145], v[226:227], 0, s[14:15]
	s_mov_b32 m0, s56
	s_nop 0
	global_load_lds_dwordx4 v[144:145], off
	v_lshl_add_u64 v[144:145], v[228:229], 0, s[14:15]
	s_mov_b32 m0, s57
	s_nop 0
	global_load_lds_dwordx4 v[144:145], off
	s_waitcnt vmcnt(8)
	s_waitcnt lgkmcnt(0)
	s_barrier
	s_waitcnt lgkmcnt(0)
	v_mfma_f32_16x16x32_bf16 v[92:95], v[152:155], v[194:197], v[92:95]
	v_mfma_f32_16x16x32_bf16 v[88:91], v[160:163], v[194:197], v[88:91]
	v_mfma_f32_16x16x32_bf16 v[84:87], v[152:155], v[202:205], v[84:87]
	v_mfma_f32_16x16x32_bf16 v[80:83], v[160:163], v[202:205], v[80:83]
	v_mfma_f32_16x16x32_bf16 v[76:79], v[152:155], v[210:213], v[76:79]
	v_mfma_f32_16x16x32_bf16 v[72:75], v[160:163], v[210:213], v[72:75]
	v_mfma_f32_16x16x32_bf16 v[68:71], v[152:155], v[218:221], v[68:71]
	v_mfma_f32_16x16x32_bf16 v[64:67], v[160:163], v[218:221], v[64:67]
	v_mfma_f32_16x16x32_bf16 v[92:95], v[156:159], v[198:201], v[92:95]
	v_mfma_f32_16x16x32_bf16 v[88:91], v[164:167], v[198:201], v[88:91]
	v_mfma_f32_16x16x32_bf16 v[84:87], v[156:159], v[206:209], v[84:87]
	v_mfma_f32_16x16x32_bf16 v[80:83], v[164:167], v[206:209], v[80:83]
	v_mfma_f32_16x16x32_bf16 v[76:79], v[156:159], v[214:217], v[76:79]
	v_mfma_f32_16x16x32_bf16 v[72:75], v[164:167], v[214:217], v[72:75]
	v_mfma_f32_16x16x32_bf16 v[68:71], v[156:159], v[222:225], v[68:71]
	v_mfma_f32_16x16x32_bf16 v[64:67], v[164:167], v[222:225], v[64:67]
	v_mfma_f32_16x16x32_bf16 v[28:31], v[168:171], v[194:197], v[28:31]
	v_mfma_f32_16x16x32_bf16 v[24:27], v[176:179], v[194:197], v[24:27]
	v_mfma_f32_16x16x32_bf16 v[20:23], v[168:171], v[202:205], v[20:23]
	v_mfma_f32_16x16x32_bf16 v[16:19], v[176:179], v[202:205], v[16:19]
	v_mfma_f32_16x16x32_bf16 v[12:15], v[168:171], v[210:213], v[12:15]
	v_mfma_f32_16x16x32_bf16 v[8:11], v[176:179], v[210:213], v[8:11]
	v_mfma_f32_16x16x32_bf16 v[4:7], v[168:171], v[218:221], v[4:7]
	v_mfma_f32_16x16x32_bf16 v[0:3], v[176:179], v[218:221], v[0:3]
	v_mfma_f32_16x16x32_bf16 v[28:31], v[172:175], v[198:201], v[28:31]
	v_mfma_f32_16x16x32_bf16 v[24:27], v[190:193], v[198:201], v[24:27]
	v_mfma_f32_16x16x32_bf16 v[20:23], v[172:175], v[206:209], v[20:23]
	v_mfma_f32_16x16x32_bf16 v[16:19], v[190:193], v[206:209], v[16:19]
	v_mfma_f32_16x16x32_bf16 v[12:15], v[172:175], v[214:217], v[12:15]
	v_mfma_f32_16x16x32_bf16 v[8:11], v[190:193], v[214:217], v[8:11]
	v_mfma_f32_16x16x32_bf16 v[4:7], v[172:175], v[222:225], v[4:7]
	v_mfma_f32_16x16x32_bf16 v[0:3], v[190:193], v[222:225], v[0:3]
	s_barrier
	s_add_i32 s67, s67, 2
	s_add_u32 s30, s30, 0x100
	s_addc_u32 s31, s31, 0
	s_add_u32 s65, s65, 0x100
	s_addc_u32 s66, s66, 0
	s_cmp_gt_u32 s67, 13
	s_cbranch_scc0 .LBB0_494
	s_and_b64 vcc, exec, s[16:17]
	s_cbranch_vccz .LBB0_497
	s_barrier

; __device__ __forceinline__ int fresh_tid() { int t = (int)threadIdx.x; asm volatile("" : "+v"(t)); return t; }
; #define PG8_STAGE(bufoff, gbase, voff) do { _Pragma("unroll") for (int _i = 0; _i < 2; ++_i) \
;         __builtin_amdgcn_global_load_lds((const unsigned*)((const char*)(gbase) + (voff)[_i]), (PG8_LAS unsigned*)(lds + (bufoff) + ldsw + _i * 8192), 16, 0, 0); } while (0)
; #define PG8_WAIT_V(n) asm volatile("s_waitcnt vmcnt(" #n ")" ::: "memory")
; #define PG8_BAR __builtin_amdgcn_s_barrier()
; template <class Epi, class Sched, bool ALIGN_EPI = false, bool SP2 = false>
; __device__ __forceinline__ void gemm_phase(PG8_LAS unsigned char* lds, const Gemm g, const Sched& S, const Epi& E) {
;     const int tid = fresh_tid(), wid = __builtin_amdgcn_readfirstlane(tid >> 6), lane = tid & 63, wr = wid >> 2, wc = wid & 3, fr = lane & 15, fq = lane >> 4;
;     const int K = g.K, nt = K / BK;
;     unsigned voffA[2], voffB[2];
; #pragma unroll
;     for (int i = 0; i < 2; ++i) { int R, C; stage_rc(tid * 16 + i * 8192, R, C); const int Rb = Epi::PERM ? ((R & ~31) + perm32(R & 31)) : R;
;         voffA[i] = (unsigned)(R * K + C) * 2u; voffB[i] = (unsigned)(Rb * K + C) * 2u; }
;     const size_t kstep = (size_t)(BK * 2);
;     const size_t hstep = (size_t)HALF * K * 2;
;     const size_t tstep = 2 * hstep;
;     const unsigned ldsw = (unsigned)wid * 1024u;
;     const int aoff = lds_byte(wr * 64 + fr, fq * 8), boff = lds_byte(wc * 32 + fr, fq * 8);
;     ...
;     const char* cA = (const char*)g.A + (size_t)cur.pm * tstep; const char* cB = (const char*)g.Bt + (size_t)cur.pn * tstep;
;     S.a_ready(cur);
;     if constexpr (SP2) {
;         PG8_STAGE(PG8_SB(0, 0), cB, voffB); PG8_STAGE(PG8_SB(0, 1), cB + hstep, voffB); PG8_STAGE(PG8_SA(0, 0), cA, voffA); PG8_STAGE(PG8_SA(0, 1), cA + hstep, voffA);
;         if (wr == 1) PG8_BAR;
;         PG8_WAIT_V(2); PG8_BAR;
;         PG8_STAGE(PG8_SB(1, 0), cB + kstep, voffB); PG8_STAGE(PG8_SA(1, 0), cA + kstep, voffA); PG8_STAGE(PG8_SB(1, 1), cB + hstep + kstep, voffB);
;         PG8_WAIT_V(6); PG8_BAR;
.LBB0_748:
	v_ashrrev_i32_e32 v1, 31, v8
	v_lshrrev_b32_e32 v1, 26, v1
	v_add_u32_e32 v1, v8, v1
	v_ashrrev_i32_e32 v9, 6, v1
	v_bfe_i32 v1, v8, 27, 1
	v_lshlrev_b32_e32 v0, 4, v8
	v_lshrrev_b32_e32 v1, 22, v1
	v_add_u32_e32 v1, v0, v1
	v_and_b32_e32 v1, 0xfffffc00, v1
	v_sub_u32_e32 v1, v0, v1
	v_lshrrev_b32_e32 v2, 4, v1
	v_bitop3_b32 v2, v2, v1, 32 bitop3:0x6c
	v_ashrrev_i32_e32 v1, 31, v1
	v_lshrrev_b32_e32 v1, 26, v1
	v_add_u32_e32 v1, v2, v1
	v_ashrrev_i32_e32 v10, 6, v1
	v_lshlrev_b32_e32 v3, 3, v9
	v_mul_i32_i24_e32 v4, 64, v10
	v_and_b32_e32 v3, -16, v3
	v_sub_u32_e32 v2, v2, v4
	v_mov_b32_e32 v4, 1
	v_add_u32_e32 v1, v10, v3
	v_lshlrev_b32_e32 v3, 5, v9
	v_ashrrev_i16_sdwa v2, v4, sext(v2) dst_sel:DWORD dst_unused:UNUSED_PAD src0_sel:DWORD src1_sel:BYTE_0
	v_and_b32_e32 v3, 32, v3
	v_bfe_i32 v11, v2, 0, 16
	v_and_b32_e32 v6, 3, v10
	s_mov_b32 s1, 0x3fffe0
	v_add_lshl_u32 v3, v3, v11, 1
	v_add_u32_e32 v0, 0x2000, v0
	v_lshlrev_b32_e32 v2, 1, v1
	v_lshrrev_b32_e32 v5, 2, v1
	v_and_or_b32 v6, v1, s1, v6
	v_lshl_add_u32 v136, v1, 10, v3
	v_ashrrev_i32_e32 v1, 31, v0
	v_lshrrev_b32_e32 v1, 22, v1
	v_add_u32_e32 v1, v0, v1
	v_ashrrev_i32_e32 v12, 10, v1
	v_mul_i32_i24_e32 v1, 0x400, v12
	v_sub_u32_e32 v0, v0, v1
	v_and_b32_e32 v2, 24, v2
	v_and_b32_e32 v5, 4, v5
	v_lshrrev_b32_e32 v1, 4, v0
	v_or3_b32 v2, v6, v5, v2
	v_bitop3_b32 v0, v1, v0, 32 bitop3:0x6c
	v_lshl_add_u32 v138, v2, 10, v3
	v_ashrrev_i32_e32 v2, 31, v0
	s_ashr_i32 s0, s23, 3
	v_lshrrev_b32_e32 v2, 26, v2
	s_waitcnt lgkmcnt(0)
	s_add_u32 s41, s16, 0x11300000
	v_add_u32_e32 v2, v0, v2
	s_addc_u32 s42, s17, 0
	v_lshlrev_b32_e32 v1, 3, v12
	v_ashrrev_i32_e32 v13, 6, v2
	v_and_b32_e32 v2, 0xc0, v2
	s_add_u32 s43, s12, 0x1500000
	v_and_b32_e32 v1, -16, v1
	v_sub_u32_e32 v0, v0, v2
	s_addc_u32 s47, s13, 0
	v_add_u32_e32 v1, v13, v1
	v_ashrrev_i16_sdwa v0, v4, sext(v0) dst_sel:DWORD dst_unused:UNUSED_PAD src0_sel:DWORD src1_sel:BYTE_0
	v_and_b32_e32 v4, 3, v13
	s_add_i32 s0, s22, s0
	v_and_or_b32 v4, v1, s1, v4
	s_ashr_i32 s1, s0, 31
	s_lshr_b32 s1, s1, 28
	s_add_i32 s1, s0, s1
	s_ashr_i32 s3, s1, 4
	s_and_b32 s1, s1, -16
	s_sub_i32 s0, s0, s1
	s_bfe_i32 s1, s0, 0x80000
	s_bfe_u32 s1, s1, 0x3000c
	s_add_i32 s1, s0, s1
	s_bfe_i32 s12, s1, 0x80000
	s_and_b32 s1, s1, 0xf8
	s_sub_i32 s0, s0, s1
	s_lshl_b32 s3, s3, 3
	s_sext_i32_i16 s12, s12
	s_sext_i32_i8 s0, s0
	s_ashr_i32 s21, s24, 8
	s_lshr_b32 s20, s12, 3
	s_add_i32 s30, s3, s0
	s_ashr_i32 s18, s24, 6
	s_ashr_i32 s31, s30, 31
	s_bfe_i64 s[12:13], s[20:21], 0x100000
	s_lshl_b32 s52, s18, 10
	s_lshl_b64 s[0:1], s[30:31], 18
	s_lshl_b64 s[12:13], s[12:13], 18
	s_add_u32 s36, s43, s12
	v_lshlrev_b32_e32 v3, 5, v12
	v_bfe_i32 v14, v0, 0, 16
	v_lshlrev_b32_e32 v0, 1, v1
	v_lshrrev_b32_e32 v2, 2, v1
	s_addc_u32 s37, s47, s13
	s_add_i32 s31, s52, 0
	v_and_b32_e32 v3, 32, v3
	v_and_b32_e32 v0, 24, v0
	v_and_b32_e32 v2, 4, v2
	s_add_i32 m0, s31, 0x10000
	v_or3_b32 v0, v4, v2, v0
	v_add_lshl_u32 v2, v3, v14, 1
	v_readfirstlane_b32 vcc_lo, v8
	s_nop 3
	s_lshr_b32 vcc_lo, vcc_lo, 8
	s_cmp_eq_u32 vcc_lo, 0
	s_cbranch_scc0 .Lmy_prio_3
	s_setprio 1
.Lmy_prio_3:
	global_load_lds_dwordx4 v138, s[36:37]
	s_add_i32 m0, s31, 0x12000
	v_lshl_add_u32 v142, v0, 10, v2
	s_add_u32 s12, s36, 0x20000
	global_load_lds_dwordx4 v142, s[36:37]
	s_addc_u32 s13, s37, 0
	s_add_i32 m0, s31, 0x14000
	v_lshl_add_u32 v140, v1, 10, v2
	global_load_lds_dwordx4 v138, s[12:13]
	s_add_i32 m0, s31, 0x16000
	s_add_u32 s34, s41, s0
	s_addc_u32 s35, s42, s1
	s_add_i32 s53, s31, 0x2000
	global_load_lds_dwordx4 v142, s[12:13]
	s_mov_b32 m0, s31
	s_add_u32 s0, s34, 0x20000
	global_load_lds_dwordx4 v136, s[34:35]
	s_mov_b32 m0, s53
	s_addc_u32 s1, s35, 0
	s_add_i32 s54, s31, 0x4000
	global_load_lds_dwordx4 v140, s[34:35]
	s_mov_b32 m0, s54
	s_add_i32 s55, s31, 0x6000
	global_load_lds_dwordx4 v136, s[0:1]
	s_mov_b32 m0, s55
	s_load_dwordx2 s[10:11], s[10:11], 0xb8
	global_load_lds_dwordx4 v140, s[0:1]
	v_mov_b32_e32 v139, 0
	v_mov_b32_e32 v143, v139
	v_mov_b32_e32 v137, v139
	v_mov_b32_e32 v141, v139
	s_cmp_eq_u32 s21, 1
	s_mov_b32 s56, 0
	v_lshl_add_u64 v[6:7], s[36:37], 0, v[138:139]
	v_lshl_add_u64 v[4:5], s[36:37], 0, v[142:143]
	v_lshl_add_u64 v[0:1], s[34:35], 0, v[136:137]
	s_cselect_b64 s[12:13], -1, 0
	s_cmp_lg_u32 s21, 1
	v_lshl_add_u64 v[2:3], s[34:35], 0, v[140:141]
	s_cbranch_scc1 .LBB0_750
	s_barrier

; #define PG8_STAGE(bufoff, gbase, voff) do { _Pragma("unroll") for (int _i = 0; _i < 2; ++_i) \
;         __builtin_amdgcn_global_load_lds((const unsigned*)((const char*)(gbase) + (voff)[_i]), (PG8_LAS unsigned*)(lds + (bufoff) + ldsw + _i * 8192), 16, 0, 0); } while (0)
; #define PG8_LDA(dst, b, h) do { _Pragma("unroll") for (int m = 0; m < 4; ++m) _Pragma("unroll") for (int k = 0; k < 2; ++k) dst[m][k] = *(const PG8_LAS bf16x8*)(lds + PG8_SA(b, h) + aoff + m * 2048 + k * 1024); } while (0)
; #define PG8_LDB(dst, b, h) do { _Pragma("unroll") for (int n = 0; n < 2; ++n) _Pragma("unroll") for (int k = 0; k < 2; ++k) dst[n][k] = *(const PG8_LAS bf16x8*)(lds + PG8_SB(b, h) + boff + n * 2048 + k * 1024); } while (0)
; #define PG8_BAR __builtin_amdgcn_s_barrier()
; template <class Epi, class Sched, bool ALIGN_EPI = false, bool SP2 = false>
; __device__ __forceinline__ void gemm_phase(PG8_LAS unsigned char* lds, const Gemm g, const Sched& S, const Epi& E) {
;     ...
;             const bool last = (t == nt - 2);
;             const char* a1 = cA + (size_t)(t + 1) * kstep;
;             const char* a2 = last ? nA : cA + (size_t)(t + 2) * kstep; const char* b2 = last ? nB : cB + (size_t)(t + 2) * kstep;
;             const char* a3 = a2 + kstep; const char* b3 = b2 + kstep;
;             if (last && has_next) S.a_ready(nxt);
;             if constexpr (SP2) {
;             PG8_LDB(B0, 0, 0); PG8_LDB(B1, 0, 1); PG8_SCHED; PG8_LDA(At, 0, 0); PG8_STAGE(PG8_SA(1, 1), a1 + hstep, voffA);
;             PG8_WAIT_V(8); PG8_WAIT_L(0); PG8_BAR; PG8_MMA(0, 0, At, B0); PG8_MMA(0, 1, At, B1); PG8_BAR; PG8_SCHED;
;             PG8_LDA(At, 0, 1); PG8_STAGE(PG8_SB(0, 0), b2, voffB); PG8_STAGE(PG8_SB(0, 1), b2 + hstep, voffB); PG8_STAGE(PG8_SA(0, 0), a2, voffA);
;             PG8_WAIT_V(8); PG8_WAIT_L(0); PG8_BAR; PG8_MMA(1, 0, At, B0); PG8_MMA(1, 1, At, B1); PG8_BAR; PG8_SCHED;
;             PG8_LDB(B0, 1, 0); PG8_LDB(B1, 1, 1); PG8_SCHED; PG8_LDA(At, 1, 0); PG8_STAGE(PG8_SA(0, 1), a2 + hstep, voffA);
;             PG8_WAIT_V(8); PG8_WAIT_L(0); PG8_BAR; PG8_MMA(0, 0, At, B0); PG8_MMA(0, 1, At, B1); PG8_BAR; PG8_SCHED;
;             PG8_LDA(At, 1, 1); PG8_STAGE(PG8_SB(1, 0), b3, voffB); PG8_STAGE(PG8_SB(1, 1), b3 + hstep, voffB); PG8_STAGE(PG8_SA(1, 0), a3, voffA);
;             PG8_WAIT_V(8); PG8_WAIT_L(0); PG8_BAR; PG8_MMA(1, 0, At, B0); PG8_MMA(1, 1, At, B1); PG8_BAR; PG8_SCHED;
.LBB0_760:
	ds_read_b128 v[112:115], v167
	ds_read_b128 v[116:119], v167 offset:1024
	ds_read_b128 v[152:155], v167 offset:2048
	ds_read_b128 v[156:159], v167 offset:3072
	ds_read_b128 v[160:163], v168
	ds_read_b128 v[170:173], v168 offset:1024
	ds_read_b128 v[174:177], v168 offset:2048
	ds_read_b128 v[178:181], v168 offset:3072
	s_add_u32 s0, s34, 0xfffe0080
	s_addc_u32 s1, s35, -1
	s_cmp_eq_u32 s68, 4
	s_cselect_b32 s39, s25, s1
	s_cselect_b32 s38, s64, s0
	s_cselect_b32 s37, s23, s67
	s_cselect_b32 s36, s65, s66
	v_lshl_add_u64 v[222:223], s[34:35], 0, v[144:145]
	s_add_i32 m0, s31, 0xc000
	ds_read_b128 v[190:193], v169
	ds_read_b128 v[194:197], v169 offset:1024
	ds_read_b128 v[198:201], v169 offset:2048
	ds_read_b128 v[202:205], v169 offset:3072
	ds_read_b128 v[206:209], v169 offset:4096
	ds_read_b128 v[210:213], v169 offset:5120
	ds_read_b128 v[214:217], v169 offset:6144
	ds_read_b128 v[218:221], v169 offset:7168
	global_load_lds_dwordx4 v[222:223], off
	v_lshl_add_u64 v[222:223], s[34:35], 0, v[146:147]
	s_add_i32 m0, s31, 0xe000
	s_nop 0
	global_load_lds_dwordx4 v[222:223], off
	s_waitcnt vmcnt(8)
	s_waitcnt lgkmcnt(0)
	s_barrier
	s_waitcnt lgkmcnt(0)
	v_mfma_f32_16x16x32_bf16 v[132:135], v[112:115], v[190:193], v[132:135]
	v_mfma_f32_16x16x32_bf16 v[128:131], v[152:155], v[190:193], v[128:131]
	v_mfma_f32_16x16x32_bf16 v[124:127], v[112:115], v[198:201], v[124:127]
	v_mfma_f32_16x16x32_bf16 v[120:123], v[152:155], v[198:201], v[120:123]
	v_mfma_f32_16x16x32_bf16 v[108:111], v[112:115], v[206:209], v[108:111]
	v_mfma_f32_16x16x32_bf16 v[104:107], v[152:155], v[206:209], v[104:107]
	v_mfma_f32_16x16x32_bf16 v[100:103], v[112:115], v[214:217], v[100:103]
	v_mfma_f32_16x16x32_bf16 v[96:99], v[152:155], v[214:217], v[96:99]
	v_mfma_f32_16x16x32_bf16 v[132:135], v[116:119], v[194:197], v[132:135]
	v_mfma_f32_16x16x32_bf16 v[128:131], v[156:159], v[194:197], v[128:131]
	v_mfma_f32_16x16x32_bf16 v[124:127], v[116:119], v[202:205], v[124:127]
	v_mfma_f32_16x16x32_bf16 v[120:123], v[156:159], v[202:205], v[120:123]
	v_mfma_f32_16x16x32_bf16 v[108:111], v[116:119], v[210:213], v[108:111]
	v_mfma_f32_16x16x32_bf16 v[104:107], v[156:159], v[210:213], v[104:107]
	v_mfma_f32_16x16x32_bf16 v[100:103], v[116:119], v[218:221], v[100:103]
	v_mfma_f32_16x16x32_bf16 v[96:99], v[156:159], v[218:221], v[96:99]
	v_mfma_f32_16x16x32_bf16 v[60:63], v[160:163], v[190:193], v[60:63]
	v_mfma_f32_16x16x32_bf16 v[56:59], v[174:177], v[190:193], v[56:59]
	v_mfma_f32_16x16x32_bf16 v[52:55], v[160:163], v[198:201], v[52:55]
	v_mfma_f32_16x16x32_bf16 v[48:51], v[174:177], v[198:201], v[48:51]
	v_mfma_f32_16x16x32_bf16 v[44:47], v[160:163], v[206:209], v[44:47]
	v_mfma_f32_16x16x32_bf16 v[40:43], v[174:177], v[206:209], v[40:43]
	v_mfma_f32_16x16x32_bf16 v[36:39], v[160:163], v[214:217], v[36:39]
	v_mfma_f32_16x16x32_bf16 v[32:35], v[174:177], v[214:217], v[32:35]
	v_mfma_f32_16x16x32_bf16 v[60:63], v[170:173], v[194:197], v[60:63]
	v_mfma_f32_16x16x32_bf16 v[56:59], v[178:181], v[194:197], v[56:59]
	v_mfma_f32_16x16x32_bf16 v[52:55], v[170:173], v[202:205], v[52:55]
	v_mfma_f32_16x16x32_bf16 v[48:51], v[178:181], v[202:205], v[48:51]
	v_mfma_f32_16x16x32_bf16 v[44:47], v[170:173], v[210:213], v[44:47]
	v_mfma_f32_16x16x32_bf16 v[40:43], v[178:181], v[210:213], v[40:43]
	v_mfma_f32_16x16x32_bf16 v[36:39], v[170:173], v[218:221], v[36:39]
	v_mfma_f32_16x16x32_bf16 v[32:35], v[178:181], v[218:221], v[32:35]
	s_barrier
	s_add_i32 s0, s61, s52
	v_lshl_add_u64 v[222:223], s[36:37], 0, v[138:139]
	s_mov_b32 m0, s0
	ds_read_b128 v[190:193], v169 offset:16384
	ds_read_b128 v[194:197], v169 offset:17408
	ds_read_b128 v[198:201], v169 offset:18432
	ds_read_b128 v[202:205], v169 offset:19456
	ds_read_b128 v[206:209], v169 offset:20480
	ds_read_b128 v[210:213], v169 offset:21504
	ds_read_b128 v[214:217], v169 offset:22528
	ds_read_b128 v[218:221], v169 offset:23552
	global_load_lds_dwordx4 v[222:223], off
	s_add_i32 m0, s0, 0x2000
	s_add_u32 s0, s36, 0x20000
	v_lshl_add_u64 v[224:225], s[36:37], 0, v[142:143]
	s_addc_u32 s1, s37, 0
	s_add_i32 s3, s62, s52
	global_load_lds_dwordx4 v[224:225], off
	v_lshl_add_u64 v[226:227], s[0:1], 0, v[138:139]
	s_mov_b32 m0, s3
	v_lshl_add_u64 v[228:229], s[38:39], 0, v[140:141]
	global_load_lds_dwordx4 v[226:227], off
	v_lshl_add_u64 v[226:227], s[0:1], 0, v[142:143]
	s_add_i32 m0, s3, 0x2000
	s_nop 0
	global_load_lds_dwordx4 v[226:227], off
	v_lshl_add_u64 v[226:227], s[38:39], 0, v[136:137]
	s_mov_b32 m0, s31
	s_nop 0
	global_load_lds_dwordx4 v[226:227], off
	s_mov_b32 m0, s53
	s_nop 0
	global_load_lds_dwordx4 v[228:229], off
	s_waitcnt vmcnt(8)
	s_waitcnt lgkmcnt(0)
	s_barrier
; #define PG8_STAGE(bufoff, gbase, voff) do { _Pragma("unroll") for (int _i = 0; _i < 2; ++_i) \
;         __builtin_amdgcn_global_load_lds((const unsigned*)((const char*)(gbase) + (voff)[_i]), (PG8_LAS unsigned*)(lds + (bufoff) + ldsw + _i * 8192), 16, 0, 0); } while (0)
; #define PG8_LDA(dst, b, h) do { _Pragma("unroll") for (int m = 0; m < 4; ++m) _Pragma("unroll") for (int k = 0; k < 2; ++k) dst[m][k] = *(const PG8_LAS bf16x8*)(lds + PG8_SA(b, h) + aoff + m * 2048 + k * 1024); } while (0)
; #define PG8_LDB(dst, b, h) do { _Pragma("unroll") for (int n = 0; n < 2; ++n) _Pragma("unroll") for (int k = 0; k < 2; ++k) dst[n][k] = *(const PG8_LAS bf16x8*)(lds + PG8_SB(b, h) + boff + n * 2048 + k * 1024); } while (0)
; #define PG8_MMA(ai, bj, At, Bt) do { __builtin_amdgcn_s_setprio(1); _Pragma("unroll") for (int m = 0; m < 4; ++m) _Pragma("unroll") for (int n = 0; n < 2; ++n) _Pragma("unroll") for (int k = 0; k < 2; ++k) \
;         acc[ai][bj][m][n] = __builtin_amdgcn_mfma_f32_16x16x32_bf16(Bt[n][k], At[m][k], acc[ai][bj][m][n], 0, 0, 0); __builtin_amdgcn_s_setprio(0); } while (0)
; #define PG8_WAIT_V(n) asm volatile("s_waitcnt vmcnt(" #n ")" ::: "memory")
; template <class Epi, class Sched, bool ALIGN_EPI = false, bool SP2 = false>
; __device__ __forceinline__ void gemm_phase(PG8_LAS unsigned char* lds, const Gemm g, const Sched& S, const Epi& E) {
;     ...
;             PG8_LDB(B0, 0, 0); PG8_LDB(B1, 0, 1); PG8_SCHED; PG8_LDA(At, 0, 0); PG8_STAGE(PG8_SA(1, 1), a1 + hstep, voffA);
;             PG8_WAIT_V(8); PG8_WAIT_L(0); PG8_BAR; PG8_MMA(0, 0, At, B0); PG8_MMA(0, 1, At, B1); PG8_BAR; PG8_SCHED;
;             PG8_LDA(At, 0, 1); PG8_STAGE(PG8_SB(0, 0), b2, voffB); PG8_STAGE(PG8_SB(0, 1), b2 + hstep, voffB); PG8_STAGE(PG8_SA(0, 0), a2, voffA);
;             PG8_WAIT_V(8); PG8_WAIT_L(0); PG8_BAR; PG8_MMA(1, 0, At, B0); PG8_MMA(1, 1, At, B1); PG8_BAR; PG8_SCHED;
;             PG8_LDB(B0, 1, 0); PG8_LDB(B1, 1, 1); PG8_SCHED; PG8_LDA(At, 1, 0); PG8_STAGE(PG8_SA(0, 1), a2 + hstep, voffA);
;             PG8_WAIT_V(8); PG8_WAIT_L(0); PG8_BAR; PG8_MMA(0, 0, At, B0); PG8_MMA(0, 1, At, B1); PG8_BAR; PG8_SCHED;
;             PG8_LDA(At, 1, 1); PG8_STAGE(PG8_SB(1, 0), b3, voffB); PG8_STAGE(PG8_SB(1, 1), b3 + hstep, voffB); PG8_STAGE(PG8_SA(1, 0), a3, voffA);
;             PG8_WAIT_V(8); PG8_WAIT_L(0); PG8_BAR; PG8_MMA(1, 0, At, B0); PG8_MMA(1, 1, At, B1); PG8_BAR; PG8_SCHED;
	s_waitcnt lgkmcnt(0)
	v_mfma_f32_16x16x32_bf16 v[92:95], v[112:115], v[190:193], v[92:95]
	v_mfma_f32_16x16x32_bf16 v[88:91], v[152:155], v[190:193], v[88:91]
	v_mfma_f32_16x16x32_bf16 v[84:87], v[112:115], v[198:201], v[84:87]
	v_mfma_f32_16x16x32_bf16 v[80:83], v[152:155], v[198:201], v[80:83]
	v_mfma_f32_16x16x32_bf16 v[76:79], v[112:115], v[206:209], v[76:79]
	v_mfma_f32_16x16x32_bf16 v[72:75], v[152:155], v[206:209], v[72:75]
	v_mfma_f32_16x16x32_bf16 v[68:71], v[112:115], v[214:217], v[68:71]
	v_mfma_f32_16x16x32_bf16 v[64:67], v[152:155], v[214:217], v[64:67]
	v_mfma_f32_16x16x32_bf16 v[92:95], v[116:119], v[194:197], v[92:95]
	v_mfma_f32_16x16x32_bf16 v[88:91], v[156:159], v[194:197], v[88:91]
	v_mfma_f32_16x16x32_bf16 v[84:87], v[116:119], v[202:205], v[84:87]
	v_mfma_f32_16x16x32_bf16 v[80:83], v[156:159], v[202:205], v[80:83]
	v_mfma_f32_16x16x32_bf16 v[76:79], v[116:119], v[210:213], v[76:79]
	v_mfma_f32_16x16x32_bf16 v[72:75], v[156:159], v[210:213], v[72:75]
	v_mfma_f32_16x16x32_bf16 v[68:71], v[116:119], v[218:221], v[68:71]
	v_mfma_f32_16x16x32_bf16 v[64:67], v[156:159], v[218:221], v[64:67]
	v_mfma_f32_16x16x32_bf16 v[28:31], v[160:163], v[190:193], v[28:31]
	v_mfma_f32_16x16x32_bf16 v[24:27], v[174:177], v[190:193], v[24:27]
	v_mfma_f32_16x16x32_bf16 v[20:23], v[160:163], v[198:201], v[20:23]
	v_mfma_f32_16x16x32_bf16 v[16:19], v[174:177], v[198:201], v[16:19]
	v_mfma_f32_16x16x32_bf16 v[12:15], v[160:163], v[206:209], v[12:15]
	v_mfma_f32_16x16x32_bf16 v[8:11], v[174:177], v[206:209], v[8:11]
	v_mfma_f32_16x16x32_bf16 v[4:7], v[160:163], v[214:217], v[4:7]
	v_mfma_f32_16x16x32_bf16 v[0:3], v[174:177], v[214:217], v[0:3]
	v_mfma_f32_16x16x32_bf16 v[28:31], v[170:173], v[194:197], v[28:31]
	v_mfma_f32_16x16x32_bf16 v[24:27], v[178:181], v[194:197], v[24:27]
	v_mfma_f32_16x16x32_bf16 v[20:23], v[170:173], v[202:205], v[20:23]
	v_mfma_f32_16x16x32_bf16 v[16:19], v[178:181], v[202:205], v[16:19]
	v_mfma_f32_16x16x32_bf16 v[12:15], v[170:173], v[210:213], v[12:15]
	v_mfma_f32_16x16x32_bf16 v[8:11], v[178:181], v[210:213], v[8:11]
	v_mfma_f32_16x16x32_bf16 v[4:7], v[170:173], v[218:221], v[4:7]
	v_mfma_f32_16x16x32_bf16 v[0:3], v[178:181], v[218:221], v[0:3]
	s_barrier
	s_add_i32 s3, 0, 0x18000
	s_add_i32 s45, 0, 0x1c000
	v_add_u32_e32 v156, s3, v165
	v_add_u32_e32 v178, s45, v165
	ds_read_b128 v[112:115], v156
	ds_read_b128 v[116:119], v156 offset:1024
	ds_read_b128 v[152:155], v156 offset:2048
	ds_read_b128 v[156:159], v156 offset:3072
	ds_read_b128 v[160:163], v178
	ds_read_b128 v[170:173], v178 offset:1024
	ds_read_b128 v[174:177], v178 offset:2048
	ds_read_b128 v[178:181], v178 offset:3072
	s_add_u32 s0, s38, 0x20000
	s_addc_u32 s1, s39, 0
	s_mov_b32 m0, s54
	v_lshl_add_u64 v[230:231], s[0:1], 0, v[136:137]
	ds_read_b128 v[190:193], v169 offset:32768
	ds_read_b128 v[194:197], v169 offset:33792
	ds_read_b128 v[198:201], v169 offset:34816
	ds_read_b128 v[202:205], v169 offset:35840
	ds_read_b128 v[206:209], v169 offset:36864
	ds_read_b128 v[210:213], v169 offset:37888
	ds_read_b128 v[214:217], v169 offset:38912
	ds_read_b128 v[218:221], v169 offset:39936
	global_load_lds_dwordx4 v[230:231], off
	v_lshl_add_u64 v[230:231], s[0:1], 0, v[140:141]
	s_mov_b32 m0, s55
	s_nop 0
	global_load_lds_dwordx4 v[230:231], off
	s_waitcnt vmcnt(8)
	s_waitcnt lgkmcnt(0)
	s_barrier
	s_waitcnt lgkmcnt(0)
	v_mfma_f32_16x16x32_bf16 v[132:135], v[112:115], v[190:193], v[132:135]
	v_mfma_f32_16x16x32_bf16 v[128:131], v[152:155], v[190:193], v[128:131]
	v_mfma_f32_16x16x32_bf16 v[124:127], v[112:115], v[198:201], v[124:127]
	v_mfma_f32_16x16x32_bf16 v[120:123], v[152:155], v[198:201], v[120:123]
	v_mfma_f32_16x16x32_bf16 v[108:111], v[112:115], v[206:209], v[108:111]
	v_mfma_f32_16x16x32_bf16 v[104:107], v[152:155], v[206:209], v[104:107]
	v_mfma_f32_16x16x32_bf16 v[100:103], v[112:115], v[214:217], v[100:103]
	v_mfma_f32_16x16x32_bf16 v[96:99], v[152:155], v[214:217], v[96:99]
	v_mfma_f32_16x16x32_bf16 v[132:135], v[116:119], v[194:197], v[132:135]
	v_mfma_f32_16x16x32_bf16 v[128:131], v[156:159], v[194:197], v[128:131]
	v_mfma_f32_16x16x32_bf16 v[124:127], v[116:119], v[202:205], v[124:127]
	v_mfma_f32_16x16x32_bf16 v[120:123], v[156:159], v[202:205], v[120:123]
	v_mfma_f32_16x16x32_bf16 v[108:111], v[116:119], v[210:213], v[108:111]
	v_mfma_f32_16x16x32_bf16 v[104:107], v[156:159], v[210:213], v[104:107]
	v_mfma_f32_16x16x32_bf16 v[100:103], v[116:119], v[218:221], v[100:103]
	v_mfma_f32_16x16x32_bf16 v[96:99], v[156:159], v[218:221], v[96:99]
	v_mfma_f32_16x16x32_bf16 v[60:63], v[160:163], v[190:193], v[60:63]
	v_mfma_f32_16x16x32_bf16 v[56:59], v[174:177], v[190:193], v[56:59]
	v_mfma_f32_16x16x32_bf16 v[52:55], v[160:163], v[198:201], v[52:55]
	v_mfma_f32_16x16x32_bf16 v[48:51], v[174:177], v[198:201], v[48:51]
	v_mfma_f32_16x16x32_bf16 v[44:47], v[160:163], v[206:209], v[44:47]
	v_mfma_f32_16x16x32_bf16 v[40:43], v[174:177], v[206:209], v[40:43]
	v_mfma_f32_16x16x32_bf16 v[36:39], v[160:163], v[214:217], v[36:39]
	v_mfma_f32_16x16x32_bf16 v[32:35], v[174:177], v[214:217], v[32:35]
	v_mfma_f32_16x16x32_bf16 v[60:63], v[170:173], v[194:197], v[60:63]
	v_mfma_f32_16x16x32_bf16 v[56:59], v[178:181], v[194:197], v[56:59]
	v_mfma_f32_16x16x32_bf16 v[52:55], v[170:173], v[202:205], v[52:55]
	v_mfma_f32_16x16x32_bf16 v[48:51], v[178:181], v[202:205], v[48:51]
	v_mfma_f32_16x16x32_bf16 v[44:47], v[170:173], v[210:213], v[44:47]
	v_mfma_f32_16x16x32_bf16 v[40:43], v[178:181], v[210:213], v[40:43]
	v_mfma_f32_16x16x32_bf16 v[36:39], v[170:173], v[218:221], v[36:39]
	v_mfma_f32_16x16x32_bf16 v[32:35], v[178:181], v[218:221], v[32:35]
	s_barrier
; #define PG8_STAGE(bufoff, gbase, voff) do { _Pragma("unroll") for (int _i = 0; _i < 2; ++_i) \
;         __builtin_amdgcn_global_load_lds((const unsigned*)((const char*)(gbase) + (voff)[_i]), (PG8_LAS unsigned*)(lds + (bufoff) + ldsw + _i * 8192), 16, 0, 0); } while (0)
; #define PG8_LDA(dst, b, h) do { _Pragma("unroll") for (int m = 0; m < 4; ++m) _Pragma("unroll") for (int k = 0; k < 2; ++k) dst[m][k] = *(const PG8_LAS bf16x8*)(lds + PG8_SA(b, h) + aoff + m * 2048 + k * 1024); } while (0)
; #define PG8_LDB(dst, b, h) do { _Pragma("unroll") for (int n = 0; n < 2; ++n) _Pragma("unroll") for (int k = 0; k < 2; ++k) dst[n][k] = *(const PG8_LAS bf16x8*)(lds + PG8_SB(b, h) + boff + n * 2048 + k * 1024); } while (0)
; #define PG8_MMA(ai, bj, At, Bt) do { __builtin_amdgcn_s_setprio(1); _Pragma("unroll") for (int m = 0; m < 4; ++m) _Pragma("unroll") for (int n = 0; n < 2; ++n) _Pragma("unroll") for (int k = 0; k < 2; ++k) \
;         acc[ai][bj][m][n] = __builtin_amdgcn_mfma_f32_16x16x32_bf16(Bt[n][k], At[m][k], acc[ai][bj][m][n], 0, 0, 0); __builtin_amdgcn_s_setprio(0); } while (0)
; #define PG8_WAIT_V(n) asm volatile("s_waitcnt vmcnt(" #n ")" ::: "memory")
; #define PG8_WAIT_L(n) asm volatile("s_waitcnt lgkmcnt(" #n ")" ::: "memory")
; #define PG8_BAR __builtin_amdgcn_s_barrier()
; #define PG8_SCHED __builtin_amdgcn_sched_barrier(0)
; template <class Epi, class Sched, bool ALIGN_EPI = false, bool SP2 = false>
; __device__ __forceinline__ void gemm_phase(PG8_LAS unsigned char* lds, const Gemm g, const Sched& S, const Epi& E) {
;     ...
;             PG8_LDB(B0, 1, 0); PG8_LDB(B1, 1, 1); PG8_SCHED; PG8_LDA(At, 1, 0); PG8_STAGE(PG8_SA(0, 1), a2 + hstep, voffA);
;             PG8_WAIT_V(8); PG8_WAIT_L(0); PG8_BAR; PG8_MMA(0, 0, At, B0); PG8_MMA(0, 1, At, B1); PG8_BAR; PG8_SCHED;
;             PG8_LDA(At, 1, 1); PG8_STAGE(PG8_SB(1, 0), b3, voffB); PG8_STAGE(PG8_SB(1, 1), b3 + hstep, voffB); PG8_STAGE(PG8_SA(1, 0), a3, voffA);
;             PG8_WAIT_V(8); PG8_WAIT_L(0); PG8_BAR; PG8_MMA(1, 0, At, B0); PG8_MMA(1, 1, At, B1); PG8_BAR; PG8_SCHED;
	s_add_i32 s0, s3, s52
	v_lshl_add_u64 v[222:223], v[222:223], 0, s[18:19]
	s_mov_b32 m0, s0
	ds_read_b128 v[190:193], v169 offset:49152
	ds_read_b128 v[194:197], v169 offset:50176
	ds_read_b128 v[198:201], v169 offset:51200
	ds_read_b128 v[202:205], v169 offset:52224
	ds_read_b128 v[206:209], v169 offset:53248
	ds_read_b128 v[210:213], v169 offset:54272
	ds_read_b128 v[214:217], v169 offset:55296
	ds_read_b128 v[218:221], v169 offset:56320
	global_load_lds_dwordx4 v[222:223], off
	s_add_i32 m0, s0, 0x2000
	s_add_u32 s0, s36, 0x20080
	v_lshl_add_u64 v[222:223], v[224:225], 0, s[18:19]
	s_addc_u32 s1, s37, 0
	s_add_i32 s3, s45, s52
	global_load_lds_dwordx4 v[222:223], off
	v_lshl_add_u64 v[222:223], s[0:1], 0, v[138:139]
	s_mov_b32 m0, s3
	s_nop 0
	global_load_lds_dwordx4 v[222:223], off
	v_lshl_add_u64 v[222:223], s[0:1], 0, v[142:143]
	s_add_i32 m0, s3, 0x2000
	s_nop 0
	global_load_lds_dwordx4 v[222:223], off
	v_lshl_add_u64 v[222:223], v[226:227], 0, s[18:19]
	s_mov_b32 m0, s57
	s_nop 0
	global_load_lds_dwordx4 v[222:223], off
	v_lshl_add_u64 v[222:223], v[228:229], 0, s[18:19]
	s_mov_b32 m0, s58
	s_nop 0
	global_load_lds_dwordx4 v[222:223], off
	s_waitcnt vmcnt(8)
	s_waitcnt lgkmcnt(0)
	s_barrier
	s_waitcnt lgkmcnt(0)
	v_mfma_f32_16x16x32_bf16 v[92:95], v[112:115], v[190:193], v[92:95]
	v_mfma_f32_16x16x32_bf16 v[88:91], v[152:155], v[190:193], v[88:91]
	v_mfma_f32_16x16x32_bf16 v[84:87], v[112:115], v[198:201], v[84:87]
	v_mfma_f32_16x16x32_bf16 v[80:83], v[152:155], v[198:201], v[80:83]
	v_mfma_f32_16x16x32_bf16 v[76:79], v[112:115], v[206:209], v[76:79]
	v_mfma_f32_16x16x32_bf16 v[72:75], v[152:155], v[206:209], v[72:75]
	v_mfma_f32_16x16x32_bf16 v[68:71], v[112:115], v[214:217], v[68:71]
	v_mfma_f32_16x16x32_bf16 v[64:67], v[152:155], v[214:217], v[64:67]
	v_mfma_f32_16x16x32_bf16 v[92:95], v[116:119], v[194:197], v[92:95]
	v_mfma_f32_16x16x32_bf16 v[88:91], v[156:159], v[194:197], v[88:91]
	v_mfma_f32_16x16x32_bf16 v[84:87], v[116:119], v[202:205], v[84:87]
	v_mfma_f32_16x16x32_bf16 v[80:83], v[156:159], v[202:205], v[80:83]
	v_mfma_f32_16x16x32_bf16 v[76:79], v[116:119], v[210:213], v[76:79]
	v_mfma_f32_16x16x32_bf16 v[72:75], v[156:159], v[210:213], v[72:75]
	v_mfma_f32_16x16x32_bf16 v[68:71], v[116:119], v[218:221], v[68:71]
	v_mfma_f32_16x16x32_bf16 v[64:67], v[156:159], v[218:221], v[64:67]
	v_mfma_f32_16x16x32_bf16 v[28:31], v[160:163], v[190:193], v[28:31]
	v_mfma_f32_16x16x32_bf16 v[24:27], v[174:177], v[190:193], v[24:27]
	v_mfma_f32_16x16x32_bf16 v[20:23], v[160:163], v[198:201], v[20:23]
	v_mfma_f32_16x16x32_bf16 v[16:19], v[174:177], v[198:201], v[16:19]
	v_mfma_f32_16x16x32_bf16 v[12:15], v[160:163], v[206:209], v[12:15]
	v_mfma_f32_16x16x32_bf16 v[8:11], v[174:177], v[206:209], v[8:11]
	v_mfma_f32_16x16x32_bf16 v[4:7], v[160:163], v[214:217], v[4:7]
	v_mfma_f32_16x16x32_bf16 v[0:3], v[174:177], v[214:217], v[0:3]
	v_mfma_f32_16x16x32_bf16 v[28:31], v[170:173], v[194:197], v[28:31]
	v_mfma_f32_16x16x32_bf16 v[24:27], v[178:181], v[194:197], v[24:27]
	v_mfma_f32_16x16x32_bf16 v[20:23], v[170:173], v[202:205], v[20:23]
	v_mfma_f32_16x16x32_bf16 v[16:19], v[178:181], v[202:205], v[16:19]
	v_mfma_f32_16x16x32_bf16 v[12:15], v[170:173], v[210:213], v[12:15]
	v_mfma_f32_16x16x32_bf16 v[8:11], v[178:181], v[210:213], v[8:11]
	v_mfma_f32_16x16x32_bf16 v[4:7], v[170:173], v[218:221], v[4:7]
	v_mfma_f32_16x16x32_bf16 v[0:3], v[178:181], v[218:221], v[0:3]
	s_barrier
	s_add_i32 s68, s68, 2
	s_add_u32 s34, s34, 0x100
	s_addc_u32 s35, s35, 0
	s_add_u32 s66, s66, 0x100
	s_addc_u32 s67, s67, 0
	s_cmp_gt_u32 s68, 5
	s_cbranch_scc0 .LBB0_760
	s_and_b64 vcc, exec, s[20:21]
	s_cbranch_vccz .LBB0_763
	s_barrier

; __device__ __forceinline__ int fresh_tid() { int t = (int)threadIdx.x; asm volatile("" : "+v"(t)); return t; }
; #define PG8_STAGE(bufoff, gbase, voff) do { _Pragma("unroll") for (int _i = 0; _i < 2; ++_i) \
;         __builtin_amdgcn_global_load_lds((const unsigned*)((const char*)(gbase) + (voff)[_i]), (PG8_LAS unsigned*)(lds + (bufoff) + ldsw + _i * 8192), 16, 0, 0); } while (0)
; #define PG8_WAIT_V(n) asm volatile("s_waitcnt vmcnt(" #n ")" ::: "memory")
; #define PG8_BAR __builtin_amdgcn_s_barrier()
; template <class Epi, class Sched, bool ALIGN_EPI = false, bool SP2 = false>
; __device__ __forceinline__ void gemm_phase(PG8_LAS unsigned char* lds, const Gemm g, const Sched& S, const Epi& E) {
;     const int tid = fresh_tid(), wid = __builtin_amdgcn_readfirstlane(tid >> 6), lane = tid & 63, wr = wid >> 2, wc = wid & 3, fr = lane & 15, fq = lane >> 4;
;     const int K = g.K, nt = K / BK;
;     unsigned voffA[2], voffB[2];
; #pragma unroll
;     for (int i = 0; i < 2; ++i) { int R, C; stage_rc(tid * 16 + i * 8192, R, C); const int Rb = Epi::PERM ? ((R & ~31) + perm32(R & 31)) : R;
;         voffA[i] = (unsigned)(R * K + C) * 2u; voffB[i] = (unsigned)(Rb * K + C) * 2u; }
;     const size_t kstep = (size_t)(BK * 2);
;     const size_t hstep = (size_t)HALF * K * 2;
;     const size_t tstep = 2 * hstep;
;     const unsigned ldsw = (unsigned)wid * 1024u;
;     const int aoff = lds_byte(wr * 64 + fr, fq * 8), boff = lds_byte(wc * 32 + fr, fq * 8);
;     ...
;     const char* cA = (const char*)g.A + (size_t)cur.pm * tstep; const char* cB = (const char*)g.Bt + (size_t)cur.pn * tstep;
;     S.a_ready(cur);
;     if constexpr (SP2) {
;         PG8_STAGE(PG8_SB(0, 0), cB, voffB); PG8_STAGE(PG8_SB(0, 1), cB + hstep, voffB); PG8_STAGE(PG8_SA(0, 0), cA, voffA); PG8_STAGE(PG8_SA(0, 1), cA + hstep, voffA);
;         if (wr == 1) PG8_BAR;
;         PG8_WAIT_V(2); PG8_BAR;
;         PG8_STAGE(PG8_SB(1, 0), cB + kstep, voffB); PG8_STAGE(PG8_SA(1, 0), cA + kstep, voffA); PG8_STAGE(PG8_SB(1, 1), cB + hstep + kstep, voffB);
;         PG8_WAIT_V(6); PG8_BAR;
.LBB0_917:
	v_ashrrev_i32_e32 v1, 31, v8
	v_lshrrev_b32_e32 v1, 26, v1
	v_add_u32_e32 v1, v8, v1
	v_ashrrev_i32_e32 v9, 6, v1
	v_bfe_i32 v1, v8, 27, 1
	v_lshlrev_b32_e32 v0, 4, v8
	v_lshrrev_b32_e32 v1, 22, v1
	v_add_u32_e32 v1, v0, v1
	v_and_b32_e32 v1, 0xfffffc00, v1
	v_sub_u32_e32 v1, v0, v1
	v_lshrrev_b32_e32 v2, 4, v1
	v_bitop3_b32 v2, v2, v1, 32 bitop3:0x6c
	v_ashrrev_i32_e32 v1, 31, v1
	v_lshrrev_b32_e32 v1, 26, v1
	v_add_u32_e32 v1, v2, v1
	v_ashrrev_i32_e32 v10, 6, v1
	v_lshlrev_b32_e32 v3, 3, v9
	v_mul_i32_i24_e32 v4, 64, v10
	v_and_b32_e32 v3, -16, v3
	v_sub_u32_e32 v2, v2, v4
	v_mov_b32_e32 v4, 1
	v_add_u32_e32 v1, v10, v3
	v_lshlrev_b32_e32 v3, 5, v9
	v_ashrrev_i16_sdwa v2, v4, sext(v2) dst_sel:DWORD dst_unused:UNUSED_PAD src0_sel:DWORD src1_sel:BYTE_0
	v_and_b32_e32 v3, 32, v3
	v_bfe_i32 v11, v2, 0, 16
	v_and_b32_e32 v6, 3, v10
	s_mov_b32 s1, 0x1fffe0
	v_add_lshl_u32 v3, v3, v11, 1
	v_add_u32_e32 v0, 0x2000, v0
	v_lshlrev_b32_e32 v2, 1, v1
	v_lshrrev_b32_e32 v5, 2, v1
	v_and_or_b32 v6, v1, s1, v6
	v_lshl_add_u32 v128, v1, 11, v3
	v_ashrrev_i32_e32 v1, 31, v0
	v_lshrrev_b32_e32 v1, 22, v1
	v_add_u32_e32 v1, v0, v1
	v_ashrrev_i32_e32 v12, 10, v1
	v_mul_i32_i24_e32 v1, 0x400, v12
	v_sub_u32_e32 v0, v0, v1
	v_and_b32_e32 v2, 24, v2
	v_and_b32_e32 v5, 4, v5
	v_lshrrev_b32_e32 v1, 4, v0
	v_or3_b32 v2, v6, v5, v2
	v_bitop3_b32 v0, v1, v0, 32 bitop3:0x6c
	v_lshl_add_u32 v130, v2, 11, v3
	v_ashrrev_i32_e32 v2, 31, v0
	s_ashr_i32 s0, s18, 3
	v_lshrrev_b32_e32 v2, 26, v2
	s_waitcnt lgkmcnt(0)
	s_add_u32 s43, s14, 0x16400000
	v_add_u32_e32 v2, v0, v2
	s_addc_u32 s47, s15, 0
	v_lshlrev_b32_e32 v1, 3, v12
	v_ashrrev_i32_e32 v13, 6, v2
	v_and_b32_e32 v2, 0xc0, v2
	s_add_u32 s54, s12, 0x1600000
	v_and_b32_e32 v1, -16, v1
	v_sub_u32_e32 v0, v0, v2
	s_addc_u32 s55, s13, 0
	v_add_u32_e32 v1, v13, v1
	v_ashrrev_i16_sdwa v0, v4, sext(v0) dst_sel:DWORD dst_unused:UNUSED_PAD src0_sel:DWORD src1_sel:BYTE_0
	v_and_b32_e32 v4, 3, v13
	s_add_i32 s0, s19, s0
	v_and_or_b32 v4, v1, s1, v4
	s_ashr_i32 s1, s0, 31
	s_lshr_b32 s1, s1, 27
	s_add_i32 s1, s0, s1
	s_ashr_i32 s3, s1, 5
	s_andn2_b32 s1, s1, 31
	s_sub_i32 s0, s0, s1
	s_bfe_i32 s1, s0, 0x80000
	s_bfe_u32 s1, s1, 0x3000c
	s_add_i32 s1, s0, s1
	s_bfe_i32 s12, s1, 0x80000
	s_and_b32 s1, s1, 0xf8
	s_sub_i32 s0, s0, s1
	s_lshl_b32 s3, s3, 3
	s_sext_i32_i16 s12, s12
	s_sext_i32_i8 s0, s0
	s_lshr_b32 s20, s12, 3
	s_add_i32 s38, s3, s0
	s_ashr_i32 s18, s21, 6
	s_ashr_i32 s39, s38, 31
	s_bfe_i64 s[12:13], s[20:21], 0x100000
	s_ashr_i32 s22, s21, 8
	s_lshl_b32 s56, s18, 10
	s_lshl_b64 s[0:1], s[38:39], 19
	s_lshl_b64 s[12:13], s[12:13], 19
	s_add_u32 s50, s54, s12
	v_lshlrev_b32_e32 v3, 5, v12
	v_bfe_i32 v14, v0, 0, 16
	v_lshlrev_b32_e32 v0, 1, v1
	v_lshrrev_b32_e32 v2, 2, v1
	s_addc_u32 s51, s55, s13
	s_add_i32 s39, s56, 0
	v_and_b32_e32 v3, 32, v3
	v_and_b32_e32 v0, 24, v0
	v_and_b32_e32 v2, 4, v2
	s_add_i32 m0, s39, 0x10000
	v_or3_b32 v0, v4, v2, v0
	v_add_lshl_u32 v2, v3, v14, 1
	v_readfirstlane_b32 vcc_lo, v8
	s_nop 3
	s_lshr_b32 vcc_lo, vcc_lo, 8
	s_cmp_eq_u32 vcc_lo, 0
	s_cbranch_scc0 .Lmy_prio_4
	s_setprio 1
.Lmy_prio_4:
	v_bfe_u32 v239, v8, 3, 3
	v_and_b32_e32 v240, 7, v8
	v_xor_b32_e32 v240, v240, v239
	v_lshlrev_b32_e32 v240, 4, v240
	v_lshrrev_b32_e32 v241, 6, v8
	v_lshl_add_u32 v242, v241, 3, v239
	v_mov_b32_e32 v243, 0x800
	v_mad_u32_u24 v128, v242, v243, v240
	v_add_u32_e32 v132, 0x20000, v128
	v_lshrrev_b32_e32 v244, 2, v241
	v_lshlrev_b32_e32 v244, 5, v244
	v_and_b32_e32 v245, 1, v241
	v_lshrrev_b32_e32 v246, 2, v239
	v_lshl_add_u32 v245, v245, 1, v246
	v_lshl_add_u32 v244, v245, 3, v244
	v_bfe_u32 v245, v241, 1, 1
	v_lshl_add_u32 v244, v245, 2, v244
	v_and_b32_e32 v245, 3, v239
	v_add_u32_e32 v244, v244, v245
	v_mad_u32_u24 v130, v244, v243, v240
	v_add_u32_e32 v134, 0x20000, v130
	global_load_lds_dwordx4 v130, s[50:51]
	s_add_i32 m0, s39, 0x12000
	s_add_u32 s12, s50, 0x40000
	global_load_lds_dwordx4 v134, s[50:51]
	s_addc_u32 s13, s51, 0
	s_add_i32 m0, s39, 0x14000
	global_load_lds_dwordx4 v130, s[12:13]
	s_add_i32 m0, s39, 0x16000
	s_add_u32 s40, s43, s0
	s_addc_u32 s41, s47, s1
	s_add_i32 s57, s39, 0x2000
	global_load_lds_dwordx4 v134, s[12:13]
	s_mov_b32 m0, s39
	s_add_u32 s0, s40, 0x40000
	global_load_lds_dwordx4 v128, s[40:41]
	s_mov_b32 m0, s57
	s_addc_u32 s1, s41, 0
	s_add_i32 s58, s39, 0x4000
	global_load_lds_dwordx4 v132, s[40:41]
	s_mov_b32 m0, s58
	s_add_i32 s59, s39, 0x6000
	global_load_lds_dwordx4 v128, s[0:1]
	s_mov_b32 m0, s59
	v_mov_b32_e32 v131, 0
	global_load_lds_dwordx4 v132, s[0:1]
	v_mov_b32_e32 v135, v131
	v_mov_b32_e32 v129, v131
	v_mov_b32_e32 v133, v131
	s_cmp_eq_u32 s22, 1
	s_mov_b32 s60, 0
	v_lshl_add_u64 v[6:7], s[50:51], 0, v[130:131]
	v_lshl_add_u64 v[2:3], s[50:51], 0, v[134:135]
	s_mov_b64 s[12:13], 0x40000
	v_lshl_add_u64 v[0:1], s[40:41], 0, v[128:129]
	s_cselect_b64 s[14:15], -1, 0
	s_cmp_lg_u32 s22, 1
	v_lshl_add_u64 v[4:5], s[40:41], 0, v[132:133]
	s_cbranch_scc1 .LBB0_919
	s_barrier

; #define PG8_STAGE(bufoff, gbase, voff) do { _Pragma("unroll") for (int _i = 0; _i < 2; ++_i) \
;         __builtin_amdgcn_global_load_lds((const unsigned*)((const char*)(gbase) + (voff)[_i]), (PG8_LAS unsigned*)(lds + (bufoff) + ldsw + _i * 8192), 16, 0, 0); } while (0)
; #define PG8_LDA(dst, b, h) do { _Pragma("unroll") for (int m = 0; m < 4; ++m) _Pragma("unroll") for (int k = 0; k < 2; ++k) dst[m][k] = *(const PG8_LAS bf16x8*)(lds + PG8_SA(b, h) + aoff + m * 2048 + k * 1024); } while (0)
; #define PG8_LDB(dst, b, h) do { _Pragma("unroll") for (int n = 0; n < 2; ++n) _Pragma("unroll") for (int k = 0; k < 2; ++k) dst[n][k] = *(const PG8_LAS bf16x8*)(lds + PG8_SB(b, h) + boff + n * 2048 + k * 1024); } while (0)
; #define PG8_BAR __builtin_amdgcn_s_barrier()
; template <class Epi, class Sched, bool ALIGN_EPI = false, bool SP2 = false>
; __device__ __forceinline__ void gemm_phase(PG8_LAS unsigned char* lds, const Gemm g, const Sched& S, const Epi& E) {
;     ...
;             const bool last = (t == nt - 2);
;             const char* a1 = cA + (size_t)(t + 1) * kstep;
;             const char* a2 = last ? nA : cA + (size_t)(t + 2) * kstep; const char* b2 = last ? nB : cB + (size_t)(t + 2) * kstep;
;             const char* a3 = a2 + kstep; const char* b3 = b2 + kstep;
;             if (last && has_next) S.a_ready(nxt);
;             if constexpr (SP2) {
;             PG8_LDB(B0, 0, 0); PG8_LDB(B1, 0, 1); PG8_SCHED; PG8_LDA(At, 0, 0); PG8_STAGE(PG8_SA(1, 1), a1 + hstep, voffA);
;             PG8_WAIT_V(8); PG8_WAIT_L(0); PG8_BAR; PG8_MMA(0, 0, At, B0); PG8_MMA(0, 1, At, B1); PG8_BAR; PG8_SCHED;
;             PG8_LDA(At, 0, 1); PG8_STAGE(PG8_SB(0, 0), b2, voffB); PG8_STAGE(PG8_SB(0, 1), b2 + hstep, voffB); PG8_STAGE(PG8_SA(0, 0), a2, voffA);
;             PG8_WAIT_V(8); PG8_WAIT_L(0); PG8_BAR; PG8_MMA(1, 0, At, B0); PG8_MMA(1, 1, At, B1); PG8_BAR; PG8_SCHED;
;             PG8_LDB(B0, 1, 0); PG8_LDB(B1, 1, 1); PG8_SCHED; PG8_LDA(At, 1, 0); PG8_STAGE(PG8_SA(0, 1), a2 + hstep, voffA);
;             PG8_WAIT_V(8); PG8_WAIT_L(0); PG8_BAR; PG8_MMA(0, 0, At, B0); PG8_MMA(0, 1, At, B1); PG8_BAR; PG8_SCHED;
;             PG8_LDA(At, 1, 1); PG8_STAGE(PG8_SB(1, 0), b3, voffB); PG8_STAGE(PG8_SB(1, 1), b3 + hstep, voffB); PG8_STAGE(PG8_SA(1, 0), a3, voffA);
;             PG8_WAIT_V(8); PG8_WAIT_L(0); PG8_BAR; PG8_MMA(1, 0, At, B0); PG8_MMA(1, 1, At, B1); PG8_BAR; PG8_SCHED;
.LBB0_929:
	ds_read_b128 v[150:153], v147
	ds_read_b128 v[154:157], v235
	ds_read_b128 v[158:161], v147 offset:2048
	ds_read_b128 v[162:165], v235 offset:2048
	ds_read_b128 v[166:169], v148
	ds_read_b128 v[170:173], v236
	ds_read_b128 v[174:177], v148 offset:2048
	ds_read_b128 v[178:181], v236 offset:2048
	s_add_u32 s3, s40, 0xfffc0080
	s_addc_u32 s45, s41, -1
	s_cmp_eq_u32 s76, 12
	s_cselect_b32 s53, s31, s45
	s_cselect_b32 s52, s72, s3
	s_cselect_b32 s51, s29, s75
	s_cselect_b32 s50, s73, s74
	v_lshl_add_u64 v[222:223], s[40:41], 0, v[136:137]
	s_add_i32 m0, s39, 0xc000
	ds_read_b128 v[190:193], v149
	ds_read_b128 v[194:197], v233
	ds_read_b128 v[198:201], v149 offset:2048
	ds_read_b128 v[202:205], v233 offset:2048
	ds_read_b128 v[206:209], v149 offset:4096
	ds_read_b128 v[210:213], v233 offset:4096
	ds_read_b128 v[214:217], v149 offset:6144
	ds_read_b128 v[218:221], v233 offset:6144
	global_load_lds_dwordx4 v[222:223], off
	v_lshl_add_u64 v[222:223], s[40:41], 0, v[138:139]
	s_add_i32 m0, s39, 0xe000
	s_nop 0
	global_load_lds_dwordx4 v[222:223], off
	s_waitcnt vmcnt(8)
	s_waitcnt lgkmcnt(0)
	s_barrier
	s_waitcnt lgkmcnt(0)
	v_mfma_f32_16x16x32_bf16 v[124:127], v[150:153], v[190:193], v[124:127]
	v_mfma_f32_16x16x32_bf16 v[120:123], v[158:161], v[190:193], v[120:123]
	v_mfma_f32_16x16x32_bf16 v[116:119], v[150:153], v[198:201], v[116:119]
	v_mfma_f32_16x16x32_bf16 v[112:115], v[158:161], v[198:201], v[112:115]
	v_mfma_f32_16x16x32_bf16 v[108:111], v[150:153], v[206:209], v[108:111]
	v_mfma_f32_16x16x32_bf16 v[104:107], v[158:161], v[206:209], v[104:107]
	v_mfma_f32_16x16x32_bf16 v[100:103], v[150:153], v[214:217], v[100:103]
	v_mfma_f32_16x16x32_bf16 v[96:99], v[158:161], v[214:217], v[96:99]
	v_mfma_f32_16x16x32_bf16 v[124:127], v[154:157], v[194:197], v[124:127]
	v_mfma_f32_16x16x32_bf16 v[120:123], v[162:165], v[194:197], v[120:123]
	v_mfma_f32_16x16x32_bf16 v[116:119], v[154:157], v[202:205], v[116:119]
	v_mfma_f32_16x16x32_bf16 v[112:115], v[162:165], v[202:205], v[112:115]
	v_mfma_f32_16x16x32_bf16 v[108:111], v[154:157], v[210:213], v[108:111]
	v_mfma_f32_16x16x32_bf16 v[104:107], v[162:165], v[210:213], v[104:107]
	v_mfma_f32_16x16x32_bf16 v[100:103], v[154:157], v[218:221], v[100:103]
	v_mfma_f32_16x16x32_bf16 v[96:99], v[162:165], v[218:221], v[96:99]
	v_mfma_f32_16x16x32_bf16 v[76:79], v[166:169], v[190:193], v[76:79]
	v_mfma_f32_16x16x32_bf16 v[68:71], v[174:177], v[190:193], v[68:71]
	v_mfma_f32_16x16x32_bf16 v[60:63], v[166:169], v[198:201], v[60:63]
	v_mfma_f32_16x16x32_bf16 v[52:55], v[174:177], v[198:201], v[52:55]
	v_mfma_f32_16x16x32_bf16 v[44:47], v[166:169], v[206:209], v[44:47]
	v_mfma_f32_16x16x32_bf16 v[40:43], v[174:177], v[206:209], v[40:43]
	v_mfma_f32_16x16x32_bf16 v[36:39], v[166:169], v[214:217], v[36:39]
	v_mfma_f32_16x16x32_bf16 v[32:35], v[174:177], v[214:217], v[32:35]
	v_mfma_f32_16x16x32_bf16 v[76:79], v[170:173], v[194:197], v[76:79]
	v_mfma_f32_16x16x32_bf16 v[68:71], v[178:181], v[194:197], v[68:71]
	v_mfma_f32_16x16x32_bf16 v[60:63], v[170:173], v[202:205], v[60:63]
	v_mfma_f32_16x16x32_bf16 v[52:55], v[178:181], v[202:205], v[52:55]
	v_mfma_f32_16x16x32_bf16 v[44:47], v[170:173], v[210:213], v[44:47]
	v_mfma_f32_16x16x32_bf16 v[40:43], v[178:181], v[210:213], v[40:43]
	v_mfma_f32_16x16x32_bf16 v[36:39], v[170:173], v[218:221], v[36:39]
	v_mfma_f32_16x16x32_bf16 v[32:35], v[178:181], v[218:221], v[32:35]
	s_barrier
	s_add_i32 s3, s65, s56
	v_lshl_add_u64 v[222:223], s[50:51], 0, v[130:131]
	s_mov_b32 m0, s3
	ds_read_b128 v[190:193], v149 offset:16384
	ds_read_b128 v[194:197], v233 offset:16384
	ds_read_b128 v[198:201], v149 offset:18432
	ds_read_b128 v[202:205], v233 offset:18432
	ds_read_b128 v[206:209], v149 offset:20480
	ds_read_b128 v[210:213], v233 offset:20480
	ds_read_b128 v[214:217], v149 offset:22528
	ds_read_b128 v[218:221], v233 offset:22528
	global_load_lds_dwordx4 v[222:223], off
	s_add_i32 m0, s3, 0x2000
	s_add_u32 s70, s50, 0x40000
	v_lshl_add_u64 v[224:225], s[50:51], 0, v[134:135]
	s_addc_u32 s71, s51, 0
	s_add_i32 s3, s66, s56
	global_load_lds_dwordx4 v[224:225], off
	v_lshl_add_u64 v[226:227], s[70:71], 0, v[130:131]
	s_mov_b32 m0, s3
	v_lshl_add_u64 v[228:229], s[52:53], 0, v[132:133]
	global_load_lds_dwordx4 v[226:227], off
	v_lshl_add_u64 v[226:227], s[70:71], 0, v[134:135]
	s_add_i32 m0, s3, 0x2000
	s_nop 0
	global_load_lds_dwordx4 v[226:227], off
	v_lshl_add_u64 v[226:227], s[52:53], 0, v[128:129]
	s_mov_b32 m0, s39
	s_nop 0
	global_load_lds_dwordx4 v[226:227], off
	s_mov_b32 m0, s57
	s_nop 0
	global_load_lds_dwordx4 v[228:229], off
	s_waitcnt vmcnt(8)
	s_waitcnt lgkmcnt(0)
	s_barrier
; #define PG8_STAGE(bufoff, gbase, voff) do { _Pragma("unroll") for (int _i = 0; _i < 2; ++_i) \
;         __builtin_amdgcn_global_load_lds((const unsigned*)((const char*)(gbase) + (voff)[_i]), (PG8_LAS unsigned*)(lds + (bufoff) + ldsw + _i * 8192), 16, 0, 0); } while (0)
; #define PG8_LDA(dst, b, h) do { _Pragma("unroll") for (int m = 0; m < 4; ++m) _Pragma("unroll") for (int k = 0; k < 2; ++k) dst[m][k] = *(const PG8_LAS bf16x8*)(lds + PG8_SA(b, h) + aoff + m * 2048 + k * 1024); } while (0)
; #define PG8_LDB(dst, b, h) do { _Pragma("unroll") for (int n = 0; n < 2; ++n) _Pragma("unroll") for (int k = 0; k < 2; ++k) dst[n][k] = *(const PG8_LAS bf16x8*)(lds + PG8_SB(b, h) + boff + n * 2048 + k * 1024); } while (0)
; #define PG8_MMA(ai, bj, At, Bt) do { __builtin_amdgcn_s_setprio(1); _Pragma("unroll") for (int m = 0; m < 4; ++m) _Pragma("unroll") for (int n = 0; n < 2; ++n) _Pragma("unroll") for (int k = 0; k < 2; ++k) \
;         acc[ai][bj][m][n] = __builtin_amdgcn_mfma_f32_16x16x32_bf16(Bt[n][k], At[m][k], acc[ai][bj][m][n], 0, 0, 0); __builtin_amdgcn_s_setprio(0); } while (0)
; #define PG8_WAIT_V(n) asm volatile("s_waitcnt vmcnt(" #n ")" ::: "memory")
; template <class Epi, class Sched, bool ALIGN_EPI = false, bool SP2 = false>
; __device__ __forceinline__ void gemm_phase(PG8_LAS unsigned char* lds, const Gemm g, const Sched& S, const Epi& E) {
;     ...
;             PG8_LDB(B0, 0, 0); PG8_LDB(B1, 0, 1); PG8_SCHED; PG8_LDA(At, 0, 0); PG8_STAGE(PG8_SA(1, 1), a1 + hstep, voffA);
;             PG8_WAIT_V(8); PG8_WAIT_L(0); PG8_BAR; PG8_MMA(0, 0, At, B0); PG8_MMA(0, 1, At, B1); PG8_BAR; PG8_SCHED;
;             PG8_LDA(At, 0, 1); PG8_STAGE(PG8_SB(0, 0), b2, voffB); PG8_STAGE(PG8_SB(0, 1), b2 + hstep, voffB); PG8_STAGE(PG8_SA(0, 0), a2, voffA);
;             PG8_WAIT_V(8); PG8_WAIT_L(0); PG8_BAR; PG8_MMA(1, 0, At, B0); PG8_MMA(1, 1, At, B1); PG8_BAR; PG8_SCHED;
;             PG8_LDB(B0, 1, 0); PG8_LDB(B1, 1, 1); PG8_SCHED; PG8_LDA(At, 1, 0); PG8_STAGE(PG8_SA(0, 1), a2 + hstep, voffA);
;             PG8_WAIT_V(8); PG8_WAIT_L(0); PG8_BAR; PG8_MMA(0, 0, At, B0); PG8_MMA(0, 1, At, B1); PG8_BAR; PG8_SCHED;
;             PG8_LDA(At, 1, 1); PG8_STAGE(PG8_SB(1, 0), b3, voffB); PG8_STAGE(PG8_SB(1, 1), b3 + hstep, voffB); PG8_STAGE(PG8_SA(1, 0), a3, voffA);
;             PG8_WAIT_V(8); PG8_WAIT_L(0); PG8_BAR; PG8_MMA(1, 0, At, B0); PG8_MMA(1, 1, At, B1); PG8_BAR; PG8_SCHED;
	s_waitcnt lgkmcnt(0)
	v_mfma_f32_16x16x32_bf16 v[92:95], v[150:153], v[190:193], v[92:95]
	v_mfma_f32_16x16x32_bf16 v[88:91], v[158:161], v[190:193], v[88:91]
	v_mfma_f32_16x16x32_bf16 v[84:87], v[150:153], v[198:201], v[84:87]
	v_mfma_f32_16x16x32_bf16 v[80:83], v[158:161], v[198:201], v[80:83]
	v_mfma_f32_16x16x32_bf16 v[72:75], v[150:153], v[206:209], v[72:75]
	v_mfma_f32_16x16x32_bf16 v[64:67], v[158:161], v[206:209], v[64:67]
	v_mfma_f32_16x16x32_bf16 v[56:59], v[150:153], v[214:217], v[56:59]
	v_mfma_f32_16x16x32_bf16 v[48:51], v[158:161], v[214:217], v[48:51]
	v_mfma_f32_16x16x32_bf16 v[92:95], v[154:157], v[194:197], v[92:95]
	v_mfma_f32_16x16x32_bf16 v[88:91], v[162:165], v[194:197], v[88:91]
	v_mfma_f32_16x16x32_bf16 v[84:87], v[154:157], v[202:205], v[84:87]
	v_mfma_f32_16x16x32_bf16 v[80:83], v[162:165], v[202:205], v[80:83]
	v_mfma_f32_16x16x32_bf16 v[72:75], v[154:157], v[210:213], v[72:75]
	v_mfma_f32_16x16x32_bf16 v[64:67], v[162:165], v[210:213], v[64:67]
	v_mfma_f32_16x16x32_bf16 v[56:59], v[154:157], v[218:221], v[56:59]
	v_mfma_f32_16x16x32_bf16 v[48:51], v[162:165], v[218:221], v[48:51]
	v_mfma_f32_16x16x32_bf16 v[28:31], v[166:169], v[190:193], v[28:31]
	v_mfma_f32_16x16x32_bf16 v[24:27], v[174:177], v[190:193], v[24:27]
	v_mfma_f32_16x16x32_bf16 v[20:23], v[166:169], v[198:201], v[20:23]
	v_mfma_f32_16x16x32_bf16 v[16:19], v[174:177], v[198:201], v[16:19]
	v_mfma_f32_16x16x32_bf16 v[12:15], v[166:169], v[206:209], v[12:15]
	v_mfma_f32_16x16x32_bf16 v[8:11], v[174:177], v[206:209], v[8:11]
	v_mfma_f32_16x16x32_bf16 v[4:7], v[166:169], v[214:217], v[4:7]
	v_mfma_f32_16x16x32_bf16 v[0:3], v[174:177], v[214:217], v[0:3]
	v_mfma_f32_16x16x32_bf16 v[28:31], v[170:173], v[194:197], v[28:31]
	v_mfma_f32_16x16x32_bf16 v[24:27], v[178:181], v[194:197], v[24:27]
	v_mfma_f32_16x16x32_bf16 v[20:23], v[170:173], v[202:205], v[20:23]
	v_mfma_f32_16x16x32_bf16 v[16:19], v[178:181], v[202:205], v[16:19]
	v_mfma_f32_16x16x32_bf16 v[12:15], v[170:173], v[210:213], v[12:15]
	v_mfma_f32_16x16x32_bf16 v[8:11], v[178:181], v[210:213], v[8:11]
	v_mfma_f32_16x16x32_bf16 v[4:7], v[170:173], v[218:221], v[4:7]
	v_mfma_f32_16x16x32_bf16 v[0:3], v[178:181], v[218:221], v[0:3]
	s_barrier
	s_add_i32 s3, 0, 0x18000
	s_add_i32 s45, 0, 0x1c000
	v_add_u32_e32 v162, s3, v145
	v_add_u32_e32 v237, s3, v234
	v_add_u32_e32 v178, s45, v145
	v_add_u32_e32 v238, s45, v234
	ds_read_b128 v[150:153], v162
	ds_read_b128 v[154:157], v237
	ds_read_b128 v[158:161], v162 offset:2048
	ds_read_b128 v[162:165], v237 offset:2048
	ds_read_b128 v[166:169], v178
	ds_read_b128 v[170:173], v238
	ds_read_b128 v[174:177], v178 offset:2048
	ds_read_b128 v[178:181], v238 offset:2048
	s_add_u32 s52, s52, 0x40000
	s_addc_u32 s53, s53, 0
	s_mov_b32 m0, s58
	v_lshl_add_u64 v[230:231], s[52:53], 0, v[128:129]
	ds_read_b128 v[190:193], v149 offset:32768
	ds_read_b128 v[194:197], v233 offset:32768
	ds_read_b128 v[198:201], v149 offset:34816
	ds_read_b128 v[202:205], v233 offset:34816
	ds_read_b128 v[206:209], v149 offset:36864
	ds_read_b128 v[210:213], v233 offset:36864
	ds_read_b128 v[214:217], v149 offset:38912
	ds_read_b128 v[218:221], v233 offset:38912
	global_load_lds_dwordx4 v[230:231], off
	v_lshl_add_u64 v[230:231], s[52:53], 0, v[132:133]
	s_mov_b32 m0, s59
	s_nop 0
	global_load_lds_dwordx4 v[230:231], off
	s_waitcnt vmcnt(8)
	s_waitcnt lgkmcnt(0)
	s_barrier
	s_waitcnt lgkmcnt(0)
	v_mfma_f32_16x16x32_bf16 v[124:127], v[150:153], v[190:193], v[124:127]
	v_mfma_f32_16x16x32_bf16 v[120:123], v[158:161], v[190:193], v[120:123]
	v_mfma_f32_16x16x32_bf16 v[116:119], v[150:153], v[198:201], v[116:119]
	v_mfma_f32_16x16x32_bf16 v[112:115], v[158:161], v[198:201], v[112:115]
	v_mfma_f32_16x16x32_bf16 v[108:111], v[150:153], v[206:209], v[108:111]
	v_mfma_f32_16x16x32_bf16 v[104:107], v[158:161], v[206:209], v[104:107]
	v_mfma_f32_16x16x32_bf16 v[100:103], v[150:153], v[214:217], v[100:103]
	v_mfma_f32_16x16x32_bf16 v[96:99], v[158:161], v[214:217], v[96:99]
	v_mfma_f32_16x16x32_bf16 v[124:127], v[154:157], v[194:197], v[124:127]
	v_mfma_f32_16x16x32_bf16 v[120:123], v[162:165], v[194:197], v[120:123]
	v_mfma_f32_16x16x32_bf16 v[116:119], v[154:157], v[202:205], v[116:119]
	v_mfma_f32_16x16x32_bf16 v[112:115], v[162:165], v[202:205], v[112:115]
	v_mfma_f32_16x16x32_bf16 v[108:111], v[154:157], v[210:213], v[108:111]
	v_mfma_f32_16x16x32_bf16 v[104:107], v[162:165], v[210:213], v[104:107]
	v_mfma_f32_16x16x32_bf16 v[100:103], v[154:157], v[218:221], v[100:103]
	v_mfma_f32_16x16x32_bf16 v[96:99], v[162:165], v[218:221], v[96:99]
	v_mfma_f32_16x16x32_bf16 v[76:79], v[166:169], v[190:193], v[76:79]
	v_mfma_f32_16x16x32_bf16 v[68:71], v[174:177], v[190:193], v[68:71]
	v_mfma_f32_16x16x32_bf16 v[60:63], v[166:169], v[198:201], v[60:63]
	v_mfma_f32_16x16x32_bf16 v[52:55], v[174:177], v[198:201], v[52:55]
	v_mfma_f32_16x16x32_bf16 v[44:47], v[166:169], v[206:209], v[44:47]
	v_mfma_f32_16x16x32_bf16 v[40:43], v[174:177], v[206:209], v[40:43]
	v_mfma_f32_16x16x32_bf16 v[36:39], v[166:169], v[214:217], v[36:39]
	v_mfma_f32_16x16x32_bf16 v[32:35], v[174:177], v[214:217], v[32:35]
	v_mfma_f32_16x16x32_bf16 v[76:79], v[170:173], v[194:197], v[76:79]
	v_mfma_f32_16x16x32_bf16 v[68:71], v[178:181], v[194:197], v[68:71]
	v_mfma_f32_16x16x32_bf16 v[60:63], v[170:173], v[202:205], v[60:63]
	v_mfma_f32_16x16x32_bf16 v[52:55], v[178:181], v[202:205], v[52:55]
	v_mfma_f32_16x16x32_bf16 v[44:47], v[170:173], v[210:213], v[44:47]
	v_mfma_f32_16x16x32_bf16 v[40:43], v[178:181], v[210:213], v[40:43]
	v_mfma_f32_16x16x32_bf16 v[36:39], v[170:173], v[218:221], v[36:39]
	v_mfma_f32_16x16x32_bf16 v[32:35], v[178:181], v[218:221], v[32:35]
	s_barrier
; #define PG8_STAGE(bufoff, gbase, voff) do { _Pragma("unroll") for (int _i = 0; _i < 2; ++_i) \
;         __builtin_amdgcn_global_load_lds((const unsigned*)((const char*)(gbase) + (voff)[_i]), (PG8_LAS unsigned*)(lds + (bufoff) + ldsw + _i * 8192), 16, 0, 0); } while (0)
; #define PG8_LDA(dst, b, h) do { _Pragma("unroll") for (int m = 0; m < 4; ++m) _Pragma("unroll") for (int k = 0; k < 2; ++k) dst[m][k] = *(const PG8_LAS bf16x8*)(lds + PG8_SA(b, h) + aoff + m * 2048 + k * 1024); } while (0)
; #define PG8_LDB(dst, b, h) do { _Pragma("unroll") for (int n = 0; n < 2; ++n) _Pragma("unroll") for (int k = 0; k < 2; ++k) dst[n][k] = *(const PG8_LAS bf16x8*)(lds + PG8_SB(b, h) + boff + n * 2048 + k * 1024); } while (0)
; #define PG8_MMA(ai, bj, At, Bt) do { __builtin_amdgcn_s_setprio(1); _Pragma("unroll") for (int m = 0; m < 4; ++m) _Pragma("unroll") for (int n = 0; n < 2; ++n) _Pragma("unroll") for (int k = 0; k < 2; ++k) \
;         acc[ai][bj][m][n] = __builtin_amdgcn_mfma_f32_16x16x32_bf16(Bt[n][k], At[m][k], acc[ai][bj][m][n], 0, 0, 0); __builtin_amdgcn_s_setprio(0); } while (0)
; #define PG8_WAIT_V(n) asm volatile("s_waitcnt vmcnt(" #n ")" ::: "memory")
; #define PG8_WAIT_L(n) asm volatile("s_waitcnt lgkmcnt(" #n ")" ::: "memory")
; #define PG8_BAR __builtin_amdgcn_s_barrier()
; #define PG8_SCHED __builtin_amdgcn_sched_barrier(0)
; template <class Epi, class Sched, bool ALIGN_EPI = false, bool SP2 = false>
; __device__ __forceinline__ void gemm_phase(PG8_LAS unsigned char* lds, const Gemm g, const Sched& S, const Epi& E) {
;     ...
;             PG8_LDB(B0, 1, 0); PG8_LDB(B1, 1, 1); PG8_SCHED; PG8_LDA(At, 1, 0); PG8_STAGE(PG8_SA(0, 1), a2 + hstep, voffA);
;             PG8_WAIT_V(8); PG8_WAIT_L(0); PG8_BAR; PG8_MMA(0, 0, At, B0); PG8_MMA(0, 1, At, B1); PG8_BAR; PG8_SCHED;
;             PG8_LDA(At, 1, 1); PG8_STAGE(PG8_SB(1, 0), b3, voffB); PG8_STAGE(PG8_SB(1, 1), b3 + hstep, voffB); PG8_STAGE(PG8_SA(1, 0), a3, voffA);
;             PG8_WAIT_V(8); PG8_WAIT_L(0); PG8_BAR; PG8_MMA(1, 0, At, B0); PG8_MMA(1, 1, At, B1); PG8_BAR; PG8_SCHED;
	s_add_i32 s3, s3, s56
	v_lshl_add_u64 v[222:223], v[222:223], 0, s[18:19]
	s_mov_b32 m0, s3
	ds_read_b128 v[190:193], v149 offset:49152
	ds_read_b128 v[194:197], v233 offset:49152
	ds_read_b128 v[198:201], v149 offset:51200
	ds_read_b128 v[202:205], v233 offset:51200
	ds_read_b128 v[206:209], v149 offset:53248
	ds_read_b128 v[210:213], v233 offset:53248
	ds_read_b128 v[214:217], v149 offset:55296
	ds_read_b128 v[218:221], v233 offset:55296
	global_load_lds_dwordx4 v[222:223], off
	s_add_i32 m0, s3, 0x2000
	s_add_u32 s50, s50, 0x40080
	v_lshl_add_u64 v[222:223], v[224:225], 0, s[18:19]
	s_addc_u32 s51, s51, 0
	s_add_i32 s3, s45, s56
	global_load_lds_dwordx4 v[222:223], off
	v_lshl_add_u64 v[222:223], s[50:51], 0, v[130:131]
	s_mov_b32 m0, s3
	s_nop 0
	global_load_lds_dwordx4 v[222:223], off
	v_lshl_add_u64 v[222:223], s[50:51], 0, v[134:135]
	s_add_i32 m0, s3, 0x2000
	s_nop 0
	global_load_lds_dwordx4 v[222:223], off
	v_lshl_add_u64 v[222:223], v[226:227], 0, s[18:19]
	s_mov_b32 m0, s61
	s_nop 0
	global_load_lds_dwordx4 v[222:223], off
	v_lshl_add_u64 v[222:223], v[228:229], 0, s[18:19]
	s_mov_b32 m0, s62
	s_nop 0
	global_load_lds_dwordx4 v[222:223], off
	s_waitcnt vmcnt(8)
	s_waitcnt lgkmcnt(0)
	s_barrier
	s_waitcnt lgkmcnt(0)
	v_mfma_f32_16x16x32_bf16 v[92:95], v[150:153], v[190:193], v[92:95]
	v_mfma_f32_16x16x32_bf16 v[88:91], v[158:161], v[190:193], v[88:91]
	v_mfma_f32_16x16x32_bf16 v[84:87], v[150:153], v[198:201], v[84:87]
	v_mfma_f32_16x16x32_bf16 v[80:83], v[158:161], v[198:201], v[80:83]
	v_mfma_f32_16x16x32_bf16 v[72:75], v[150:153], v[206:209], v[72:75]
	v_mfma_f32_16x16x32_bf16 v[64:67], v[158:161], v[206:209], v[64:67]
	v_mfma_f32_16x16x32_bf16 v[56:59], v[150:153], v[214:217], v[56:59]
	v_mfma_f32_16x16x32_bf16 v[48:51], v[158:161], v[214:217], v[48:51]
	v_mfma_f32_16x16x32_bf16 v[92:95], v[154:157], v[194:197], v[92:95]
	v_mfma_f32_16x16x32_bf16 v[88:91], v[162:165], v[194:197], v[88:91]
	v_mfma_f32_16x16x32_bf16 v[84:87], v[154:157], v[202:205], v[84:87]
	v_mfma_f32_16x16x32_bf16 v[80:83], v[162:165], v[202:205], v[80:83]
	v_mfma_f32_16x16x32_bf16 v[72:75], v[154:157], v[210:213], v[72:75]
	v_mfma_f32_16x16x32_bf16 v[64:67], v[162:165], v[210:213], v[64:67]
	v_mfma_f32_16x16x32_bf16 v[56:59], v[154:157], v[218:221], v[56:59]
	v_mfma_f32_16x16x32_bf16 v[48:51], v[162:165], v[218:221], v[48:51]
	v_mfma_f32_16x16x32_bf16 v[28:31], v[166:169], v[190:193], v[28:31]
	v_mfma_f32_16x16x32_bf16 v[24:27], v[174:177], v[190:193], v[24:27]
	v_mfma_f32_16x16x32_bf16 v[20:23], v[166:169], v[198:201], v[20:23]
	v_mfma_f32_16x16x32_bf16 v[16:19], v[174:177], v[198:201], v[16:19]
	v_mfma_f32_16x16x32_bf16 v[12:15], v[166:169], v[206:209], v[12:15]
	v_mfma_f32_16x16x32_bf16 v[8:11], v[174:177], v[206:209], v[8:11]
	v_mfma_f32_16x16x32_bf16 v[4:7], v[166:169], v[214:217], v[4:7]
	v_mfma_f32_16x16x32_bf16 v[0:3], v[174:177], v[214:217], v[0:3]
	v_mfma_f32_16x16x32_bf16 v[28:31], v[170:173], v[194:197], v[28:31]
	v_mfma_f32_16x16x32_bf16 v[24:27], v[178:181], v[194:197], v[24:27]
	v_mfma_f32_16x16x32_bf16 v[20:23], v[170:173], v[202:205], v[20:23]
	v_mfma_f32_16x16x32_bf16 v[16:19], v[178:181], v[202:205], v[16:19]
	v_mfma_f32_16x16x32_bf16 v[12:15], v[170:173], v[210:213], v[12:15]
	v_mfma_f32_16x16x32_bf16 v[8:11], v[178:181], v[210:213], v[8:11]
	v_mfma_f32_16x16x32_bf16 v[4:7], v[170:173], v[218:221], v[4:7]
	v_mfma_f32_16x16x32_bf16 v[0:3], v[178:181], v[218:221], v[0:3]
	s_barrier
	s_add_i32 s76, s76, 2
	s_add_u32 s40, s40, 0x100
	s_addc_u32 s41, s41, 0
	s_add_u32 s74, s74, 0x100
	s_addc_u32 s75, s75, 0
	s_cmp_gt_u32 s76, 13
	s_cbranch_scc0 .LBB0_929
	s_and_b64 vcc, exec, s[20:21]
	s_cbranch_vccz .LBB0_932
	s_barrier

; __device__ __forceinline__ int fresh_tid() { int t = (int)threadIdx.x; asm volatile("" : "+v"(t)); return t; }
; #define PG8_STAGE(bufoff, gbase, voff) do { _Pragma("unroll") for (int _i = 0; _i < 2; ++_i) \
;         __builtin_amdgcn_global_load_lds((const unsigned*)((const char*)(gbase) + (voff)[_i]), (PG8_LAS unsigned*)(lds + (bufoff) + ldsw + _i * 8192), 16, 0, 0); } while (0)
; #define PG8_WAIT_V(n) asm volatile("s_waitcnt vmcnt(" #n ")" ::: "memory")
; #define PG8_BAR __builtin_amdgcn_s_barrier()
; template <class Epi, class Sched, bool ALIGN_EPI = false, bool SP2 = false>
; __device__ __forceinline__ void gemm_phase(PG8_LAS unsigned char* lds, const Gemm g, const Sched& S, const Epi& E) {
;     const int tid = fresh_tid(), wid = __builtin_amdgcn_readfirstlane(tid >> 6), lane = tid & 63, wr = wid >> 2, wc = wid & 3, fr = lane & 15, fq = lane >> 4;
;     const int K = g.K, nt = K / BK;
;     unsigned voffA[2], voffB[2];
; #pragma unroll
;     for (int i = 0; i < 2; ++i) { int R, C; stage_rc(tid * 16 + i * 8192, R, C); const int Rb = Epi::PERM ? ((R & ~31) + perm32(R & 31)) : R;
;         voffA[i] = (unsigned)(R * K + C) * 2u; voffB[i] = (unsigned)(Rb * K + C) * 2u; }
;     const size_t kstep = (size_t)(BK * 2);
;     const size_t hstep = (size_t)HALF * K * 2;
;     const size_t tstep = 2 * hstep;
;     const unsigned ldsw = (unsigned)wid * 1024u;
;     const int aoff = lds_byte(wr * 64 + fr, fq * 8), boff = lds_byte(wc * 32 + fr, fq * 8);
;     ...
;     const char* cA = (const char*)g.A + (size_t)cur.pm * tstep; const char* cB = (const char*)g.Bt + (size_t)cur.pn * tstep;
;     S.a_ready(cur);
;     if constexpr (SP2) {
;         PG8_STAGE(PG8_SB(0, 0), cB, voffB); PG8_STAGE(PG8_SB(0, 1), cB + hstep, voffB); PG8_STAGE(PG8_SA(0, 0), cA, voffA); PG8_STAGE(PG8_SA(0, 1), cA + hstep, voffA);
;         if (wr == 1) PG8_BAR;
;         PG8_WAIT_V(2); PG8_BAR;
;         PG8_STAGE(PG8_SB(1, 0), cB + kstep, voffB); PG8_STAGE(PG8_SA(1, 0), cA + kstep, voffA); PG8_STAGE(PG8_SB(1, 1), cB + hstep + kstep, voffB);
;         PG8_WAIT_V(6); PG8_BAR;
.LBB0_1109:
	s_mov_b64 s[12:13], s[80:81]
	s_mov_b64 s[14:15], s[80:81]
	s_mov_b64 s[10:11], s[80:81]
	v_mov_b32_e32 v8, v182
	s_barrier
	s_andn2_b64 vcc, exec, s[48:49]
	v_readfirstlane_b32 s19, v8
	s_cbranch_vccnz .LBB0_1125
	v_lshlrev_b32_e32 v0, 4, v8
	v_add_u32_e32 v1, 0x2000, v0
	v_ashrrev_i32_e32 v2, 31, v1
	v_lshrrev_b32_e32 v2, 22, v2
	v_add_u32_e32 v2, v1, v2
	v_ashrrev_i32_e32 v9, 10, v2
	v_mul_i32_i24_e32 v2, 0x400, v9
	v_sub_u32_e32 v1, v1, v2
	v_lshrrev_b32_e32 v2, 4, v1
	v_bitop3_b32 v1, v2, v1, 32 bitop3:0x6c
	v_ashrrev_i32_e32 v2, 31, v1
	s_load_dwordx2 s[0:1], s[12:13], 0x110
	s_load_dwordx2 s[16:17], s[14:15], 0x110
	v_lshrrev_b32_e32 v2, 26, v2
	v_add_u32_e32 v2, v1, v2
	v_lshlrev_b32_e32 v3, 3, v9
	v_ashrrev_i32_e32 v10, 6, v2
	v_and_b32_e32 v3, -16, v3
	v_add_u32_e32 v3, v10, v3
	s_waitcnt lgkmcnt(0)
	s_add_u32 s38, s0, 0x3000000
	v_and_b32_e32 v4, 3, v10
	s_mov_b32 s0, 0x1fffe0
	v_lshrrev_b32_e32 v5, 2, v3
	v_lshlrev_b32_e32 v6, 1, v3
	v_and_b32_e32 v2, 0xc0, v2
	v_and_or_b32 v4, v3, s0, v4
	v_and_b32_e32 v5, 4, v5
	v_and_b32_e32 v6, 24, v6
	v_sub_u32_e32 v1, v1, v2
	v_mov_b32_e32 v2, 1
	v_or3_b32 v4, v4, v5, v6
	v_lshlrev_b32_e32 v5, 5, v9
	v_ashrrev_i16_sdwa v1, v2, sext(v1) dst_sel:DWORD dst_unused:UNUSED_PAD src0_sel:DWORD src1_sel:BYTE_0
	v_and_b32_e32 v5, 32, v5
	v_bfe_i32 v11, v1, 0, 16
	v_add_lshl_u32 v1, v5, v11, 1
	v_lshl_add_u32 v128, v4, 11, v1
	v_lshl_add_u32 v130, v3, 11, v1
	v_bfe_i32 v1, v8, 27, 1
	v_lshrrev_b32_e32 v1, 22, v1
	v_add_u32_e32 v1, v0, v1
	v_and_b32_e32 v1, 0xfffffc00, v1
	v_sub_u32_e32 v0, v0, v1
	v_lshrrev_b32_e32 v1, 4, v0
	v_bitop3_b32 v1, v1, v0, 32 bitop3:0x6c
	v_ashrrev_i32_e32 v0, 31, v0
	v_lshrrev_b32_e32 v0, 26, v0
	v_add_u32_e32 v0, v1, v0
	v_ashrrev_i32_e32 v12, 6, v0
	v_ashrrev_i32_e32 v0, 31, v8
	v_lshrrev_b32_e32 v0, 26, v0
	v_add_u32_e32 v0, v8, v0
	v_ashrrev_i32_e32 v13, 6, v0
	s_addc_u32 s39, s1, 0
	v_lshlrev_b32_e32 v0, 3, v13
	s_add_u32 s40, s16, 0x1800000
	v_and_b32_e32 v0, -16, v0
	s_addc_u32 s41, s17, 0
	v_add_u32_e32 v0, v12, v0
	v_and_b32_e32 v3, 3, v12
	s_ashr_i32 s43, s33, 31
	v_and_or_b32 v3, v0, s0, v3
	s_lshr_b32 s0, s43, 29
	s_add_i32 s0, s33, s0
	s_ashr_i32 s16, s19, 6
	s_ashr_i32 s1, s0, 3
	s_and_b32 s0, s0, -8
	s_ashr_i32 s20, s19, 8
	s_lshl_b32 s42, s16, 10
	s_sub_i32 s0, s33, s0
	s_cmp_lt_i32 s0, 0
	s_movk_i32 s47, 0x161
	s_cselect_b32 s3, s47, 0x160
	s_mul_i32 s0, s0, s3
	s_add_i32 s0, s0, s1
	s_mul_hi_i32 s1, s0, 0x2e8ba2e9
	s_lshr_b32 s3, s1, 31
	s_ashr_i32 s1, s1, 5
	s_add_i32 s1, s1, s3
	s_lshl_b32 s3, s1, 3
	s_mulk_i32 s1, 0xb0
	s_sub_i32 s0, s0, s1
	s_sext_i32_i16 s1, s0
	s_bfe_u32 s1, s1, 0x3001c
	s_add_i32 s1, s0, s1
	s_sext_i32_i16 s12, s1
	s_and_b32 s1, s1, 0xfff8
	v_lshrrev_b32_e32 v4, 2, v0
	v_lshlrev_b32_e32 v5, 1, v0
	s_sub_i32 s0, s0, s1
	v_and_b32_e32 v4, 4, v4
	v_and_b32_e32 v5, 24, v5
	s_sext_i32_i16 s0, s0
	v_or3_b32 v3, v3, v4, v5
	v_mul_i32_i24_e32 v5, 64, v12
	s_lshr_b32 s18, s12, 3
	s_add_i32 s28, s3, s0
	v_sub_u32_e32 v1, v1, v5
	s_ashr_i32 s29, s28, 31
	s_bfe_i64 s[12:13], s[18:19], 0x100000
	v_lshlrev_b32_e32 v4, 5, v13
	v_ashrrev_i16_sdwa v1, v2, sext(v1) dst_sel:DWORD dst_unused:UNUSED_PAD src0_sel:DWORD src1_sel:BYTE_0
	s_lshl_b64 s[0:1], s[28:29], 19
	s_lshl_b64 s[12:13], s[12:13], 19
	v_and_b32_e32 v4, 32, v4
	v_bfe_i32 v14, v1, 0, 16
	s_add_u32 s34, s40, s12
	v_add_lshl_u32 v1, v4, v14, 1
	s_addc_u32 s35, s41, s13
	s_add_i32 s29, s42, 0
	v_lshl_add_u32 v132, v3, 11, v1
	s_add_i32 m0, s29, 0x10000
	v_lshl_add_u32 v134, v0, 11, v1
	v_readfirstlane_b32 vcc_lo, v8
	s_nop 3
	s_lshr_b32 vcc_lo, vcc_lo, 8
	s_cmp_eq_u32 vcc_lo, 0
	s_cbranch_scc0 .Lmy_prio_5
	s_setprio 1
.Lmy_prio_5:
	v_bfe_u32 v239, v8, 3, 3
	v_and_b32_e32 v240, 7, v8
	v_xor_b32_e32 v240, v240, v239
	v_lshlrev_b32_e32 v240, 4, v240
	v_lshrrev_b32_e32 v241, 6, v8
	v_lshl_add_u32 v242, v241, 3, v239
	v_mov_b32_e32 v243, 0x800
	v_mad_u32_u24 v134, v242, v243, v240
	v_add_u32_e32 v130, 0x20000, v134
	v_lshrrev_b32_e32 v244, 2, v241
	v_lshlrev_b32_e32 v244, 5, v244
	v_and_b32_e32 v245, 1, v241
	v_lshrrev_b32_e32 v246, 2, v239
	v_lshl_add_u32 v245, v245, 1, v246
	v_lshl_add_u32 v244, v245, 3, v244
	v_bfe_u32 v245, v241, 1, 1
	v_lshl_add_u32 v244, v245, 2, v244
	v_and_b32_e32 v245, 3, v239
	v_add_u32_e32 v244, v244, v245
	v_mad_u32_u24 v132, v244, v243, v240
	v_add_u32_e32 v128, 0x20000, v132
	global_load_lds_dwordx4 v132, s[34:35]
	s_add_i32 m0, s29, 0x12000
	s_add_u32 s12, s34, 0x40000
	global_load_lds_dwordx4 v128, s[34:35]
	s_addc_u32 s13, s35, 0
	s_add_i32 m0, s29, 0x14000
	s_load_dwordx2 s[10:11], s[10:11], 0x110
	global_load_lds_dwordx4 v132, s[12:13]
	s_add_i32 m0, s29, 0x16000
	s_add_u32 s30, s38, s0
	s_addc_u32 s31, s39, s1
	s_add_i32 s48, s29, 0x2000
	global_load_lds_dwordx4 v128, s[12:13]
	s_mov_b32 m0, s29
	s_add_u32 s0, s30, 0x40000
	global_load_lds_dwordx4 v134, s[30:31]
	s_mov_b32 m0, s48
	s_addc_u32 s1, s31, 0
	s_add_i32 s49, s29, 0x4000
	global_load_lds_dwordx4 v130, s[30:31]
	s_mov_b32 m0, s49
	s_add_i32 s50, s29, 0x6000
	global_load_lds_dwordx4 v134, s[0:1]
	s_mov_b32 m0, s50
	v_mov_b32_e32 v133, 0
	global_load_lds_dwordx4 v130, s[0:1]
	v_mov_b32_e32 v129, v133
	v_mov_b32_e32 v135, v133
	v_mov_b32_e32 v131, v133
	s_cmp_eq_u32 s20, 1
	s_mov_b32 s51, 0
	v_lshl_add_u64 v[6:7], s[34:35], 0, v[132:133]
	v_lshl_add_u64 v[4:5], s[34:35], 0, v[128:129]
	v_lshl_add_u64 v[0:1], s[30:31], 0, v[134:135]
	s_cselect_b64 s[12:13], -1, 0
	s_cmp_lg_u32 s20, 1
	v_lshl_add_u64 v[2:3], s[30:31], 0, v[130:131]
	s_cbranch_scc1 .LBB0_1112
	s_barrier

; #define PG8_STAGE(bufoff, gbase, voff) do { _Pragma("unroll") for (int _i = 0; _i < 2; ++_i) \
;         __builtin_amdgcn_global_load_lds((const unsigned*)((const char*)(gbase) + (voff)[_i]), (PG8_LAS unsigned*)(lds + (bufoff) + ldsw + _i * 8192), 16, 0, 0); } while (0)
; #define PG8_LDA(dst, b, h) do { _Pragma("unroll") for (int m = 0; m < 4; ++m) _Pragma("unroll") for (int k = 0; k < 2; ++k) dst[m][k] = *(const PG8_LAS bf16x8*)(lds + PG8_SA(b, h) + aoff + m * 2048 + k * 1024); } while (0)
; #define PG8_LDB(dst, b, h) do { _Pragma("unroll") for (int n = 0; n < 2; ++n) _Pragma("unroll") for (int k = 0; k < 2; ++k) dst[n][k] = *(const PG8_LAS bf16x8*)(lds + PG8_SB(b, h) + boff + n * 2048 + k * 1024); } while (0)
; #define PG8_BAR __builtin_amdgcn_s_barrier()
; template <class Epi, class Sched, bool ALIGN_EPI = false, bool SP2 = false>
; __device__ __forceinline__ void gemm_phase(PG8_LAS unsigned char* lds, const Gemm g, const Sched& S, const Epi& E) {
;     ...
;             const bool last = (t == nt - 2);
;             const char* a1 = cA + (size_t)(t + 1) * kstep;
;             const char* a2 = last ? nA : cA + (size_t)(t + 2) * kstep; const char* b2 = last ? nB : cB + (size_t)(t + 2) * kstep;
;             const char* a3 = a2 + kstep; const char* b3 = b2 + kstep;
;             if (last && has_next) S.a_ready(nxt);
;             if constexpr (SP2) {
;             PG8_LDB(B0, 0, 0); PG8_LDB(B1, 0, 1); PG8_SCHED; PG8_LDA(At, 0, 0); PG8_STAGE(PG8_SA(1, 1), a1 + hstep, voffA);
;             PG8_WAIT_V(8); PG8_WAIT_L(0); PG8_BAR; PG8_MMA(0, 0, At, B0); PG8_MMA(0, 1, At, B1); PG8_BAR; PG8_SCHED;
;             PG8_LDA(At, 0, 1); PG8_STAGE(PG8_SB(0, 0), b2, voffB); PG8_STAGE(PG8_SB(0, 1), b2 + hstep, voffB); PG8_STAGE(PG8_SA(0, 0), a2, voffA);
;             PG8_WAIT_V(8); PG8_WAIT_L(0); PG8_BAR; PG8_MMA(1, 0, At, B0); PG8_MMA(1, 1, At, B1); PG8_BAR; PG8_SCHED;
;             PG8_LDB(B0, 1, 0); PG8_LDB(B1, 1, 1); PG8_SCHED; PG8_LDA(At, 1, 0); PG8_STAGE(PG8_SA(0, 1), a2 + hstep, voffA);
;             PG8_WAIT_V(8); PG8_WAIT_L(0); PG8_BAR; PG8_MMA(0, 0, At, B0); PG8_MMA(0, 1, At, B1); PG8_BAR; PG8_SCHED;
;             PG8_LDA(At, 1, 1); PG8_STAGE(PG8_SB(1, 0), b3, voffB); PG8_STAGE(PG8_SB(1, 1), b3 + hstep, voffB); PG8_STAGE(PG8_SA(1, 0), a3, voffA);
;             PG8_WAIT_V(8); PG8_WAIT_L(0); PG8_BAR; PG8_MMA(1, 0, At, B0); PG8_MMA(1, 1, At, B1); PG8_BAR; PG8_SCHED;
.LBB0_1118:
	ds_read_b128 v[144:147], v151
	ds_read_b128 v[154:157], v235
	ds_read_b128 v[158:161], v151 offset:2048
	ds_read_b128 v[162:165], v235 offset:2048
	ds_read_b128 v[166:169], v152
	ds_read_b128 v[170:173], v236
	ds_read_b128 v[174:177], v152 offset:2048
	ds_read_b128 v[178:181], v236 offset:2048
	s_add_u32 s0, s30, 0xfffc0080
	s_addc_u32 s1, s31, -1
	s_cmp_eq_u32 s64, 12
	s_cselect_b32 s37, s23, s1
	s_cselect_b32 s36, s60, s0
	s_cselect_b32 s35, s21, s63
	s_cselect_b32 s34, s61, s62
	v_lshl_add_u64 v[222:223], s[30:31], 0, v[136:137]
	s_add_i32 m0, s29, 0xc000
	ds_read_b128 v[190:193], v153
	ds_read_b128 v[194:197], v233
	ds_read_b128 v[198:201], v153 offset:2048
	ds_read_b128 v[202:205], v233 offset:2048
	ds_read_b128 v[206:209], v153 offset:4096
	ds_read_b128 v[210:213], v233 offset:4096
	ds_read_b128 v[214:217], v153 offset:6144
	ds_read_b128 v[218:221], v233 offset:6144
	global_load_lds_dwordx4 v[222:223], off
	v_lshl_add_u64 v[222:223], s[30:31], 0, v[138:139]
	s_add_i32 m0, s29, 0xe000
	s_nop 0
	global_load_lds_dwordx4 v[222:223], off
	s_waitcnt vmcnt(8)
	s_waitcnt lgkmcnt(0)
	s_barrier
	s_waitcnt lgkmcnt(0)
	v_mfma_f32_16x16x32_bf16 v[124:127], v[144:147], v[190:193], v[124:127]
	v_mfma_f32_16x16x32_bf16 v[120:123], v[158:161], v[190:193], v[120:123]
	v_mfma_f32_16x16x32_bf16 v[108:111], v[144:147], v[198:201], v[108:111]
	v_mfma_f32_16x16x32_bf16 v[104:107], v[158:161], v[198:201], v[104:107]
	v_mfma_f32_16x16x32_bf16 v[92:95], v[144:147], v[206:209], v[92:95]
	v_mfma_f32_16x16x32_bf16 v[88:91], v[158:161], v[206:209], v[88:91]
	v_mfma_f32_16x16x32_bf16 v[76:79], v[144:147], v[214:217], v[76:79]
	v_mfma_f32_16x16x32_bf16 v[72:75], v[158:161], v[214:217], v[72:75]
	v_mfma_f32_16x16x32_bf16 v[124:127], v[154:157], v[194:197], v[124:127]
	v_mfma_f32_16x16x32_bf16 v[120:123], v[162:165], v[194:197], v[120:123]
	v_mfma_f32_16x16x32_bf16 v[108:111], v[154:157], v[202:205], v[108:111]
	v_mfma_f32_16x16x32_bf16 v[104:107], v[162:165], v[202:205], v[104:107]
	v_mfma_f32_16x16x32_bf16 v[92:95], v[154:157], v[210:213], v[92:95]
	v_mfma_f32_16x16x32_bf16 v[88:91], v[162:165], v[210:213], v[88:91]
	v_mfma_f32_16x16x32_bf16 v[76:79], v[154:157], v[218:221], v[76:79]
	v_mfma_f32_16x16x32_bf16 v[72:75], v[162:165], v[218:221], v[72:75]
	v_mfma_f32_16x16x32_bf16 v[116:119], v[166:169], v[190:193], v[116:119]
	v_mfma_f32_16x16x32_bf16 v[112:115], v[174:177], v[190:193], v[112:115]
	v_mfma_f32_16x16x32_bf16 v[100:103], v[166:169], v[198:201], v[100:103]
	v_mfma_f32_16x16x32_bf16 v[96:99], v[174:177], v[198:201], v[96:99]
	v_mfma_f32_16x16x32_bf16 v[84:87], v[166:169], v[206:209], v[84:87]
	v_mfma_f32_16x16x32_bf16 v[80:83], v[174:177], v[206:209], v[80:83]
	v_mfma_f32_16x16x32_bf16 v[68:71], v[166:169], v[214:217], v[68:71]
	v_mfma_f32_16x16x32_bf16 v[64:67], v[174:177], v[214:217], v[64:67]
	v_mfma_f32_16x16x32_bf16 v[116:119], v[170:173], v[194:197], v[116:119]
	v_mfma_f32_16x16x32_bf16 v[112:115], v[178:181], v[194:197], v[112:115]
	v_mfma_f32_16x16x32_bf16 v[100:103], v[170:173], v[202:205], v[100:103]
	v_mfma_f32_16x16x32_bf16 v[96:99], v[178:181], v[202:205], v[96:99]
	v_mfma_f32_16x16x32_bf16 v[84:87], v[170:173], v[210:213], v[84:87]
	v_mfma_f32_16x16x32_bf16 v[80:83], v[178:181], v[210:213], v[80:83]
	v_mfma_f32_16x16x32_bf16 v[68:71], v[170:173], v[218:221], v[68:71]
	v_mfma_f32_16x16x32_bf16 v[64:67], v[178:181], v[218:221], v[64:67]
	s_barrier
	s_add_i32 s0, s56, s42
	v_lshl_add_u64 v[222:223], s[34:35], 0, v[132:133]
	s_mov_b32 m0, s0
	ds_read_b128 v[190:193], v153 offset:16384
	ds_read_b128 v[194:197], v233 offset:16384
	ds_read_b128 v[198:201], v153 offset:18432
	ds_read_b128 v[202:205], v233 offset:18432
	ds_read_b128 v[206:209], v153 offset:20480
	ds_read_b128 v[210:213], v233 offset:20480
	ds_read_b128 v[214:217], v153 offset:22528
	ds_read_b128 v[218:221], v233 offset:22528
	global_load_lds_dwordx4 v[222:223], off
	s_add_i32 m0, s0, 0x2000
	s_add_u32 s0, s34, 0x40000
	v_lshl_add_u64 v[224:225], s[34:35], 0, v[128:129]
	s_addc_u32 s1, s35, 0
	s_add_i32 s3, s57, s42
	global_load_lds_dwordx4 v[224:225], off
	v_lshl_add_u64 v[226:227], s[0:1], 0, v[132:133]
	s_mov_b32 m0, s3
	v_lshl_add_u64 v[228:229], s[36:37], 0, v[130:131]
	global_load_lds_dwordx4 v[226:227], off
	v_lshl_add_u64 v[226:227], s[0:1], 0, v[128:129]
	s_add_i32 m0, s3, 0x2000
	s_nop 0
	global_load_lds_dwordx4 v[226:227], off
	v_lshl_add_u64 v[226:227], s[36:37], 0, v[134:135]
	s_mov_b32 m0, s29
	s_nop 0
	global_load_lds_dwordx4 v[226:227], off
	s_mov_b32 m0, s48
	s_nop 0
	global_load_lds_dwordx4 v[228:229], off
	s_waitcnt vmcnt(8)
	s_waitcnt lgkmcnt(0)
	s_barrier
; #define PG8_STAGE(bufoff, gbase, voff) do { _Pragma("unroll") for (int _i = 0; _i < 2; ++_i) \
;         __builtin_amdgcn_global_load_lds((const unsigned*)((const char*)(gbase) + (voff)[_i]), (PG8_LAS unsigned*)(lds + (bufoff) + ldsw + _i * 8192), 16, 0, 0); } while (0)
; #define PG8_LDA(dst, b, h) do { _Pragma("unroll") for (int m = 0; m < 4; ++m) _Pragma("unroll") for (int k = 0; k < 2; ++k) dst[m][k] = *(const PG8_LAS bf16x8*)(lds + PG8_SA(b, h) + aoff + m * 2048 + k * 1024); } while (0)
; #define PG8_LDB(dst, b, h) do { _Pragma("unroll") for (int n = 0; n < 2; ++n) _Pragma("unroll") for (int k = 0; k < 2; ++k) dst[n][k] = *(const PG8_LAS bf16x8*)(lds + PG8_SB(b, h) + boff + n * 2048 + k * 1024); } while (0)
; #define PG8_MMA(ai, bj, At, Bt) do { __builtin_amdgcn_s_setprio(1); _Pragma("unroll") for (int m = 0; m < 4; ++m) _Pragma("unroll") for (int n = 0; n < 2; ++n) _Pragma("unroll") for (int k = 0; k < 2; ++k) \
;         acc[ai][bj][m][n] = __builtin_amdgcn_mfma_f32_16x16x32_bf16(Bt[n][k], At[m][k], acc[ai][bj][m][n], 0, 0, 0); __builtin_amdgcn_s_setprio(0); } while (0)
; #define PG8_WAIT_V(n) asm volatile("s_waitcnt vmcnt(" #n ")" ::: "memory")
; template <class Epi, class Sched, bool ALIGN_EPI = false, bool SP2 = false>
; __device__ __forceinline__ void gemm_phase(PG8_LAS unsigned char* lds, const Gemm g, const Sched& S, const Epi& E) {
;     ...
;             PG8_LDB(B0, 0, 0); PG8_LDB(B1, 0, 1); PG8_SCHED; PG8_LDA(At, 0, 0); PG8_STAGE(PG8_SA(1, 1), a1 + hstep, voffA);
;             PG8_WAIT_V(8); PG8_WAIT_L(0); PG8_BAR; PG8_MMA(0, 0, At, B0); PG8_MMA(0, 1, At, B1); PG8_BAR; PG8_SCHED;
;             PG8_LDA(At, 0, 1); PG8_STAGE(PG8_SB(0, 0), b2, voffB); PG8_STAGE(PG8_SB(0, 1), b2 + hstep, voffB); PG8_STAGE(PG8_SA(0, 0), a2, voffA);
;             PG8_WAIT_V(8); PG8_WAIT_L(0); PG8_BAR; PG8_MMA(1, 0, At, B0); PG8_MMA(1, 1, At, B1); PG8_BAR; PG8_SCHED;
;             PG8_LDB(B0, 1, 0); PG8_LDB(B1, 1, 1); PG8_SCHED; PG8_LDA(At, 1, 0); PG8_STAGE(PG8_SA(0, 1), a2 + hstep, voffA);
;             PG8_WAIT_V(8); PG8_WAIT_L(0); PG8_BAR; PG8_MMA(0, 0, At, B0); PG8_MMA(0, 1, At, B1); PG8_BAR; PG8_SCHED;
;             PG8_LDA(At, 1, 1); PG8_STAGE(PG8_SB(1, 0), b3, voffB); PG8_STAGE(PG8_SB(1, 1), b3 + hstep, voffB); PG8_STAGE(PG8_SA(1, 0), a3, voffA);
;             PG8_WAIT_V(8); PG8_WAIT_L(0); PG8_BAR; PG8_MMA(1, 0, At, B0); PG8_MMA(1, 1, At, B1); PG8_BAR; PG8_SCHED;
	s_waitcnt lgkmcnt(0)
	v_mfma_f32_16x16x32_bf16 v[60:63], v[144:147], v[190:193], v[60:63]
	v_mfma_f32_16x16x32_bf16 v[56:59], v[158:161], v[190:193], v[56:59]
	v_mfma_f32_16x16x32_bf16 v[44:47], v[144:147], v[198:201], v[44:47]
	v_mfma_f32_16x16x32_bf16 v[40:43], v[158:161], v[198:201], v[40:43]
	v_mfma_f32_16x16x32_bf16 v[28:31], v[144:147], v[206:209], v[28:31]
	v_mfma_f32_16x16x32_bf16 v[24:27], v[158:161], v[206:209], v[24:27]
	v_mfma_f32_16x16x32_bf16 v[12:15], v[144:147], v[214:217], v[12:15]
	v_mfma_f32_16x16x32_bf16 v[8:11], v[158:161], v[214:217], v[8:11]
	v_mfma_f32_16x16x32_bf16 v[60:63], v[154:157], v[194:197], v[60:63]
	v_mfma_f32_16x16x32_bf16 v[56:59], v[162:165], v[194:197], v[56:59]
	v_mfma_f32_16x16x32_bf16 v[44:47], v[154:157], v[202:205], v[44:47]
	v_mfma_f32_16x16x32_bf16 v[40:43], v[162:165], v[202:205], v[40:43]
	v_mfma_f32_16x16x32_bf16 v[28:31], v[154:157], v[210:213], v[28:31]
	v_mfma_f32_16x16x32_bf16 v[24:27], v[162:165], v[210:213], v[24:27]
	v_mfma_f32_16x16x32_bf16 v[12:15], v[154:157], v[218:221], v[12:15]
	v_mfma_f32_16x16x32_bf16 v[8:11], v[162:165], v[218:221], v[8:11]
	v_mfma_f32_16x16x32_bf16 v[52:55], v[166:169], v[190:193], v[52:55]
	v_mfma_f32_16x16x32_bf16 v[48:51], v[174:177], v[190:193], v[48:51]
	v_mfma_f32_16x16x32_bf16 v[36:39], v[166:169], v[198:201], v[36:39]
	v_mfma_f32_16x16x32_bf16 v[32:35], v[174:177], v[198:201], v[32:35]
	v_mfma_f32_16x16x32_bf16 v[20:23], v[166:169], v[206:209], v[20:23]
	v_mfma_f32_16x16x32_bf16 v[16:19], v[174:177], v[206:209], v[16:19]
	v_mfma_f32_16x16x32_bf16 v[4:7], v[166:169], v[214:217], v[4:7]
	v_mfma_f32_16x16x32_bf16 v[0:3], v[174:177], v[214:217], v[0:3]
	v_mfma_f32_16x16x32_bf16 v[52:55], v[170:173], v[194:197], v[52:55]
	v_mfma_f32_16x16x32_bf16 v[48:51], v[178:181], v[194:197], v[48:51]
	v_mfma_f32_16x16x32_bf16 v[36:39], v[170:173], v[202:205], v[36:39]
	v_mfma_f32_16x16x32_bf16 v[32:35], v[178:181], v[202:205], v[32:35]
	v_mfma_f32_16x16x32_bf16 v[20:23], v[170:173], v[210:213], v[20:23]
	v_mfma_f32_16x16x32_bf16 v[16:19], v[178:181], v[210:213], v[16:19]
	v_mfma_f32_16x16x32_bf16 v[4:7], v[170:173], v[218:221], v[4:7]
	v_mfma_f32_16x16x32_bf16 v[0:3], v[178:181], v[218:221], v[0:3]
	s_barrier
	s_add_i32 s3, 0, 0x18000
	s_add_i32 s45, 0, 0x1c000
	v_add_u32_e32 v162, s3, v149
	v_add_u32_e32 v237, s3, v234
	v_add_u32_e32 v178, s45, v149
	v_add_u32_e32 v238, s45, v234
	ds_read_b128 v[144:147], v162
	ds_read_b128 v[154:157], v237
	ds_read_b128 v[158:161], v162 offset:2048
	ds_read_b128 v[162:165], v237 offset:2048
	ds_read_b128 v[166:169], v178
	ds_read_b128 v[170:173], v238
	ds_read_b128 v[174:177], v178 offset:2048
	ds_read_b128 v[178:181], v238 offset:2048
	s_add_u32 s0, s36, 0x40000
	s_addc_u32 s1, s37, 0
	s_mov_b32 m0, s49
	v_lshl_add_u64 v[230:231], s[0:1], 0, v[134:135]
	ds_read_b128 v[190:193], v153 offset:32768
	ds_read_b128 v[194:197], v233 offset:32768
	ds_read_b128 v[198:201], v153 offset:34816
	ds_read_b128 v[202:205], v233 offset:34816
	ds_read_b128 v[206:209], v153 offset:36864
	ds_read_b128 v[210:213], v233 offset:36864
	ds_read_b128 v[214:217], v153 offset:38912
	ds_read_b128 v[218:221], v233 offset:38912
	global_load_lds_dwordx4 v[230:231], off
	v_lshl_add_u64 v[230:231], s[0:1], 0, v[130:131]
	s_mov_b32 m0, s50
	s_nop 0
	global_load_lds_dwordx4 v[230:231], off
	s_waitcnt vmcnt(8)
	s_waitcnt lgkmcnt(0)
	s_barrier
	s_waitcnt lgkmcnt(0)
	v_mfma_f32_16x16x32_bf16 v[124:127], v[144:147], v[190:193], v[124:127]
	v_mfma_f32_16x16x32_bf16 v[120:123], v[158:161], v[190:193], v[120:123]
	v_mfma_f32_16x16x32_bf16 v[108:111], v[144:147], v[198:201], v[108:111]
	v_mfma_f32_16x16x32_bf16 v[104:107], v[158:161], v[198:201], v[104:107]
	v_mfma_f32_16x16x32_bf16 v[92:95], v[144:147], v[206:209], v[92:95]
	v_mfma_f32_16x16x32_bf16 v[88:91], v[158:161], v[206:209], v[88:91]
	v_mfma_f32_16x16x32_bf16 v[76:79], v[144:147], v[214:217], v[76:79]
	v_mfma_f32_16x16x32_bf16 v[72:75], v[158:161], v[214:217], v[72:75]
	v_mfma_f32_16x16x32_bf16 v[124:127], v[154:157], v[194:197], v[124:127]
	v_mfma_f32_16x16x32_bf16 v[120:123], v[162:165], v[194:197], v[120:123]
	v_mfma_f32_16x16x32_bf16 v[108:111], v[154:157], v[202:205], v[108:111]
	v_mfma_f32_16x16x32_bf16 v[104:107], v[162:165], v[202:205], v[104:107]
	v_mfma_f32_16x16x32_bf16 v[92:95], v[154:157], v[210:213], v[92:95]
	v_mfma_f32_16x16x32_bf16 v[88:91], v[162:165], v[210:213], v[88:91]
	v_mfma_f32_16x16x32_bf16 v[76:79], v[154:157], v[218:221], v[76:79]
	v_mfma_f32_16x16x32_bf16 v[72:75], v[162:165], v[218:221], v[72:75]
	v_mfma_f32_16x16x32_bf16 v[116:119], v[166:169], v[190:193], v[116:119]
	v_mfma_f32_16x16x32_bf16 v[112:115], v[174:177], v[190:193], v[112:115]
	v_mfma_f32_16x16x32_bf16 v[100:103], v[166:169], v[198:201], v[100:103]
	v_mfma_f32_16x16x32_bf16 v[96:99], v[174:177], v[198:201], v[96:99]
	v_mfma_f32_16x16x32_bf16 v[84:87], v[166:169], v[206:209], v[84:87]
	v_mfma_f32_16x16x32_bf16 v[80:83], v[174:177], v[206:209], v[80:83]
	v_mfma_f32_16x16x32_bf16 v[68:71], v[166:169], v[214:217], v[68:71]
	v_mfma_f32_16x16x32_bf16 v[64:67], v[174:177], v[214:217], v[64:67]
	v_mfma_f32_16x16x32_bf16 v[116:119], v[170:173], v[194:197], v[116:119]
	v_mfma_f32_16x16x32_bf16 v[112:115], v[178:181], v[194:197], v[112:115]
	v_mfma_f32_16x16x32_bf16 v[100:103], v[170:173], v[202:205], v[100:103]
	v_mfma_f32_16x16x32_bf16 v[96:99], v[178:181], v[202:205], v[96:99]
	v_mfma_f32_16x16x32_bf16 v[84:87], v[170:173], v[210:213], v[84:87]
	v_mfma_f32_16x16x32_bf16 v[80:83], v[178:181], v[210:213], v[80:83]
	v_mfma_f32_16x16x32_bf16 v[68:71], v[170:173], v[218:221], v[68:71]
	v_mfma_f32_16x16x32_bf16 v[64:67], v[178:181], v[218:221], v[64:67]
	s_barrier
; #define PG8_STAGE(bufoff, gbase, voff) do { _Pragma("unroll") for (int _i = 0; _i < 2; ++_i) \
;         __builtin_amdgcn_global_load_lds((const unsigned*)((const char*)(gbase) + (voff)[_i]), (PG8_LAS unsigned*)(lds + (bufoff) + ldsw + _i * 8192), 16, 0, 0); } while (0)
; #define PG8_LDA(dst, b, h) do { _Pragma("unroll") for (int m = 0; m < 4; ++m) _Pragma("unroll") for (int k = 0; k < 2; ++k) dst[m][k] = *(const PG8_LAS bf16x8*)(lds + PG8_SA(b, h) + aoff + m * 2048 + k * 1024); } while (0)
; #define PG8_LDB(dst, b, h) do { _Pragma("unroll") for (int n = 0; n < 2; ++n) _Pragma("unroll") for (int k = 0; k < 2; ++k) dst[n][k] = *(const PG8_LAS bf16x8*)(lds + PG8_SB(b, h) + boff + n * 2048 + k * 1024); } while (0)
; #define PG8_MMA(ai, bj, At, Bt) do { __builtin_amdgcn_s_setprio(1); _Pragma("unroll") for (int m = 0; m < 4; ++m) _Pragma("unroll") for (int n = 0; n < 2; ++n) _Pragma("unroll") for (int k = 0; k < 2; ++k) \
;         acc[ai][bj][m][n] = __builtin_amdgcn_mfma_f32_16x16x32_bf16(Bt[n][k], At[m][k], acc[ai][bj][m][n], 0, 0, 0); __builtin_amdgcn_s_setprio(0); } while (0)
; #define PG8_WAIT_V(n) asm volatile("s_waitcnt vmcnt(" #n ")" ::: "memory")
; #define PG8_WAIT_L(n) asm volatile("s_waitcnt lgkmcnt(" #n ")" ::: "memory")
; #define PG8_BAR __builtin_amdgcn_s_barrier()
; #define PG8_SCHED __builtin_amdgcn_sched_barrier(0)
; template <class Epi, class Sched, bool ALIGN_EPI = false, bool SP2 = false>
; __device__ __forceinline__ void gemm_phase(PG8_LAS unsigned char* lds, const Gemm g, const Sched& S, const Epi& E) {
;     ...
;             PG8_LDB(B0, 1, 0); PG8_LDB(B1, 1, 1); PG8_SCHED; PG8_LDA(At, 1, 0); PG8_STAGE(PG8_SA(0, 1), a2 + hstep, voffA);
;             PG8_WAIT_V(8); PG8_WAIT_L(0); PG8_BAR; PG8_MMA(0, 0, At, B0); PG8_MMA(0, 1, At, B1); PG8_BAR; PG8_SCHED;
;             PG8_LDA(At, 1, 1); PG8_STAGE(PG8_SB(1, 0), b3, voffB); PG8_STAGE(PG8_SB(1, 1), b3 + hstep, voffB); PG8_STAGE(PG8_SA(1, 0), a3, voffA);
;             PG8_WAIT_V(8); PG8_WAIT_L(0); PG8_BAR; PG8_MMA(1, 0, At, B0); PG8_MMA(1, 1, At, B1); PG8_BAR; PG8_SCHED;
	s_add_i32 s0, s3, s42
	v_lshl_add_u64 v[222:223], v[222:223], 0, s[16:17]
	s_mov_b32 m0, s0
	ds_read_b128 v[190:193], v153 offset:49152
	ds_read_b128 v[194:197], v233 offset:49152
	ds_read_b128 v[198:201], v153 offset:51200
	ds_read_b128 v[202:205], v233 offset:51200
	ds_read_b128 v[206:209], v153 offset:53248
	ds_read_b128 v[210:213], v233 offset:53248
	ds_read_b128 v[214:217], v153 offset:55296
	ds_read_b128 v[218:221], v233 offset:55296
	global_load_lds_dwordx4 v[222:223], off
	s_add_i32 m0, s0, 0x2000
	s_add_u32 s0, s34, 0x40080
	v_lshl_add_u64 v[222:223], v[224:225], 0, s[16:17]
	s_addc_u32 s1, s35, 0
	s_add_i32 s3, s45, s42
	global_load_lds_dwordx4 v[222:223], off
	v_lshl_add_u64 v[222:223], s[0:1], 0, v[132:133]
	s_mov_b32 m0, s3
	s_nop 0
	global_load_lds_dwordx4 v[222:223], off
	v_lshl_add_u64 v[222:223], s[0:1], 0, v[128:129]
	s_add_i32 m0, s3, 0x2000
	s_nop 0
	global_load_lds_dwordx4 v[222:223], off
	v_lshl_add_u64 v[222:223], v[226:227], 0, s[16:17]
	s_mov_b32 m0, s52
	s_nop 0
	global_load_lds_dwordx4 v[222:223], off
	v_lshl_add_u64 v[222:223], v[228:229], 0, s[16:17]
	s_mov_b32 m0, s53
	s_nop 0
	global_load_lds_dwordx4 v[222:223], off
	s_waitcnt vmcnt(8)
	s_waitcnt lgkmcnt(0)
	s_barrier
	s_waitcnt lgkmcnt(0)
	v_mfma_f32_16x16x32_bf16 v[60:63], v[144:147], v[190:193], v[60:63]
	v_mfma_f32_16x16x32_bf16 v[56:59], v[158:161], v[190:193], v[56:59]
	v_mfma_f32_16x16x32_bf16 v[44:47], v[144:147], v[198:201], v[44:47]
	v_mfma_f32_16x16x32_bf16 v[40:43], v[158:161], v[198:201], v[40:43]
	v_mfma_f32_16x16x32_bf16 v[28:31], v[144:147], v[206:209], v[28:31]
	v_mfma_f32_16x16x32_bf16 v[24:27], v[158:161], v[206:209], v[24:27]
	v_mfma_f32_16x16x32_bf16 v[12:15], v[144:147], v[214:217], v[12:15]
	v_mfma_f32_16x16x32_bf16 v[8:11], v[158:161], v[214:217], v[8:11]
	v_mfma_f32_16x16x32_bf16 v[60:63], v[154:157], v[194:197], v[60:63]
	v_mfma_f32_16x16x32_bf16 v[56:59], v[162:165], v[194:197], v[56:59]
	v_mfma_f32_16x16x32_bf16 v[44:47], v[154:157], v[202:205], v[44:47]
	v_mfma_f32_16x16x32_bf16 v[40:43], v[162:165], v[202:205], v[40:43]
	v_mfma_f32_16x16x32_bf16 v[28:31], v[154:157], v[210:213], v[28:31]
	v_mfma_f32_16x16x32_bf16 v[24:27], v[162:165], v[210:213], v[24:27]
	v_mfma_f32_16x16x32_bf16 v[12:15], v[154:157], v[218:221], v[12:15]
	v_mfma_f32_16x16x32_bf16 v[8:11], v[162:165], v[218:221], v[8:11]
	v_mfma_f32_16x16x32_bf16 v[52:55], v[166:169], v[190:193], v[52:55]
	v_mfma_f32_16x16x32_bf16 v[48:51], v[174:177], v[190:193], v[48:51]
	v_mfma_f32_16x16x32_bf16 v[36:39], v[166:169], v[198:201], v[36:39]
	v_mfma_f32_16x16x32_bf16 v[32:35], v[174:177], v[198:201], v[32:35]
	v_mfma_f32_16x16x32_bf16 v[20:23], v[166:169], v[206:209], v[20:23]
	v_mfma_f32_16x16x32_bf16 v[16:19], v[174:177], v[206:209], v[16:19]
	v_mfma_f32_16x16x32_bf16 v[4:7], v[166:169], v[214:217], v[4:7]
	v_mfma_f32_16x16x32_bf16 v[0:3], v[174:177], v[214:217], v[0:3]
	v_mfma_f32_16x16x32_bf16 v[52:55], v[170:173], v[194:197], v[52:55]
	v_mfma_f32_16x16x32_bf16 v[48:51], v[178:181], v[194:197], v[48:51]
	v_mfma_f32_16x16x32_bf16 v[36:39], v[170:173], v[202:205], v[36:39]
	v_mfma_f32_16x16x32_bf16 v[32:35], v[178:181], v[202:205], v[32:35]
	v_mfma_f32_16x16x32_bf16 v[20:23], v[170:173], v[210:213], v[20:23]
	v_mfma_f32_16x16x32_bf16 v[16:19], v[178:181], v[210:213], v[16:19]
	v_mfma_f32_16x16x32_bf16 v[4:7], v[170:173], v[218:221], v[4:7]
	v_mfma_f32_16x16x32_bf16 v[0:3], v[178:181], v[218:221], v[0:3]
	s_barrier
	s_add_i32 s64, s64, 2
	s_add_u32 s30, s30, 0x100
	s_addc_u32 s31, s31, 0
	s_add_u32 s62, s62, 0x100
	s_addc_u32 s63, s63, 0
	s_cmp_gt_u32 s64, 13
	s_cbranch_scc0 .LBB0_1118
	s_and_b64 vcc, exec, s[18:19]
	s_cbranch_vccz .LBB0_1121
	s_barrier

; __device__ __forceinline__ int fresh_tid() { int t = (int)threadIdx.x; asm volatile("" : "+v"(t)); return t; }
; #define PG8_STAGE(bufoff, gbase, voff) do { _Pragma("unroll") for (int _i = 0; _i < 2; ++_i) \
;         __builtin_amdgcn_global_load_lds((const unsigned*)((const char*)(gbase) + (voff)[_i]), (PG8_LAS unsigned*)(lds + (bufoff) + ldsw + _i * 8192), 16, 0, 0); } while (0)
; #define PG8_WAIT_V(n) asm volatile("s_waitcnt vmcnt(" #n ")" ::: "memory")
; #define PG8_BAR __builtin_amdgcn_s_barrier()
; template <class Epi, class Sched, bool ALIGN_EPI = false, bool SP2 = false>
; __device__ __forceinline__ void gemm_phase(PG8_LAS unsigned char* lds, const Gemm g, const Sched& S, const Epi& E) {
;     const int tid = fresh_tid(), wid = __builtin_amdgcn_readfirstlane(tid >> 6), lane = tid & 63, wr = wid >> 2, wc = wid & 3, fr = lane & 15, fq = lane >> 4;
;     const int K = g.K, nt = K / BK;
;     unsigned voffA[2], voffB[2];
; #pragma unroll
;     for (int i = 0; i < 2; ++i) { int R, C; stage_rc(tid * 16 + i * 8192, R, C); const int Rb = Epi::PERM ? ((R & ~31) + perm32(R & 31)) : R;
;         voffA[i] = (unsigned)(R * K + C) * 2u; voffB[i] = (unsigned)(Rb * K + C) * 2u; }
;     const size_t kstep = (size_t)(BK * 2);
;     const size_t hstep = (size_t)HALF * K * 2;
;     const size_t tstep = 2 * hstep;
;     const unsigned ldsw = (unsigned)wid * 1024u;
;     const int aoff = lds_byte(wr * 64 + fr, fq * 8), boff = lds_byte(wc * 32 + fr, fq * 8);
;     ...
;     const char* cA = (const char*)g.A + (size_t)cur.pm * tstep; const char* cB = (const char*)g.Bt + (size_t)cur.pn * tstep;
;     S.a_ready(cur);
;     if constexpr (SP2) {
;         PG8_STAGE(PG8_SB(0, 0), cB, voffB); PG8_STAGE(PG8_SB(0, 1), cB + hstep, voffB); PG8_STAGE(PG8_SA(0, 0), cA, voffA); PG8_STAGE(PG8_SA(0, 1), cA + hstep, voffA);
;         if (wr == 1) PG8_BAR;
;         PG8_WAIT_V(2); PG8_BAR;
;         PG8_STAGE(PG8_SB(1, 0), cB + kstep, voffB); PG8_STAGE(PG8_SA(1, 0), cA + kstep, voffA); PG8_STAGE(PG8_SB(1, 1), cB + hstep + kstep, voffB);
;         PG8_WAIT_V(6); PG8_BAR;
.LBB0_1193:
	v_ashrrev_i32_e32 v1, 31, v8
	v_lshrrev_b32_e32 v1, 26, v1
	v_add_u32_e32 v1, v8, v1
	v_ashrrev_i32_e32 v9, 6, v1
	v_bfe_i32 v1, v8, 27, 1
	v_lshlrev_b32_e32 v0, 4, v8
	v_lshrrev_b32_e32 v1, 22, v1
	v_add_u32_e32 v1, v0, v1
	v_and_b32_e32 v1, 0xfffffc00, v1
	v_sub_u32_e32 v1, v0, v1
	v_lshrrev_b32_e32 v2, 4, v1
	v_bitop3_b32 v2, v2, v1, 32 bitop3:0x6c
	v_ashrrev_i32_e32 v1, 31, v1
	v_lshrrev_b32_e32 v1, 26, v1
	v_lshlrev_b32_e32 v3, 3, v9
	v_add_u32_e32 v1, v2, v1
	v_and_b32_e32 v3, -16, v3
	v_ashrrev_i32_e32 v11, 6, v1
	v_add_u32_e32 v1, v11, v3
	v_lshlrev_b32_e32 v3, 5, v9
	v_and_b32_e32 v10, 32, v3
	v_mul_i32_i24_e32 v3, 64, v11
	s_waitcnt lgkmcnt(0)
	s_add_u32 s39, s10, 0xb200000
	v_sub_u32_e32 v2, v2, v3
	v_mov_b32_e32 v3, 1
	s_addc_u32 s40, s11, 0
	v_ashrrev_i16_sdwa v2, v3, sext(v2) dst_sel:DWORD dst_unused:UNUSED_PAD src0_sel:DWORD src1_sel:BYTE_0
	v_lshlrev_b32_e32 v4, 1, v1
	v_lshrrev_b32_e32 v5, 2, v1
	v_and_b32_e32 v6, 3, v11
	s_mov_b32 s0, 0xffffe0
	s_add_u32 s41, s8, 0x2300000
	v_bfe_i32 v12, v2, 0, 16
	v_and_b32_e32 v4, 24, v4
	v_and_b32_e32 v5, 4, v5
	v_and_or_b32 v6, v1, s0, v6
	s_movk_i32 s8, 0xb00
	v_add_u32_e32 v2, v10, v12
	v_or3_b32 v4, v6, v5, v4
	v_mul_lo_u32 v1, v1, s8
	v_add_lshl_u32 v128, v2, v1, 1
	v_mul_u32_u24_e32 v1, 0xb00, v4
	v_add_u32_e32 v0, 0x2000, v0
	v_add_lshl_u32 v130, v1, v2, 1
	v_ashrrev_i32_e32 v1, 31, v0
	v_lshrrev_b32_e32 v1, 22, v1
	v_add_u32_e32 v1, v0, v1
	v_ashrrev_i32_e32 v13, 10, v1
	v_mul_i32_i24_e32 v1, 0x400, v13
	v_sub_u32_e32 v0, v0, v1
	v_lshrrev_b32_e32 v1, 4, v0
	v_bitop3_b32 v0, v1, v0, 32 bitop3:0x6c
	v_ashrrev_i32_e32 v2, 31, v0
	v_lshrrev_b32_e32 v2, 26, v2
	v_lshlrev_b32_e32 v1, 3, v13
	v_add_u32_e32 v2, v0, v2
	v_and_b32_e32 v1, -16, v1
	v_ashrrev_i32_e32 v14, 6, v2
	v_lshlrev_b32_e32 v4, 5, v13
	v_add_u32_e32 v1, v14, v1
	v_and_b32_e32 v15, 32, v4
	v_and_b32_e32 v4, 3, v14
	s_addc_u32 s42, s9, 0
	v_and_or_b32 v4, v1, s0, v4
	s_add_i32 s0, s14, s12
	s_ashr_i32 s1, s0, 31
	s_lshr_b32 s1, s1, 27
	s_add_i32 s1, s0, s1
	s_ashr_i32 s3, s1, 5
	s_andn2_b32 s1, s1, 31
	s_sub_i32 s0, s0, s1
	s_bfe_i32 s1, s0, 0x80000
	s_bfe_u32 s1, s1, 0x3000c
	s_add_i32 s1, s0, s1
	s_bfe_i32 s10, s1, 0x80000
	s_and_b32 s1, s1, 0xf8
	s_sub_i32 s0, s1, s0
	s_sext_i32_i8 s0, s0
	s_lshl_b32 s1, s3, 3
	s_sext_i32_i16 s10, s10
	s_sub_i32 s0, s0, s1
	s_ashr_i32 s9, s16, 6
	v_and_b32_e32 v2, 0xc0, v2
	s_add_i32 s64, s0, 0x7f
	s_ashr_i32 s0, s10, 3
	v_sub_u32_e32 v0, v0, v2
	s_ashr_i32 s17, s16, 8
	s_lshl_b32 s43, s9, 10
	s_lshr_b32 s18, s10, 3
	s_mul_hi_i32 s1, s0, 0x160000
	s_mul_i32 s0, s0, 0x160000
	v_ashrrev_i16_sdwa v0, v3, sext(v0) dst_sel:DWORD dst_unused:UNUSED_PAD src0_sel:DWORD src1_sel:BYTE_0
	v_lshlrev_b32_e32 v2, 1, v1
	v_lshrrev_b32_e32 v3, 2, v1
	s_add_u32 s30, s41, s0
	v_bfe_i32 v16, v0, 0, 16
	v_and_b32_e32 v2, 24, v2
	v_and_b32_e32 v3, 4, v3
	s_addc_u32 s31, s42, s1
	s_add_i32 s47, s43, 0
	v_add_u32_e32 v0, v15, v16
	v_or3_b32 v2, v4, v3, v2
	v_mul_lo_u32 v1, v1, s8
	s_add_i32 m0, s47, 0x10000
	v_add_lshl_u32 v132, v0, v1, 1
	v_mul_u32_u24_e32 v1, 0xb00, v2
	v_readfirstlane_b32 vcc_lo, v8
	s_nop 3
	s_lshr_b32 vcc_lo, vcc_lo, 8
	s_cmp_eq_u32 vcc_lo, 0
	s_cbranch_scc0 .Lmy_prio_6
	s_setprio 1
.Lmy_prio_6:
	v_bfe_u32 v239, v8, 3, 3
	v_and_b32_e32 v240, 7, v8
	v_xor_b32_e32 v240, v240, v239
	v_lshlrev_b32_e32 v240, 4, v240
	v_lshrrev_b32_e32 v241, 6, v8
	v_lshl_add_u32 v242, v241, 3, v239
	v_mov_b32_e32 v243, 0x1600
	v_mad_u32_u24 v128, v242, v243, v240
	v_add_u32_e32 v132, 0x58000, v128
	v_lshrrev_b32_e32 v244, 2, v241
	v_lshlrev_b32_e32 v244, 5, v244
	v_and_b32_e32 v245, 1, v241
	v_lshrrev_b32_e32 v246, 2, v239
	v_lshl_add_u32 v245, v245, 1, v246
	v_lshl_add_u32 v244, v245, 3, v244
	v_bfe_u32 v245, v241, 1, 1
	v_lshl_add_u32 v244, v245, 2, v244
	v_and_b32_e32 v245, 3, v239
	v_add_u32_e32 v244, v244, v245
	v_mad_u32_u24 v130, v244, v243, v240
	v_add_u32_e32 v134, 0x58000, v130
	global_load_lds_dwordx4 v130, s[30:31]
	s_add_i32 m0, s47, 0x12000
	s_add_u32 s0, s30, 0xb0000
	global_load_lds_dwordx4 v134, s[30:31]
	s_addc_u32 s1, s31, 0
	s_add_i32 m0, s47, 0x14000
	s_mul_i32 s11, s64, 0x160000
	global_load_lds_dwordx4 v130, s[0:1]
	s_add_i32 m0, s47, 0x16000
	s_mul_hi_u32 s3, s64, 0x160000
	s_add_u32 s28, s39, s11
	s_addc_u32 s29, s40, s3
	s_add_i32 s48, s47, 0x2000
	global_load_lds_dwordx4 v134, s[0:1]
	s_mov_b32 m0, s47
	s_add_u32 s0, s28, 0xb0000
	global_load_lds_dwordx4 v128, s[28:29]
	s_mov_b32 m0, s48
	s_addc_u32 s1, s29, 0
	s_add_i32 s49, s47, 0x4000
	global_load_lds_dwordx4 v132, s[28:29]
	s_mov_b32 m0, s49
	s_add_i32 s50, s47, 0x6000
	global_load_lds_dwordx4 v128, s[0:1]
	s_mov_b32 m0, s50
	v_mov_b32_e32 v131, 0
	global_load_lds_dwordx4 v132, s[0:1]
	v_mov_b32_e32 v135, v131
	v_mov_b32_e32 v129, v131
	v_mov_b32_e32 v133, v131
	s_cmp_eq_u32 s17, 1
	s_mov_b32 s51, 0
	v_lshl_add_u64 v[6:7], s[30:31], 0, v[130:131]
	v_lshl_add_u64 v[4:5], s[30:31], 0, v[134:135]
	v_lshl_add_u64 v[0:1], s[28:29], 0, v[128:129]
	s_cselect_b64 s[10:11], -1, 0
	s_cmp_lg_u32 s17, 1
	v_lshl_add_u64 v[2:3], s[28:29], 0, v[132:133]
	s_cbranch_scc1 .LBB0_1195
	s_barrier

; #define PG8_STAGE(bufoff, gbase, voff) do { _Pragma("unroll") for (int _i = 0; _i < 2; ++_i) \
;         __builtin_amdgcn_global_load_lds((const unsigned*)((const char*)(gbase) + (voff)[_i]), (PG8_LAS unsigned*)(lds + (bufoff) + ldsw + _i * 8192), 16, 0, 0); } while (0)
; #define PG8_LDA(dst, b, h) do { _Pragma("unroll") for (int m = 0; m < 4; ++m) _Pragma("unroll") for (int k = 0; k < 2; ++k) dst[m][k] = *(const PG8_LAS bf16x8*)(lds + PG8_SA(b, h) + aoff + m * 2048 + k * 1024); } while (0)
; #define PG8_LDB(dst, b, h) do { _Pragma("unroll") for (int n = 0; n < 2; ++n) _Pragma("unroll") for (int k = 0; k < 2; ++k) dst[n][k] = *(const PG8_LAS bf16x8*)(lds + PG8_SB(b, h) + boff + n * 2048 + k * 1024); } while (0)
; #define PG8_BAR __builtin_amdgcn_s_barrier()
; template <class Epi, class Sched, bool ALIGN_EPI = false, bool SP2 = false>
; __device__ __forceinline__ void gemm_phase(PG8_LAS unsigned char* lds, const Gemm g, const Sched& S, const Epi& E) {
;     ...
;             const bool last = (t == nt - 2);
;             const char* a1 = cA + (size_t)(t + 1) * kstep;
;             const char* a2 = last ? nA : cA + (size_t)(t + 2) * kstep; const char* b2 = last ? nB : cB + (size_t)(t + 2) * kstep;
;             const char* a3 = a2 + kstep; const char* b3 = b2 + kstep;
;             if (last && has_next) S.a_ready(nxt);
;             if constexpr (SP2) {
;             PG8_LDB(B0, 0, 0); PG8_LDB(B1, 0, 1); PG8_SCHED; PG8_LDA(At, 0, 0); PG8_STAGE(PG8_SA(1, 1), a1 + hstep, voffA);
;             PG8_WAIT_V(8); PG8_WAIT_L(0); PG8_BAR; PG8_MMA(0, 0, At, B0); PG8_MMA(0, 1, At, B1); PG8_BAR; PG8_SCHED;
;             PG8_LDA(At, 0, 1); PG8_STAGE(PG8_SB(0, 0), b2, voffB); PG8_STAGE(PG8_SB(0, 1), b2 + hstep, voffB); PG8_STAGE(PG8_SA(0, 0), a2, voffA);
;             PG8_WAIT_V(8); PG8_WAIT_L(0); PG8_BAR; PG8_MMA(1, 0, At, B0); PG8_MMA(1, 1, At, B1); PG8_BAR; PG8_SCHED;
;             PG8_LDB(B0, 1, 0); PG8_LDB(B1, 1, 1); PG8_SCHED; PG8_LDA(At, 1, 0); PG8_STAGE(PG8_SA(0, 1), a2 + hstep, voffA);
;             PG8_WAIT_V(8); PG8_WAIT_L(0); PG8_BAR; PG8_MMA(0, 0, At, B0); PG8_MMA(0, 1, At, B1); PG8_BAR; PG8_SCHED;
;             PG8_LDA(At, 1, 1); PG8_STAGE(PG8_SB(1, 0), b3, voffB); PG8_STAGE(PG8_SB(1, 1), b3 + hstep, voffB); PG8_STAGE(PG8_SA(1, 0), a3, voffA);
;             PG8_WAIT_V(8); PG8_WAIT_L(0); PG8_BAR; PG8_MMA(1, 0, At, B0); PG8_MMA(1, 1, At, B1); PG8_BAR; PG8_SCHED;
.LBB0_1209:
	ds_read_b128 v[150:153], v147
	ds_read_b128 v[154:157], v235
	ds_read_b128 v[158:161], v147 offset:2048
	ds_read_b128 v[162:165], v235 offset:2048
	ds_read_b128 v[166:169], v148
	ds_read_b128 v[170:173], v236
	ds_read_b128 v[174:177], v148 offset:2048
	ds_read_b128 v[178:181], v236 offset:2048
	s_add_u32 s30, s28, 0x100
	s_addc_u32 s31, s29, 0
	s_cmp_eq_u32 s68, 40
	s_cselect_b32 s37, s9, s31
	s_cselect_b32 s36, s8, s30
	s_cselect_b32 s35, s27, s67
	s_cselect_b32 s34, s26, s66
	v_lshl_add_u64 v[222:223], s[28:29], 0, v[136:137]
	s_add_i32 m0, s47, 0xc000
	ds_read_b128 v[190:193], v149
	ds_read_b128 v[194:197], v233
	ds_read_b128 v[198:201], v149 offset:2048
	ds_read_b128 v[202:205], v233 offset:2048
	ds_read_b128 v[206:209], v149 offset:4096
	ds_read_b128 v[210:213], v233 offset:4096
	ds_read_b128 v[214:217], v149 offset:6144
	ds_read_b128 v[218:221], v233 offset:6144
	global_load_lds_dwordx4 v[222:223], off
	v_lshl_add_u64 v[222:223], s[28:29], 0, v[138:139]
	s_add_i32 m0, s47, 0xe000
	s_nop 0
	global_load_lds_dwordx4 v[222:223], off
	s_waitcnt vmcnt(8)
	s_waitcnt lgkmcnt(0)
	s_barrier
	s_waitcnt lgkmcnt(0)
	v_mfma_f32_16x16x32_bf16 v[124:127], v[150:153], v[190:193], v[124:127]
	v_mfma_f32_16x16x32_bf16 v[120:123], v[158:161], v[190:193], v[120:123]
	v_mfma_f32_16x16x32_bf16 v[116:119], v[150:153], v[198:201], v[116:119]
	v_mfma_f32_16x16x32_bf16 v[112:115], v[158:161], v[198:201], v[112:115]
	v_mfma_f32_16x16x32_bf16 v[108:111], v[150:153], v[206:209], v[108:111]
	v_mfma_f32_16x16x32_bf16 v[104:107], v[158:161], v[206:209], v[104:107]
	v_mfma_f32_16x16x32_bf16 v[100:103], v[150:153], v[214:217], v[100:103]
	v_mfma_f32_16x16x32_bf16 v[96:99], v[158:161], v[214:217], v[96:99]
	v_mfma_f32_16x16x32_bf16 v[124:127], v[154:157], v[194:197], v[124:127]
	v_mfma_f32_16x16x32_bf16 v[120:123], v[162:165], v[194:197], v[120:123]
	v_mfma_f32_16x16x32_bf16 v[116:119], v[154:157], v[202:205], v[116:119]
	v_mfma_f32_16x16x32_bf16 v[112:115], v[162:165], v[202:205], v[112:115]
	v_mfma_f32_16x16x32_bf16 v[108:111], v[154:157], v[210:213], v[108:111]
	v_mfma_f32_16x16x32_bf16 v[104:107], v[162:165], v[210:213], v[104:107]
	v_mfma_f32_16x16x32_bf16 v[100:103], v[154:157], v[218:221], v[100:103]
	v_mfma_f32_16x16x32_bf16 v[96:99], v[162:165], v[218:221], v[96:99]
	v_mfma_f32_16x16x32_bf16 v[76:79], v[166:169], v[190:193], v[76:79]
	v_mfma_f32_16x16x32_bf16 v[68:71], v[174:177], v[190:193], v[68:71]
	v_mfma_f32_16x16x32_bf16 v[60:63], v[166:169], v[198:201], v[60:63]
	v_mfma_f32_16x16x32_bf16 v[52:55], v[174:177], v[198:201], v[52:55]
	v_mfma_f32_16x16x32_bf16 v[44:47], v[166:169], v[206:209], v[44:47]
	v_mfma_f32_16x16x32_bf16 v[40:43], v[174:177], v[206:209], v[40:43]
	v_mfma_f32_16x16x32_bf16 v[36:39], v[166:169], v[214:217], v[36:39]
	v_mfma_f32_16x16x32_bf16 v[32:35], v[174:177], v[214:217], v[32:35]
	v_mfma_f32_16x16x32_bf16 v[76:79], v[170:173], v[194:197], v[76:79]
	v_mfma_f32_16x16x32_bf16 v[68:71], v[178:181], v[194:197], v[68:71]
	v_mfma_f32_16x16x32_bf16 v[60:63], v[170:173], v[202:205], v[60:63]
	v_mfma_f32_16x16x32_bf16 v[52:55], v[178:181], v[202:205], v[52:55]
	v_mfma_f32_16x16x32_bf16 v[44:47], v[170:173], v[210:213], v[44:47]
	v_mfma_f32_16x16x32_bf16 v[40:43], v[178:181], v[210:213], v[40:43]
	v_mfma_f32_16x16x32_bf16 v[36:39], v[170:173], v[218:221], v[36:39]
	v_mfma_f32_16x16x32_bf16 v[32:35], v[178:181], v[218:221], v[32:35]
	s_barrier
	s_add_i32 s0, s56, s43
	v_lshl_add_u64 v[222:223], s[34:35], 0, v[130:131]
	s_mov_b32 m0, s0
	ds_read_b128 v[190:193], v149 offset:16384
	ds_read_b128 v[194:197], v233 offset:16384
	ds_read_b128 v[198:201], v149 offset:18432
	ds_read_b128 v[202:205], v233 offset:18432
	ds_read_b128 v[206:209], v149 offset:20480
	ds_read_b128 v[210:213], v233 offset:20480
	ds_read_b128 v[214:217], v149 offset:22528
	ds_read_b128 v[218:221], v233 offset:22528
	global_load_lds_dwordx4 v[222:223], off
	s_add_i32 m0, s0, 0x2000
	s_add_u32 s0, s34, 0xb0000
	v_lshl_add_u64 v[224:225], s[34:35], 0, v[134:135]
	s_addc_u32 s1, s35, 0
	s_add_i32 s3, s57, s43
	global_load_lds_dwordx4 v[224:225], off
	v_lshl_add_u64 v[226:227], s[0:1], 0, v[130:131]
	s_mov_b32 m0, s3
	v_lshl_add_u64 v[228:229], s[36:37], 0, v[132:133]
	global_load_lds_dwordx4 v[226:227], off
	v_lshl_add_u64 v[226:227], s[0:1], 0, v[134:135]
	s_add_i32 m0, s3, 0x2000
	s_nop 0
	global_load_lds_dwordx4 v[226:227], off
	v_lshl_add_u64 v[226:227], s[36:37], 0, v[128:129]
	s_mov_b32 m0, s47
	s_nop 0
	global_load_lds_dwordx4 v[226:227], off
	s_mov_b32 m0, s48
	s_nop 0
	global_load_lds_dwordx4 v[228:229], off
	s_waitcnt vmcnt(8)
	s_waitcnt lgkmcnt(0)
	s_barrier
; #define PG8_STAGE(bufoff, gbase, voff) do { _Pragma("unroll") for (int _i = 0; _i < 2; ++_i) \
;         __builtin_amdgcn_global_load_lds((const unsigned*)((const char*)(gbase) + (voff)[_i]), (PG8_LAS unsigned*)(lds + (bufoff) + ldsw + _i * 8192), 16, 0, 0); } while (0)
; #define PG8_LDA(dst, b, h) do { _Pragma("unroll") for (int m = 0; m < 4; ++m) _Pragma("unroll") for (int k = 0; k < 2; ++k) dst[m][k] = *(const PG8_LAS bf16x8*)(lds + PG8_SA(b, h) + aoff + m * 2048 + k * 1024); } while (0)
; #define PG8_LDB(dst, b, h) do { _Pragma("unroll") for (int n = 0; n < 2; ++n) _Pragma("unroll") for (int k = 0; k < 2; ++k) dst[n][k] = *(const PG8_LAS bf16x8*)(lds + PG8_SB(b, h) + boff + n * 2048 + k * 1024); } while (0)
; #define PG8_MMA(ai, bj, At, Bt) do { __builtin_amdgcn_s_setprio(1); _Pragma("unroll") for (int m = 0; m < 4; ++m) _Pragma("unroll") for (int n = 0; n < 2; ++n) _Pragma("unroll") for (int k = 0; k < 2; ++k) \
;         acc[ai][bj][m][n] = __builtin_amdgcn_mfma_f32_16x16x32_bf16(Bt[n][k], At[m][k], acc[ai][bj][m][n], 0, 0, 0); __builtin_amdgcn_s_setprio(0); } while (0)
; #define PG8_WAIT_V(n) asm volatile("s_waitcnt vmcnt(" #n ")" ::: "memory")
; template <class Epi, class Sched, bool ALIGN_EPI = false, bool SP2 = false>
; __device__ __forceinline__ void gemm_phase(PG8_LAS unsigned char* lds, const Gemm g, const Sched& S, const Epi& E) {
;     ...
;             PG8_LDB(B0, 0, 0); PG8_LDB(B1, 0, 1); PG8_SCHED; PG8_LDA(At, 0, 0); PG8_STAGE(PG8_SA(1, 1), a1 + hstep, voffA);
;             PG8_WAIT_V(8); PG8_WAIT_L(0); PG8_BAR; PG8_MMA(0, 0, At, B0); PG8_MMA(0, 1, At, B1); PG8_BAR; PG8_SCHED;
;             PG8_LDA(At, 0, 1); PG8_STAGE(PG8_SB(0, 0), b2, voffB); PG8_STAGE(PG8_SB(0, 1), b2 + hstep, voffB); PG8_STAGE(PG8_SA(0, 0), a2, voffA);
;             PG8_WAIT_V(8); PG8_WAIT_L(0); PG8_BAR; PG8_MMA(1, 0, At, B0); PG8_MMA(1, 1, At, B1); PG8_BAR; PG8_SCHED;
;             PG8_LDB(B0, 1, 0); PG8_LDB(B1, 1, 1); PG8_SCHED; PG8_LDA(At, 1, 0); PG8_STAGE(PG8_SA(0, 1), a2 + hstep, voffA);
;             PG8_WAIT_V(8); PG8_WAIT_L(0); PG8_BAR; PG8_MMA(0, 0, At, B0); PG8_MMA(0, 1, At, B1); PG8_BAR; PG8_SCHED;
;             PG8_LDA(At, 1, 1); PG8_STAGE(PG8_SB(1, 0), b3, voffB); PG8_STAGE(PG8_SB(1, 1), b3 + hstep, voffB); PG8_STAGE(PG8_SA(1, 0), a3, voffA);
;             PG8_WAIT_V(8); PG8_WAIT_L(0); PG8_BAR; PG8_MMA(1, 0, At, B0); PG8_MMA(1, 1, At, B1); PG8_BAR; PG8_SCHED;
	s_waitcnt lgkmcnt(0)
	v_mfma_f32_16x16x32_bf16 v[92:95], v[150:153], v[190:193], v[92:95]
	v_mfma_f32_16x16x32_bf16 v[88:91], v[158:161], v[190:193], v[88:91]
	v_mfma_f32_16x16x32_bf16 v[84:87], v[150:153], v[198:201], v[84:87]
	v_mfma_f32_16x16x32_bf16 v[80:83], v[158:161], v[198:201], v[80:83]
	v_mfma_f32_16x16x32_bf16 v[72:75], v[150:153], v[206:209], v[72:75]
	v_mfma_f32_16x16x32_bf16 v[64:67], v[158:161], v[206:209], v[64:67]
	v_mfma_f32_16x16x32_bf16 v[56:59], v[150:153], v[214:217], v[56:59]
	v_mfma_f32_16x16x32_bf16 v[48:51], v[158:161], v[214:217], v[48:51]
	v_mfma_f32_16x16x32_bf16 v[92:95], v[154:157], v[194:197], v[92:95]
	v_mfma_f32_16x16x32_bf16 v[88:91], v[162:165], v[194:197], v[88:91]
	v_mfma_f32_16x16x32_bf16 v[84:87], v[154:157], v[202:205], v[84:87]
	v_mfma_f32_16x16x32_bf16 v[80:83], v[162:165], v[202:205], v[80:83]
	v_mfma_f32_16x16x32_bf16 v[72:75], v[154:157], v[210:213], v[72:75]
	v_mfma_f32_16x16x32_bf16 v[64:67], v[162:165], v[210:213], v[64:67]
	v_mfma_f32_16x16x32_bf16 v[56:59], v[154:157], v[218:221], v[56:59]
	v_mfma_f32_16x16x32_bf16 v[48:51], v[162:165], v[218:221], v[48:51]
	v_mfma_f32_16x16x32_bf16 v[28:31], v[166:169], v[190:193], v[28:31]
	v_mfma_f32_16x16x32_bf16 v[24:27], v[174:177], v[190:193], v[24:27]
	v_mfma_f32_16x16x32_bf16 v[20:23], v[166:169], v[198:201], v[20:23]
	v_mfma_f32_16x16x32_bf16 v[16:19], v[174:177], v[198:201], v[16:19]
	v_mfma_f32_16x16x32_bf16 v[12:15], v[166:169], v[206:209], v[12:15]
	v_mfma_f32_16x16x32_bf16 v[8:11], v[174:177], v[206:209], v[8:11]
	v_mfma_f32_16x16x32_bf16 v[4:7], v[166:169], v[214:217], v[4:7]
	v_mfma_f32_16x16x32_bf16 v[0:3], v[174:177], v[214:217], v[0:3]
	v_mfma_f32_16x16x32_bf16 v[28:31], v[170:173], v[194:197], v[28:31]
	v_mfma_f32_16x16x32_bf16 v[24:27], v[178:181], v[194:197], v[24:27]
	v_mfma_f32_16x16x32_bf16 v[20:23], v[170:173], v[202:205], v[20:23]
	v_mfma_f32_16x16x32_bf16 v[16:19], v[178:181], v[202:205], v[16:19]
	v_mfma_f32_16x16x32_bf16 v[12:15], v[170:173], v[210:213], v[12:15]
	v_mfma_f32_16x16x32_bf16 v[8:11], v[178:181], v[210:213], v[8:11]
	v_mfma_f32_16x16x32_bf16 v[4:7], v[170:173], v[218:221], v[4:7]
	v_mfma_f32_16x16x32_bf16 v[0:3], v[178:181], v[218:221], v[0:3]
	s_barrier
	s_add_i32 s3, 0, 0x18000
	s_add_i32 s28, 0, 0x1c000
	v_add_u32_e32 v162, s3, v145
	v_add_u32_e32 v237, s3, v234
	v_add_u32_e32 v178, s28, v145
	v_add_u32_e32 v238, s28, v234
	ds_read_b128 v[150:153], v162
	ds_read_b128 v[154:157], v237
	ds_read_b128 v[158:161], v162 offset:2048
	ds_read_b128 v[162:165], v237 offset:2048
	ds_read_b128 v[166:169], v178
	ds_read_b128 v[170:173], v238
	ds_read_b128 v[174:177], v178 offset:2048
	ds_read_b128 v[178:181], v238 offset:2048
	s_add_u32 s0, s36, 0xb0000
	s_addc_u32 s1, s37, 0
	s_mov_b32 m0, s49
	v_lshl_add_u64 v[230:231], s[0:1], 0, v[128:129]
	ds_read_b128 v[190:193], v149 offset:32768
	ds_read_b128 v[194:197], v233 offset:32768
	ds_read_b128 v[198:201], v149 offset:34816
	ds_read_b128 v[202:205], v233 offset:34816
	ds_read_b128 v[206:209], v149 offset:36864
	ds_read_b128 v[210:213], v233 offset:36864
	ds_read_b128 v[214:217], v149 offset:38912
	ds_read_b128 v[218:221], v233 offset:38912
	global_load_lds_dwordx4 v[230:231], off
	v_lshl_add_u64 v[230:231], s[0:1], 0, v[132:133]
	s_mov_b32 m0, s50
	s_nop 0
	global_load_lds_dwordx4 v[230:231], off
	s_waitcnt vmcnt(8)
	s_waitcnt lgkmcnt(0)
	s_barrier
	s_waitcnt lgkmcnt(0)
	v_mfma_f32_16x16x32_bf16 v[124:127], v[150:153], v[190:193], v[124:127]
	v_mfma_f32_16x16x32_bf16 v[120:123], v[158:161], v[190:193], v[120:123]
	v_mfma_f32_16x16x32_bf16 v[116:119], v[150:153], v[198:201], v[116:119]
	v_mfma_f32_16x16x32_bf16 v[112:115], v[158:161], v[198:201], v[112:115]
	v_mfma_f32_16x16x32_bf16 v[108:111], v[150:153], v[206:209], v[108:111]
	v_mfma_f32_16x16x32_bf16 v[104:107], v[158:161], v[206:209], v[104:107]
	v_mfma_f32_16x16x32_bf16 v[100:103], v[150:153], v[214:217], v[100:103]
	v_mfma_f32_16x16x32_bf16 v[96:99], v[158:161], v[214:217], v[96:99]
	v_mfma_f32_16x16x32_bf16 v[124:127], v[154:157], v[194:197], v[124:127]
	v_mfma_f32_16x16x32_bf16 v[120:123], v[162:165], v[194:197], v[120:123]
	v_mfma_f32_16x16x32_bf16 v[116:119], v[154:157], v[202:205], v[116:119]
	v_mfma_f32_16x16x32_bf16 v[112:115], v[162:165], v[202:205], v[112:115]
	v_mfma_f32_16x16x32_bf16 v[108:111], v[154:157], v[210:213], v[108:111]
	v_mfma_f32_16x16x32_bf16 v[104:107], v[162:165], v[210:213], v[104:107]
	v_mfma_f32_16x16x32_bf16 v[100:103], v[154:157], v[218:221], v[100:103]
	v_mfma_f32_16x16x32_bf16 v[96:99], v[162:165], v[218:221], v[96:99]
	v_mfma_f32_16x16x32_bf16 v[76:79], v[166:169], v[190:193], v[76:79]
	v_mfma_f32_16x16x32_bf16 v[68:71], v[174:177], v[190:193], v[68:71]
	v_mfma_f32_16x16x32_bf16 v[60:63], v[166:169], v[198:201], v[60:63]
	v_mfma_f32_16x16x32_bf16 v[52:55], v[174:177], v[198:201], v[52:55]
	v_mfma_f32_16x16x32_bf16 v[44:47], v[166:169], v[206:209], v[44:47]
	v_mfma_f32_16x16x32_bf16 v[40:43], v[174:177], v[206:209], v[40:43]
	v_mfma_f32_16x16x32_bf16 v[36:39], v[166:169], v[214:217], v[36:39]
	v_mfma_f32_16x16x32_bf16 v[32:35], v[174:177], v[214:217], v[32:35]
	v_mfma_f32_16x16x32_bf16 v[76:79], v[170:173], v[194:197], v[76:79]
	v_mfma_f32_16x16x32_bf16 v[68:71], v[178:181], v[194:197], v[68:71]
	v_mfma_f32_16x16x32_bf16 v[60:63], v[170:173], v[202:205], v[60:63]
	v_mfma_f32_16x16x32_bf16 v[52:55], v[178:181], v[202:205], v[52:55]
	v_mfma_f32_16x16x32_bf16 v[44:47], v[170:173], v[210:213], v[44:47]
	v_mfma_f32_16x16x32_bf16 v[40:43], v[178:181], v[210:213], v[40:43]
	v_mfma_f32_16x16x32_bf16 v[36:39], v[170:173], v[218:221], v[36:39]
	v_mfma_f32_16x16x32_bf16 v[32:35], v[178:181], v[218:221], v[32:35]
	s_barrier
; #define PG8_STAGE(bufoff, gbase, voff) do { _Pragma("unroll") for (int _i = 0; _i < 2; ++_i) \
;         __builtin_amdgcn_global_load_lds((const unsigned*)((const char*)(gbase) + (voff)[_i]), (PG8_LAS unsigned*)(lds + (bufoff) + ldsw + _i * 8192), 16, 0, 0); } while (0)
; #define PG8_LDA(dst, b, h) do { _Pragma("unroll") for (int m = 0; m < 4; ++m) _Pragma("unroll") for (int k = 0; k < 2; ++k) dst[m][k] = *(const PG8_LAS bf16x8*)(lds + PG8_SA(b, h) + aoff + m * 2048 + k * 1024); } while (0)
; #define PG8_LDB(dst, b, h) do { _Pragma("unroll") for (int n = 0; n < 2; ++n) _Pragma("unroll") for (int k = 0; k < 2; ++k) dst[n][k] = *(const PG8_LAS bf16x8*)(lds + PG8_SB(b, h) + boff + n * 2048 + k * 1024); } while (0)
; #define PG8_MMA(ai, bj, At, Bt) do { __builtin_amdgcn_s_setprio(1); _Pragma("unroll") for (int m = 0; m < 4; ++m) _Pragma("unroll") for (int n = 0; n < 2; ++n) _Pragma("unroll") for (int k = 0; k < 2; ++k) \
;         acc[ai][bj][m][n] = __builtin_amdgcn_mfma_f32_16x16x32_bf16(Bt[n][k], At[m][k], acc[ai][bj][m][n], 0, 0, 0); __builtin_amdgcn_s_setprio(0); } while (0)
; #define PG8_WAIT_V(n) asm volatile("s_waitcnt vmcnt(" #n ")" ::: "memory")
; #define PG8_WAIT_L(n) asm volatile("s_waitcnt lgkmcnt(" #n ")" ::: "memory")
; #define PG8_BAR __builtin_amdgcn_s_barrier()
; #define PG8_SCHED __builtin_amdgcn_sched_barrier(0)
; template <class Epi, class Sched, bool ALIGN_EPI = false, bool SP2 = false>
; __device__ __forceinline__ void gemm_phase(PG8_LAS unsigned char* lds, const Gemm g, const Sched& S, const Epi& E) {
;     ...
;             PG8_LDB(B0, 1, 0); PG8_LDB(B1, 1, 1); PG8_SCHED; PG8_LDA(At, 1, 0); PG8_STAGE(PG8_SA(0, 1), a2 + hstep, voffA);
;             PG8_WAIT_V(8); PG8_WAIT_L(0); PG8_BAR; PG8_MMA(0, 0, At, B0); PG8_MMA(0, 1, At, B1); PG8_BAR; PG8_SCHED;
;             PG8_LDA(At, 1, 1); PG8_STAGE(PG8_SB(1, 0), b3, voffB); PG8_STAGE(PG8_SB(1, 1), b3 + hstep, voffB); PG8_STAGE(PG8_SA(1, 0), a3, voffA);
;             PG8_WAIT_V(8); PG8_WAIT_L(0); PG8_BAR; PG8_MMA(1, 0, At, B0); PG8_MMA(1, 1, At, B1); PG8_BAR; PG8_SCHED;
	s_add_i32 s0, s3, s43
	v_lshl_add_u64 v[222:223], v[222:223], 0, s[14:15]
	s_mov_b32 m0, s0
	ds_read_b128 v[190:193], v149 offset:49152
	ds_read_b128 v[194:197], v233 offset:49152
	ds_read_b128 v[198:201], v149 offset:51200
	ds_read_b128 v[202:205], v233 offset:51200
	ds_read_b128 v[206:209], v149 offset:53248
	ds_read_b128 v[210:213], v233 offset:53248
	ds_read_b128 v[214:217], v149 offset:55296
	ds_read_b128 v[218:221], v233 offset:55296
	global_load_lds_dwordx4 v[222:223], off
	s_add_i32 m0, s0, 0x2000
	s_add_u32 s0, s34, 0xb0080
	v_lshl_add_u64 v[222:223], v[224:225], 0, s[14:15]
	s_addc_u32 s1, s35, 0
	s_add_i32 s3, s28, s43
	global_load_lds_dwordx4 v[222:223], off
	v_lshl_add_u64 v[222:223], s[0:1], 0, v[130:131]
	s_mov_b32 m0, s3
	s_nop 0
	global_load_lds_dwordx4 v[222:223], off
	v_lshl_add_u64 v[222:223], s[0:1], 0, v[134:135]
	s_add_i32 m0, s3, 0x2000
	s_nop 0
	global_load_lds_dwordx4 v[222:223], off
	v_lshl_add_u64 v[222:223], v[226:227], 0, s[14:15]
	s_mov_b32 m0, s52
	s_nop 0
	global_load_lds_dwordx4 v[222:223], off
	v_lshl_add_u64 v[222:223], v[228:229], 0, s[14:15]
	s_mov_b32 m0, s53
	s_nop 0
	global_load_lds_dwordx4 v[222:223], off
	s_waitcnt vmcnt(8)
	s_waitcnt lgkmcnt(0)
	s_barrier
	s_waitcnt lgkmcnt(0)
	v_mfma_f32_16x16x32_bf16 v[92:95], v[150:153], v[190:193], v[92:95]
	v_mfma_f32_16x16x32_bf16 v[88:91], v[158:161], v[190:193], v[88:91]
	v_mfma_f32_16x16x32_bf16 v[84:87], v[150:153], v[198:201], v[84:87]
	v_mfma_f32_16x16x32_bf16 v[80:83], v[158:161], v[198:201], v[80:83]
	v_mfma_f32_16x16x32_bf16 v[72:75], v[150:153], v[206:209], v[72:75]
	v_mfma_f32_16x16x32_bf16 v[64:67], v[158:161], v[206:209], v[64:67]
	v_mfma_f32_16x16x32_bf16 v[56:59], v[150:153], v[214:217], v[56:59]
	v_mfma_f32_16x16x32_bf16 v[48:51], v[158:161], v[214:217], v[48:51]
	v_mfma_f32_16x16x32_bf16 v[92:95], v[154:157], v[194:197], v[92:95]
	v_mfma_f32_16x16x32_bf16 v[88:91], v[162:165], v[194:197], v[88:91]
	v_mfma_f32_16x16x32_bf16 v[84:87], v[154:157], v[202:205], v[84:87]
	v_mfma_f32_16x16x32_bf16 v[80:83], v[162:165], v[202:205], v[80:83]
	v_mfma_f32_16x16x32_bf16 v[72:75], v[154:157], v[210:213], v[72:75]
	v_mfma_f32_16x16x32_bf16 v[64:67], v[162:165], v[210:213], v[64:67]
	v_mfma_f32_16x16x32_bf16 v[56:59], v[154:157], v[218:221], v[56:59]
	v_mfma_f32_16x16x32_bf16 v[48:51], v[162:165], v[218:221], v[48:51]
	v_mfma_f32_16x16x32_bf16 v[28:31], v[166:169], v[190:193], v[28:31]
	v_mfma_f32_16x16x32_bf16 v[24:27], v[174:177], v[190:193], v[24:27]
	v_mfma_f32_16x16x32_bf16 v[20:23], v[166:169], v[198:201], v[20:23]
	v_mfma_f32_16x16x32_bf16 v[16:19], v[174:177], v[198:201], v[16:19]
	v_mfma_f32_16x16x32_bf16 v[12:15], v[166:169], v[206:209], v[12:15]
	v_mfma_f32_16x16x32_bf16 v[8:11], v[174:177], v[206:209], v[8:11]
	v_mfma_f32_16x16x32_bf16 v[4:7], v[166:169], v[214:217], v[4:7]
	v_mfma_f32_16x16x32_bf16 v[0:3], v[174:177], v[214:217], v[0:3]
	v_mfma_f32_16x16x32_bf16 v[28:31], v[170:173], v[194:197], v[28:31]
	v_mfma_f32_16x16x32_bf16 v[24:27], v[178:181], v[194:197], v[24:27]
	v_mfma_f32_16x16x32_bf16 v[20:23], v[170:173], v[202:205], v[20:23]
	v_mfma_f32_16x16x32_bf16 v[16:19], v[178:181], v[202:205], v[16:19]
	v_mfma_f32_16x16x32_bf16 v[12:15], v[170:173], v[210:213], v[12:15]
	v_mfma_f32_16x16x32_bf16 v[8:11], v[178:181], v[210:213], v[8:11]
	v_mfma_f32_16x16x32_bf16 v[4:7], v[170:173], v[218:221], v[4:7]
	v_mfma_f32_16x16x32_bf16 v[0:3], v[178:181], v[218:221], v[0:3]
	s_barrier
	s_add_i32 s68, s68, 2
	s_add_u32 s66, s66, 0x100
	s_addc_u32 s67, s67, 0
	s_cmp_gt_u32 s68, 41
	s_mov_b64 s[28:29], s[30:31]
	s_cbranch_scc0 .LBB0_1209
	s_and_b64 vcc, exec, s[16:17]
	s_cbranch_vccz .LBB0_1212
	s_barrier
